# GEMM K-loops: 60 LDS-DMA loads whose address was SGPR base + loop-invariant zero-extended VGPR offset now use the saddr form, deleting their v_lshl_add_u64 from the load segments; on top of v25
# speedup vs baseline: 1.0037x; 1.0037x over previous
; #define PG8_STAGE(bufoff, gbase, voff) do { _Pragma("unroll") for (int _i = 0; _i < 2; ++_i) \
;         __builtin_amdgcn_global_load_lds((const unsigned*)((const char*)(gbase) + (voff)[_i]), (PG8_LAS unsigned*)(lds + (bufoff) + ldsw + _i * 8192), 16, 0, 0); } while (0)
; #define PG8_LDA(dst, b, h) do { _Pragma("unroll") for (int m = 0; m < 4; ++m) _Pragma("unroll") for (int k = 0; k < 2; ++k) dst[m][k] = *(const PG8_LAS bf16x8*)(lds + PG8_SA(b, h) + aoff + m * 2048 + k * 1024); } while (0)
; #define PG8_LDB(dst, b, h) do { _Pragma("unroll") for (int n = 0; n < 2; ++n) _Pragma("unroll") for (int k = 0; k < 2; ++k) dst[n][k] = *(const PG8_LAS bf16x8*)(lds + PG8_SB(b, h) + boff + n * 2048 + k * 1024); } while (0)
; #define PG8_MMA(ai, bj, At, Bt) do { __builtin_amdgcn_s_setprio(1); _Pragma("unroll") for (int m = 0; m < 4; ++m) _Pragma("unroll") for (int n = 0; n < 2; ++n) _Pragma("unroll") for (int k = 0; k < 2; ++k) \
;         acc[ai][bj][m][n] = __builtin_amdgcn_mfma_f32_16x16x32_bf16(Bt[n][k], At[m][k], acc[ai][bj][m][n], 0, 0, 0); __builtin_amdgcn_s_setprio(0); } while (0)
; #define PG8_WAIT_V(n) asm volatile("s_waitcnt vmcnt(" #n ")" ::: "memory")
; #define PG8_WAIT_L(n) asm volatile("s_waitcnt lgkmcnt(" #n ")" ::: "memory")
; #define PG8_BAR __builtin_amdgcn_s_barrier()
; #define PG8_SCHED __builtin_amdgcn_sched_barrier(0)
; template <class Epi, class Sched, bool ALIGN_EPI = false, bool SP2 = false>
; __device__ __forceinline__ void gemm_phase(PG8_LAS unsigned char* lds, const Gemm g, const Sched& S, const Epi& E) {
;     ...
;             const bool last = (t == nt - 2);
;             const char* a1 = cA + (size_t)(t + 1) * kstep;
;             const char* a2 = last ? nA : cA + (size_t)(t + 2) * kstep; const char* b2 = last ? nB : cB + (size_t)(t + 2) * kstep;
;             const char* a3 = a2 + kstep; const char* b3 = b2 + kstep;
;             if (last && has_next) S.a_ready(nxt);
;             if constexpr (SP2) {
;             PG8_LDB(B0, 0, 0); PG8_LDB(B1, 0, 1); PG8_SCHED; PG8_LDA(At, 0, 0); PG8_STAGE(PG8_SA(1, 1), a1 + hstep, voffA);
;             PG8_WAIT_V(8); PG8_WAIT_L(0); PG8_BAR; PG8_MMA(0, 0, At, B0); PG8_MMA(0, 1, At, B1); PG8_BAR; PG8_SCHED;
;             PG8_LDA(At, 0, 1); PG8_STAGE(PG8_SB(0, 0), b2, voffB); PG8_STAGE(PG8_SB(0, 1), b2 + hstep, voffB); PG8_STAGE(PG8_SA(0, 0), a2, voffA);
.LBB0_66:
	s_add_u32 s61, s90, 0xfffc0080
	s_addc_u32 s72, s91, -1
	s_add_i32 s73, 0, 0x10000
	s_cmp_eq_u32 s80, 12
	s_cselect_b32 s95, s47, s72
	s_cselect_b32 s94, vcc_lo, s61
	v_add_u32_e32 v147, s73, v139
	s_cselect_b32 s93, s45, s7
	s_cselect_b32 s92, vcc_hi, s4
	s_add_i32 s61, 0, 0x14000
	ds_read_b128 v[170:173], v147
	ds_read_b128 v[174:177], v147 offset:1024
	ds_read_b128 v[178:181], v147 offset:2048
	ds_read_b128 v[182:185], v147 offset:3072
	v_add_u32_e32 v147, s61, v139
	ds_read_b128 v[196:199], v147
	ds_read_b128 v[200:203], v147 offset:1024
	ds_read_b128 v[204:207], v147 offset:2048
	ds_read_b128 v[208:211], v147 offset:3072
	s_add_i32 m0, s8, 0xc000
	ds_read_b128 v[212:215], v143
	ds_read_b128 v[216:219], v143 offset:1024
	ds_read_b128 v[220:223], v143 offset:2048
	ds_read_b128 v[224:227], v143 offset:3072
	ds_read_b128 v[228:231], v143 offset:4096
	ds_read_b128 v[232:235], v143 offset:5120
	ds_read_b128 v[236:239], v143 offset:6144
	ds_read_b128 v[240:243], v143 offset:7168
	global_load_lds_dwordx4 v150, s[90:91]
	s_add_i32 m0, s8, 0xe000
	s_nop 0
	global_load_lds_dwordx4 v148, s[90:91]
	s_waitcnt vmcnt(8)
	s_waitcnt lgkmcnt(0)
	s_barrier
	v_mfma_f32_16x16x32_bf16 v[126:129], v[170:173], v[212:215], v[126:129]
	v_mfma_f32_16x16x32_bf16 v[122:125], v[178:181], v[212:215], v[122:125]
	v_mfma_f32_16x16x32_bf16 v[110:113], v[170:173], v[220:223], v[110:113]
	v_mfma_f32_16x16x32_bf16 v[106:109], v[178:181], v[220:223], v[106:109]
	v_mfma_f32_16x16x32_bf16 v[94:97], v[170:173], v[228:231], v[94:97]
	v_mfma_f32_16x16x32_bf16 v[90:93], v[178:181], v[228:231], v[90:93]
	v_mfma_f32_16x16x32_bf16 v[78:81], v[170:173], v[236:239], v[78:81]
	v_mfma_f32_16x16x32_bf16 v[74:77], v[178:181], v[236:239], v[74:77]
	v_mfma_f32_16x16x32_bf16 v[126:129], v[174:177], v[216:219], v[126:129]
	v_mfma_f32_16x16x32_bf16 v[122:125], v[182:185], v[216:219], v[122:125]
	v_mfma_f32_16x16x32_bf16 v[110:113], v[174:177], v[224:227], v[110:113]
	v_mfma_f32_16x16x32_bf16 v[106:109], v[182:185], v[224:227], v[106:109]
	v_mfma_f32_16x16x32_bf16 v[94:97], v[174:177], v[232:235], v[94:97]
	v_mfma_f32_16x16x32_bf16 v[90:93], v[182:185], v[232:235], v[90:93]
	v_mfma_f32_16x16x32_bf16 v[78:81], v[174:177], v[240:243], v[78:81]
	v_mfma_f32_16x16x32_bf16 v[74:77], v[182:185], v[240:243], v[74:77]
	v_mfma_f32_16x16x32_bf16 v[118:121], v[196:199], v[212:215], v[118:121]
	v_mfma_f32_16x16x32_bf16 v[114:117], v[204:207], v[212:215], v[114:117]
	v_mfma_f32_16x16x32_bf16 v[102:105], v[196:199], v[220:223], v[102:105]
	v_mfma_f32_16x16x32_bf16 v[98:101], v[204:207], v[220:223], v[98:101]
	v_mfma_f32_16x16x32_bf16 v[86:89], v[196:199], v[228:231], v[86:89]
	v_mfma_f32_16x16x32_bf16 v[82:85], v[204:207], v[228:231], v[82:85]
	v_mfma_f32_16x16x32_bf16 v[70:73], v[196:199], v[236:239], v[70:73]
	v_mfma_f32_16x16x32_bf16 v[66:69], v[204:207], v[236:239], v[66:69]
	v_mfma_f32_16x16x32_bf16 v[118:121], v[200:203], v[216:219], v[118:121]
	v_mfma_f32_16x16x32_bf16 v[114:117], v[208:211], v[216:219], v[114:117]
	v_mfma_f32_16x16x32_bf16 v[102:105], v[200:203], v[224:227], v[102:105]
	v_mfma_f32_16x16x32_bf16 v[98:101], v[208:211], v[224:227], v[98:101]
	v_mfma_f32_16x16x32_bf16 v[86:89], v[200:203], v[232:235], v[86:89]
	v_mfma_f32_16x16x32_bf16 v[82:85], v[208:211], v[232:235], v[82:85]
	v_mfma_f32_16x16x32_bf16 v[70:73], v[200:203], v[240:243], v[70:73]
	v_mfma_f32_16x16x32_bf16 v[66:69], v[208:211], v[240:243], v[66:69]
	s_barrier
	s_add_i32 s72, s73, s5
	v_lshl_add_u64 v[160:161], s[92:93], 0, v[132:133]
	s_mov_b32 m0, s72
	ds_read_b128 v[212:215], v143 offset:16384
	ds_read_b128 v[216:219], v143 offset:17408
	ds_read_b128 v[220:223], v143 offset:18432
	ds_read_b128 v[224:227], v143 offset:19456
	ds_read_b128 v[228:231], v143 offset:20480
	ds_read_b128 v[232:235], v143 offset:21504
	ds_read_b128 v[236:239], v143 offset:22528
	ds_read_b128 v[240:243], v143 offset:23552
	global_load_lds_dwordx4 v[160:161], off
	s_add_i32 m0, s72, 0x2000
	s_add_u32 s76, s92, 0x40000
	v_lshl_add_u64 v[244:245], s[92:93], 0, v[136:137]
	s_addc_u32 s77, s93, 0
	s_add_i32 s61, s61, s5
	global_load_lds_dwordx4 v[244:245], off
	s_mov_b32 m0, s61
	v_lshl_add_u64 v[248:249], s[94:95], 0, v[134:135]
	global_load_lds_dwordx4 v132, s[76:77]
	s_add_i32 m0, s61, 0x2000
	s_nop 0
	global_load_lds_dwordx4 v136, s[76:77]
	v_lshl_add_u64 v[246:247], s[94:95], 0, v[130:131]
	s_mov_b32 m0, s8
	s_nop 0
	global_load_lds_dwordx4 v[246:247], off
	s_mov_b32 m0, s9
	s_nop 0
	global_load_lds_dwordx4 v[248:249], off
	s_waitcnt vmcnt(8)
	s_waitcnt lgkmcnt(0)
	s_barrier
; #define PG8_STAGE(bufoff, gbase, voff) do { _Pragma("unroll") for (int _i = 0; _i < 2; ++_i) \
;         __builtin_amdgcn_global_load_lds((const unsigned*)((const char*)(gbase) + (voff)[_i]), (PG8_LAS unsigned*)(lds + (bufoff) + ldsw + _i * 8192), 16, 0, 0); } while (0)
; #define PG8_LDA(dst, b, h) do { _Pragma("unroll") for (int m = 0; m < 4; ++m) _Pragma("unroll") for (int k = 0; k < 2; ++k) dst[m][k] = *(const PG8_LAS bf16x8*)(lds + PG8_SA(b, h) + aoff + m * 2048 + k * 1024); } while (0)
; #define PG8_LDB(dst, b, h) do { _Pragma("unroll") for (int n = 0; n < 2; ++n) _Pragma("unroll") for (int k = 0; k < 2; ++k) dst[n][k] = *(const PG8_LAS bf16x8*)(lds + PG8_SB(b, h) + boff + n * 2048 + k * 1024); } while (0)
; #define PG8_MMA(ai, bj, At, Bt) do { __builtin_amdgcn_s_setprio(1); _Pragma("unroll") for (int m = 0; m < 4; ++m) _Pragma("unroll") for (int n = 0; n < 2; ++n) _Pragma("unroll") for (int k = 0; k < 2; ++k) \
;         acc[ai][bj][m][n] = __builtin_amdgcn_mfma_f32_16x16x32_bf16(Bt[n][k], At[m][k], acc[ai][bj][m][n], 0, 0, 0); __builtin_amdgcn_s_setprio(0); } while (0)
; #define PG8_WAIT_V(n) asm volatile("s_waitcnt vmcnt(" #n ")" ::: "memory")
; #define PG8_WAIT_L(n) asm volatile("s_waitcnt lgkmcnt(" #n ")" ::: "memory")
; #define PG8_BAR __builtin_amdgcn_s_barrier()
; #define PG8_SCHED __builtin_amdgcn_sched_barrier(0)
; template <class Epi, class Sched, bool ALIGN_EPI = false, bool SP2 = false>
; __device__ __forceinline__ void gemm_phase(PG8_LAS unsigned char* lds, const Gemm g, const Sched& S, const Epi& E) {
;     ...
;             PG8_WAIT_V(8); PG8_WAIT_L(0); PG8_BAR; PG8_MMA(1, 0, At, B0); PG8_MMA(1, 1, At, B1); PG8_BAR; PG8_SCHED;
;             PG8_LDB(B0, 1, 0); PG8_LDB(B1, 1, 1); PG8_SCHED; PG8_LDA(At, 1, 0); PG8_STAGE(PG8_SA(0, 1), a2 + hstep, voffA);
;             PG8_WAIT_V(8); PG8_WAIT_L(0); PG8_BAR; PG8_MMA(0, 0, At, B0); PG8_MMA(0, 1, At, B1); PG8_BAR; PG8_SCHED;
	v_mfma_f32_16x16x32_bf16 v[62:65], v[170:173], v[212:215], v[62:65]
	v_mfma_f32_16x16x32_bf16 v[58:61], v[178:181], v[212:215], v[58:61]
	v_mfma_f32_16x16x32_bf16 v[50:53], v[170:173], v[220:223], v[50:53]
	v_mfma_f32_16x16x32_bf16 v[42:45], v[178:181], v[220:223], v[42:45]
	v_mfma_f32_16x16x32_bf16 v[34:37], v[170:173], v[228:231], v[34:37]
	v_mfma_f32_16x16x32_bf16 v[24:27], v[178:181], v[228:231], v[24:27]
	v_mfma_f32_16x16x32_bf16 v[16:19], v[170:173], v[236:239], v[16:19]
	v_mfma_f32_16x16x32_bf16 v[8:11], v[178:181], v[236:239], v[8:11]
	v_mfma_f32_16x16x32_bf16 v[62:65], v[174:177], v[216:219], v[62:65]
	v_mfma_f32_16x16x32_bf16 v[58:61], v[182:185], v[216:219], v[58:61]
	v_mfma_f32_16x16x32_bf16 v[50:53], v[174:177], v[224:227], v[50:53]
	v_mfma_f32_16x16x32_bf16 v[42:45], v[182:185], v[224:227], v[42:45]
	v_mfma_f32_16x16x32_bf16 v[34:37], v[174:177], v[232:235], v[34:37]
	v_mfma_f32_16x16x32_bf16 v[24:27], v[182:185], v[232:235], v[24:27]
	v_mfma_f32_16x16x32_bf16 v[16:19], v[174:177], v[240:243], v[16:19]
	v_mfma_f32_16x16x32_bf16 v[8:11], v[182:185], v[240:243], v[8:11]
	v_mfma_f32_16x16x32_bf16 v[54:57], v[196:199], v[212:215], v[54:57]
	v_mfma_f32_16x16x32_bf16 v[46:49], v[204:207], v[212:215], v[46:49]
	v_mfma_f32_16x16x32_bf16 v[38:41], v[196:199], v[220:223], v[38:41]
	v_mfma_f32_16x16x32_bf16 v[28:31], v[204:207], v[220:223], v[28:31]
	v_mfma_f32_16x16x32_bf16 v[20:23], v[196:199], v[228:231], v[20:23]
	v_mfma_f32_16x16x32_bf16 v[12:15], v[204:207], v[228:231], v[12:15]
	v_mfma_f32_16x16x32_bf16 v[4:7], v[196:199], v[236:239], v[4:7]
	v_mfma_f32_16x16x32_bf16 v[0:3], v[204:207], v[236:239], v[0:3]
	v_mfma_f32_16x16x32_bf16 v[54:57], v[200:203], v[216:219], v[54:57]
	v_mfma_f32_16x16x32_bf16 v[46:49], v[208:211], v[216:219], v[46:49]
	v_mfma_f32_16x16x32_bf16 v[38:41], v[200:203], v[224:227], v[38:41]
	v_mfma_f32_16x16x32_bf16 v[28:31], v[208:211], v[224:227], v[28:31]
	v_mfma_f32_16x16x32_bf16 v[20:23], v[200:203], v[232:235], v[20:23]
	v_mfma_f32_16x16x32_bf16 v[12:15], v[208:211], v[232:235], v[12:15]
	v_mfma_f32_16x16x32_bf16 v[4:7], v[200:203], v[240:243], v[4:7]
	v_mfma_f32_16x16x32_bf16 v[0:3], v[208:211], v[240:243], v[0:3]
	s_barrier
	s_add_i32 s61, 0, 0x18000
	v_add_u32_e32 v147, s61, v139
	s_add_i32 s72, 0, 0x1c000
	ds_read_b128 v[170:173], v147
	ds_read_b128 v[174:177], v147 offset:1024
	ds_read_b128 v[178:181], v147 offset:2048
	ds_read_b128 v[182:185], v147 offset:3072
	v_add_u32_e32 v147, s72, v139
	ds_read_b128 v[196:199], v147
	ds_read_b128 v[200:203], v147 offset:1024
	ds_read_b128 v[204:207], v147 offset:2048
	ds_read_b128 v[208:211], v147 offset:3072
	s_add_u32 s76, s94, 0x40000
	s_addc_u32 s77, s95, 0
	s_mov_b32 m0, s89
	ds_read_b128 v[212:215], v143 offset:32768
	ds_read_b128 v[216:219], v143 offset:33792
	ds_read_b128 v[220:223], v143 offset:34816
	ds_read_b128 v[224:227], v143 offset:35840
	ds_read_b128 v[228:231], v143 offset:36864
	ds_read_b128 v[232:235], v143 offset:37888
	ds_read_b128 v[236:239], v143 offset:38912
	ds_read_b128 v[240:243], v143 offset:39936
	global_load_lds_dwordx4 v130, s[76:77]
	s_mov_b32 m0, s96
	s_nop 0
	global_load_lds_dwordx4 v134, s[76:77]
	s_waitcnt vmcnt(8)
	s_waitcnt lgkmcnt(0)
	s_barrier
	v_mfma_f32_16x16x32_bf16 v[126:129], v[170:173], v[212:215], v[126:129]
	v_mfma_f32_16x16x32_bf16 v[122:125], v[178:181], v[212:215], v[122:125]
	v_mfma_f32_16x16x32_bf16 v[110:113], v[170:173], v[220:223], v[110:113]
	v_mfma_f32_16x16x32_bf16 v[106:109], v[178:181], v[220:223], v[106:109]
	v_mfma_f32_16x16x32_bf16 v[94:97], v[170:173], v[228:231], v[94:97]
	v_mfma_f32_16x16x32_bf16 v[90:93], v[178:181], v[228:231], v[90:93]
	v_mfma_f32_16x16x32_bf16 v[78:81], v[170:173], v[236:239], v[78:81]
	v_mfma_f32_16x16x32_bf16 v[74:77], v[178:181], v[236:239], v[74:77]
	v_mfma_f32_16x16x32_bf16 v[126:129], v[174:177], v[216:219], v[126:129]
	v_mfma_f32_16x16x32_bf16 v[122:125], v[182:185], v[216:219], v[122:125]
	v_mfma_f32_16x16x32_bf16 v[110:113], v[174:177], v[224:227], v[110:113]
	v_mfma_f32_16x16x32_bf16 v[106:109], v[182:185], v[224:227], v[106:109]
	v_mfma_f32_16x16x32_bf16 v[94:97], v[174:177], v[232:235], v[94:97]
	v_mfma_f32_16x16x32_bf16 v[90:93], v[182:185], v[232:235], v[90:93]
	v_mfma_f32_16x16x32_bf16 v[78:81], v[174:177], v[240:243], v[78:81]
	v_mfma_f32_16x16x32_bf16 v[74:77], v[182:185], v[240:243], v[74:77]
	v_mfma_f32_16x16x32_bf16 v[118:121], v[196:199], v[212:215], v[118:121]
	v_mfma_f32_16x16x32_bf16 v[114:117], v[204:207], v[212:215], v[114:117]
	v_mfma_f32_16x16x32_bf16 v[102:105], v[196:199], v[220:223], v[102:105]
	v_mfma_f32_16x16x32_bf16 v[98:101], v[204:207], v[220:223], v[98:101]
	v_mfma_f32_16x16x32_bf16 v[86:89], v[196:199], v[228:231], v[86:89]
	v_mfma_f32_16x16x32_bf16 v[82:85], v[204:207], v[228:231], v[82:85]
	v_mfma_f32_16x16x32_bf16 v[70:73], v[196:199], v[236:239], v[70:73]
	v_mfma_f32_16x16x32_bf16 v[66:69], v[204:207], v[236:239], v[66:69]
	v_mfma_f32_16x16x32_bf16 v[118:121], v[200:203], v[216:219], v[118:121]
	v_mfma_f32_16x16x32_bf16 v[114:117], v[208:211], v[216:219], v[114:117]
	v_mfma_f32_16x16x32_bf16 v[102:105], v[200:203], v[224:227], v[102:105]
	v_mfma_f32_16x16x32_bf16 v[98:101], v[208:211], v[224:227], v[98:101]
	v_mfma_f32_16x16x32_bf16 v[86:89], v[200:203], v[232:235], v[86:89]
	v_mfma_f32_16x16x32_bf16 v[82:85], v[208:211], v[232:235], v[82:85]
	v_mfma_f32_16x16x32_bf16 v[70:73], v[200:203], v[240:243], v[70:73]
	v_mfma_f32_16x16x32_bf16 v[66:69], v[208:211], v[240:243], v[66:69]
	s_barrier
; #define PG8_STAGE(bufoff, gbase, voff) do { _Pragma("unroll") for (int _i = 0; _i < 2; ++_i) \
;         __builtin_amdgcn_global_load_lds((const unsigned*)((const char*)(gbase) + (voff)[_i]), (PG8_LAS unsigned*)(lds + (bufoff) + ldsw + _i * 8192), 16, 0, 0); } while (0)
; #define PG8_LDA(dst, b, h) do { _Pragma("unroll") for (int m = 0; m < 4; ++m) _Pragma("unroll") for (int k = 0; k < 2; ++k) dst[m][k] = *(const PG8_LAS bf16x8*)(lds + PG8_SA(b, h) + aoff + m * 2048 + k * 1024); } while (0)
; #define PG8_MMA(ai, bj, At, Bt) do { __builtin_amdgcn_s_setprio(1); _Pragma("unroll") for (int m = 0; m < 4; ++m) _Pragma("unroll") for (int n = 0; n < 2; ++n) _Pragma("unroll") for (int k = 0; k < 2; ++k) \
;         acc[ai][bj][m][n] = __builtin_amdgcn_mfma_f32_16x16x32_bf16(Bt[n][k], At[m][k], acc[ai][bj][m][n], 0, 0, 0); __builtin_amdgcn_s_setprio(0); } while (0)
; #define PG8_WAIT_V(n) asm volatile("s_waitcnt vmcnt(" #n ")" ::: "memory")
; #define PG8_WAIT_L(n) asm volatile("s_waitcnt lgkmcnt(" #n ")" ::: "memory")
; #define PG8_BAR __builtin_amdgcn_s_barrier()
; #define PG8_SCHED __builtin_amdgcn_sched_barrier(0)
; template <class Epi, class Sched, bool ALIGN_EPI = false, bool SP2 = false>
; __device__ __forceinline__ void gemm_phase(PG8_LAS unsigned char* lds, const Gemm g, const Sched& S, const Epi& E) {
;     ...
;             PG8_LDA(At, 1, 1); PG8_STAGE(PG8_SB(1, 0), b3, voffB); PG8_STAGE(PG8_SB(1, 1), b3 + hstep, voffB); PG8_STAGE(PG8_SA(1, 0), a3, voffA);
;             PG8_WAIT_V(8); PG8_WAIT_L(0); PG8_BAR; PG8_MMA(1, 0, At, B0); PG8_MMA(1, 1, At, B1); PG8_BAR; PG8_SCHED;
;     ...
;         if constexpr (ALIGN_EPI) { if (wr == 0) PG8_BAR; }
	s_add_i32 s61, s61, s5
	v_lshl_add_u64 v[160:161], v[160:161], 0, s[34:35]
	s_mov_b32 m0, s61
	ds_read_b128 v[212:215], v143 offset:49152
	ds_read_b128 v[216:219], v143 offset:50176
	ds_read_b128 v[220:223], v143 offset:51200
	ds_read_b128 v[224:227], v143 offset:52224
	ds_read_b128 v[228:231], v143 offset:53248
	ds_read_b128 v[232:235], v143 offset:54272
	ds_read_b128 v[236:239], v143 offset:55296
	ds_read_b128 v[240:243], v143 offset:56320
	global_load_lds_dwordx4 v[160:161], off
	s_add_i32 m0, s61, 0x2000
	s_add_u32 s76, s92, 0x40080
	v_lshl_add_u64 v[160:161], v[244:245], 0, s[34:35]
	s_addc_u32 s77, s93, 0
	s_add_i32 s61, s72, s5
	global_load_lds_dwordx4 v[160:161], off
	s_mov_b32 m0, s61
	s_nop 0
	global_load_lds_dwordx4 v132, s[76:77]
	s_add_i32 m0, s61, 0x2000
	s_nop 0
	global_load_lds_dwordx4 v136, s[76:77]
	v_lshl_add_u64 v[160:161], v[246:247], 0, s[34:35]
	s_mov_b32 m0, s0
	s_nop 0
	global_load_lds_dwordx4 v[160:161], off
	v_lshl_add_u64 v[160:161], v[248:249], 0, s[34:35]
	s_mov_b32 m0, s97
	s_nop 0
	global_load_lds_dwordx4 v[160:161], off
	s_waitcnt vmcnt(8)
	s_waitcnt lgkmcnt(0)
	s_barrier
	v_mfma_f32_16x16x32_bf16 v[62:65], v[170:173], v[212:215], v[62:65]
	v_mfma_f32_16x16x32_bf16 v[58:61], v[178:181], v[212:215], v[58:61]
	v_mfma_f32_16x16x32_bf16 v[50:53], v[170:173], v[220:223], v[50:53]
	v_mfma_f32_16x16x32_bf16 v[42:45], v[178:181], v[220:223], v[42:45]
	v_mfma_f32_16x16x32_bf16 v[34:37], v[170:173], v[228:231], v[34:37]
	v_mfma_f32_16x16x32_bf16 v[24:27], v[178:181], v[228:231], v[24:27]
	v_mfma_f32_16x16x32_bf16 v[16:19], v[170:173], v[236:239], v[16:19]
	v_mfma_f32_16x16x32_bf16 v[8:11], v[178:181], v[236:239], v[8:11]
	v_mfma_f32_16x16x32_bf16 v[62:65], v[174:177], v[216:219], v[62:65]
	v_mfma_f32_16x16x32_bf16 v[58:61], v[182:185], v[216:219], v[58:61]
	v_mfma_f32_16x16x32_bf16 v[50:53], v[174:177], v[224:227], v[50:53]
	v_mfma_f32_16x16x32_bf16 v[42:45], v[182:185], v[224:227], v[42:45]
	v_mfma_f32_16x16x32_bf16 v[34:37], v[174:177], v[232:235], v[34:37]
	v_mfma_f32_16x16x32_bf16 v[24:27], v[182:185], v[232:235], v[24:27]
	v_mfma_f32_16x16x32_bf16 v[16:19], v[174:177], v[240:243], v[16:19]
	v_mfma_f32_16x16x32_bf16 v[8:11], v[182:185], v[240:243], v[8:11]
	v_mfma_f32_16x16x32_bf16 v[54:57], v[196:199], v[212:215], v[54:57]
	v_mfma_f32_16x16x32_bf16 v[46:49], v[204:207], v[212:215], v[46:49]
	v_mfma_f32_16x16x32_bf16 v[38:41], v[196:199], v[220:223], v[38:41]
	v_mfma_f32_16x16x32_bf16 v[28:31], v[204:207], v[220:223], v[28:31]
	v_mfma_f32_16x16x32_bf16 v[20:23], v[196:199], v[228:231], v[20:23]
	v_mfma_f32_16x16x32_bf16 v[12:15], v[204:207], v[228:231], v[12:15]
	v_mfma_f32_16x16x32_bf16 v[4:7], v[196:199], v[236:239], v[4:7]
	v_mfma_f32_16x16x32_bf16 v[0:3], v[204:207], v[236:239], v[0:3]
	v_mfma_f32_16x16x32_bf16 v[54:57], v[200:203], v[216:219], v[54:57]
	v_mfma_f32_16x16x32_bf16 v[46:49], v[208:211], v[216:219], v[46:49]
	v_mfma_f32_16x16x32_bf16 v[38:41], v[200:203], v[224:227], v[38:41]
	v_mfma_f32_16x16x32_bf16 v[28:31], v[208:211], v[224:227], v[28:31]
	v_mfma_f32_16x16x32_bf16 v[20:23], v[200:203], v[232:235], v[20:23]
	v_mfma_f32_16x16x32_bf16 v[12:15], v[208:211], v[232:235], v[12:15]
	v_mfma_f32_16x16x32_bf16 v[4:7], v[200:203], v[240:243], v[4:7]
	v_mfma_f32_16x16x32_bf16 v[0:3], v[208:211], v[240:243], v[0:3]
	s_barrier
	s_add_i32 s80, s80, 2
	s_add_u32 s4, s4, 0x100
	s_addc_u32 s7, s7, 0
	s_add_u32 s90, s90, 0x100
	s_addc_u32 s91, s91, 0
	s_cmp_gt_u32 s80, 13
	s_cbranch_scc0 .LBB0_66
	s_and_b64 vcc, exec, s[38:39]
	s_cbranch_vccz .LBB0_69
	s_barrier

; #define PG8_STAGE(bufoff, gbase, voff) do { _Pragma("unroll") for (int _i = 0; _i < 2; ++_i) \
;         __builtin_amdgcn_global_load_lds((const unsigned*)((const char*)(gbase) + (voff)[_i]), (PG8_LAS unsigned*)(lds + (bufoff) + ldsw + _i * 8192), 16, 0, 0); } while (0)
; #define PG8_LDA(dst, b, h) do { _Pragma("unroll") for (int m = 0; m < 4; ++m) _Pragma("unroll") for (int k = 0; k < 2; ++k) dst[m][k] = *(const PG8_LAS bf16x8*)(lds + PG8_SA(b, h) + aoff + m * 2048 + k * 1024); } while (0)
; #define PG8_LDB(dst, b, h) do { _Pragma("unroll") for (int n = 0; n < 2; ++n) _Pragma("unroll") for (int k = 0; k < 2; ++k) dst[n][k] = *(const PG8_LAS bf16x8*)(lds + PG8_SB(b, h) + boff + n * 2048 + k * 1024); } while (0)
; #define PG8_MMA(ai, bj, At, Bt) do { __builtin_amdgcn_s_setprio(1); _Pragma("unroll") for (int m = 0; m < 4; ++m) _Pragma("unroll") for (int n = 0; n < 2; ++n) _Pragma("unroll") for (int k = 0; k < 2; ++k) \
;         acc[ai][bj][m][n] = __builtin_amdgcn_mfma_f32_16x16x32_bf16(Bt[n][k], At[m][k], acc[ai][bj][m][n], 0, 0, 0); __builtin_amdgcn_s_setprio(0); } while (0)
; #define PG8_WAIT_V(n) asm volatile("s_waitcnt vmcnt(" #n ")" ::: "memory")
; #define PG8_WAIT_L(n) asm volatile("s_waitcnt lgkmcnt(" #n ")" ::: "memory")
; #define PG8_BAR __builtin_amdgcn_s_barrier()
; #define PG8_SCHED __builtin_amdgcn_sched_barrier(0)
; template <class Epi, class Sched, bool ALIGN_EPI = false, bool SP2 = false>
; __device__ __forceinline__ void gemm_phase(PG8_LAS unsigned char* lds, const Gemm g, const Sched& S, const Epi& E) {
;     ...
;             const bool last = (t == nt - 2);
;             const char* a1 = cA + (size_t)(t + 1) * kstep;
;             const char* a2 = last ? nA : cA + (size_t)(t + 2) * kstep; const char* b2 = last ? nB : cB + (size_t)(t + 2) * kstep;
;             const char* a3 = a2 + kstep; const char* b3 = b2 + kstep;
;             if (last && has_next) S.a_ready(nxt);
;             if constexpr (SP2) {
;             PG8_LDB(B0, 0, 0); PG8_LDB(B1, 0, 1); PG8_SCHED; PG8_LDA(At, 0, 0); PG8_STAGE(PG8_SA(1, 1), a1 + hstep, voffA);
;             PG8_WAIT_V(8); PG8_WAIT_L(0); PG8_BAR; PG8_MMA(0, 0, At, B0); PG8_MMA(0, 1, At, B1); PG8_BAR; PG8_SCHED;
;             PG8_LDA(At, 0, 1); PG8_STAGE(PG8_SB(0, 0), b2, voffB); PG8_STAGE(PG8_SB(0, 1), b2 + hstep, voffB); PG8_STAGE(PG8_SA(0, 0), a2, voffA);
.LBB0_91:
	s_add_u32 s48, s46, 0xfffc0080
	s_addc_u32 s49, s47, -1
	s_add_i32 s61, 0, 0x10000
	s_cmp_eq_u32 s80, 12
	s_cselect_b32 s51, s89, s49
	s_cselect_b32 s50, vcc_lo, s48
	s_cselect_b32 s49, s87, s7
	s_cselect_b32 s48, vcc_hi, s5
	s_add_i32 s72, 0, 0x14000
	v_add_u32_e32 v110, s61, v170
	v_add_u32_e32 v173, s72, v170
	ds_read_b128 v[98:101], v110
	ds_read_b128 v[102:105], v110 offset:1024
	ds_read_b128 v[106:109], v110 offset:2048
	ds_read_b128 v[110:113], v110 offset:3072
	ds_read_b128 v[158:161], v173
	ds_read_b128 v[174:177], v173 offset:1024
	ds_read_b128 v[178:181], v173 offset:2048
	ds_read_b128 v[182:185], v173 offset:3072
	s_add_i32 m0, s9, 0xc000
	ds_read_b128 v[196:199], v172
	ds_read_b128 v[200:203], v172 offset:1024
	ds_read_b128 v[204:207], v172 offset:2048
	ds_read_b128 v[208:211], v172 offset:3072
	ds_read_b128 v[212:215], v172 offset:4096
	ds_read_b128 v[216:219], v172 offset:5120
	ds_read_b128 v[220:223], v172 offset:6144
	ds_read_b128 v[224:227], v172 offset:7168
	global_load_lds_dwordx4 v156, s[46:47]
	s_add_i32 m0, s9, 0xe000
	s_nop 0
	global_load_lds_dwordx4 v154, s[46:47]
	s_waitcnt vmcnt(8)
	s_waitcnt lgkmcnt(0)
	s_barrier
	v_mfma_f32_16x16x32_bf16 v[142:145], v[98:101], v[196:199], v[142:145]
	v_mfma_f32_16x16x32_bf16 v[138:141], v[106:109], v[196:199], v[138:141]
	v_mfma_f32_16x16x32_bf16 v[126:129], v[98:101], v[204:207], v[126:129]
	v_mfma_f32_16x16x32_bf16 v[122:125], v[106:109], v[204:207], v[122:125]
	v_mfma_f32_16x16x32_bf16 v[94:97], v[98:101], v[212:215], v[94:97]
	v_mfma_f32_16x16x32_bf16 v[90:93], v[106:109], v[212:215], v[90:93]
	v_mfma_f32_16x16x32_bf16 v[78:81], v[98:101], v[220:223], v[78:81]
	v_mfma_f32_16x16x32_bf16 v[74:77], v[106:109], v[220:223], v[74:77]
	v_mfma_f32_16x16x32_bf16 v[142:145], v[102:105], v[200:203], v[142:145]
	v_mfma_f32_16x16x32_bf16 v[138:141], v[110:113], v[200:203], v[138:141]
	v_mfma_f32_16x16x32_bf16 v[126:129], v[102:105], v[208:211], v[126:129]
	v_mfma_f32_16x16x32_bf16 v[122:125], v[110:113], v[208:211], v[122:125]
	v_mfma_f32_16x16x32_bf16 v[94:97], v[102:105], v[216:219], v[94:97]
	v_mfma_f32_16x16x32_bf16 v[90:93], v[110:113], v[216:219], v[90:93]
	v_mfma_f32_16x16x32_bf16 v[78:81], v[102:105], v[224:227], v[78:81]
	v_mfma_f32_16x16x32_bf16 v[74:77], v[110:113], v[224:227], v[74:77]
	v_mfma_f32_16x16x32_bf16 v[134:137], v[158:161], v[196:199], v[134:137]
	v_mfma_f32_16x16x32_bf16 v[130:133], v[178:181], v[196:199], v[130:133]
	v_mfma_f32_16x16x32_bf16 v[118:121], v[158:161], v[204:207], v[118:121]
	v_mfma_f32_16x16x32_bf16 v[114:117], v[178:181], v[204:207], v[114:117]
	v_mfma_f32_16x16x32_bf16 v[86:89], v[158:161], v[212:215], v[86:89]
	v_mfma_f32_16x16x32_bf16 v[82:85], v[178:181], v[212:215], v[82:85]
	v_mfma_f32_16x16x32_bf16 v[70:73], v[158:161], v[220:223], v[70:73]
	v_mfma_f32_16x16x32_bf16 v[66:69], v[178:181], v[220:223], v[66:69]
	v_mfma_f32_16x16x32_bf16 v[134:137], v[174:177], v[200:203], v[134:137]
	v_mfma_f32_16x16x32_bf16 v[130:133], v[182:185], v[200:203], v[130:133]
	v_mfma_f32_16x16x32_bf16 v[118:121], v[174:177], v[208:211], v[118:121]
	v_mfma_f32_16x16x32_bf16 v[114:117], v[182:185], v[208:211], v[114:117]
	v_mfma_f32_16x16x32_bf16 v[86:89], v[174:177], v[216:219], v[86:89]
	v_mfma_f32_16x16x32_bf16 v[82:85], v[182:185], v[216:219], v[82:85]
	v_mfma_f32_16x16x32_bf16 v[70:73], v[174:177], v[224:227], v[70:73]
	v_mfma_f32_16x16x32_bf16 v[66:69], v[182:185], v[224:227], v[66:69]
	s_barrier
	s_add_i32 s61, s61, s8
	v_lshl_add_u64 v[228:229], s[48:49], 0, v[148:149]
	s_mov_b32 m0, s61
	ds_read_b128 v[196:199], v172 offset:16384
	ds_read_b128 v[200:203], v172 offset:17408
	ds_read_b128 v[204:207], v172 offset:18432
	ds_read_b128 v[208:211], v172 offset:19456
	ds_read_b128 v[212:215], v172 offset:20480
	ds_read_b128 v[216:219], v172 offset:21504
	ds_read_b128 v[220:223], v172 offset:22528
	ds_read_b128 v[224:227], v172 offset:23552
	global_load_lds_dwordx4 v[228:229], off
	s_add_i32 m0, s61, 0x2000
	s_add_u32 s76, s48, 0x40000
	v_lshl_add_u64 v[230:231], s[48:49], 0, v[152:153]
	s_addc_u32 s77, s49, 0
	s_add_i32 s61, s72, s8
	global_load_lds_dwordx4 v[230:231], off
	s_mov_b32 m0, s61
	v_lshl_add_u64 v[234:235], s[50:51], 0, v[150:151]
	global_load_lds_dwordx4 v148, s[76:77]
	s_add_i32 m0, s61, 0x2000
	s_nop 0
	global_load_lds_dwordx4 v152, s[76:77]
	v_lshl_add_u64 v[232:233], s[50:51], 0, v[146:147]
	s_mov_b32 m0, s9
	s_nop 0
	global_load_lds_dwordx4 v[232:233], off
	s_mov_b32 m0, s96
	s_nop 0
	global_load_lds_dwordx4 v[234:235], off
	s_waitcnt vmcnt(8)
	s_waitcnt lgkmcnt(0)
	s_barrier
; #define PG8_STAGE(bufoff, gbase, voff) do { _Pragma("unroll") for (int _i = 0; _i < 2; ++_i) \
;         __builtin_amdgcn_global_load_lds((const unsigned*)((const char*)(gbase) + (voff)[_i]), (PG8_LAS unsigned*)(lds + (bufoff) + ldsw + _i * 8192), 16, 0, 0); } while (0)
; #define PG8_LDA(dst, b, h) do { _Pragma("unroll") for (int m = 0; m < 4; ++m) _Pragma("unroll") for (int k = 0; k < 2; ++k) dst[m][k] = *(const PG8_LAS bf16x8*)(lds + PG8_SA(b, h) + aoff + m * 2048 + k * 1024); } while (0)
; #define PG8_LDB(dst, b, h) do { _Pragma("unroll") for (int n = 0; n < 2; ++n) _Pragma("unroll") for (int k = 0; k < 2; ++k) dst[n][k] = *(const PG8_LAS bf16x8*)(lds + PG8_SB(b, h) + boff + n * 2048 + k * 1024); } while (0)
; #define PG8_MMA(ai, bj, At, Bt) do { __builtin_amdgcn_s_setprio(1); _Pragma("unroll") for (int m = 0; m < 4; ++m) _Pragma("unroll") for (int n = 0; n < 2; ++n) _Pragma("unroll") for (int k = 0; k < 2; ++k) \
;         acc[ai][bj][m][n] = __builtin_amdgcn_mfma_f32_16x16x32_bf16(Bt[n][k], At[m][k], acc[ai][bj][m][n], 0, 0, 0); __builtin_amdgcn_s_setprio(0); } while (0)
; #define PG8_WAIT_V(n) asm volatile("s_waitcnt vmcnt(" #n ")" ::: "memory")
; #define PG8_WAIT_L(n) asm volatile("s_waitcnt lgkmcnt(" #n ")" ::: "memory")
; #define PG8_BAR __builtin_amdgcn_s_barrier()
; #define PG8_SCHED __builtin_amdgcn_sched_barrier(0)
; template <class Epi, class Sched, bool ALIGN_EPI = false, bool SP2 = false>
; __device__ __forceinline__ void gemm_phase(PG8_LAS unsigned char* lds, const Gemm g, const Sched& S, const Epi& E) {
;     ...
;             PG8_WAIT_V(8); PG8_WAIT_L(0); PG8_BAR; PG8_MMA(1, 0, At, B0); PG8_MMA(1, 1, At, B1); PG8_BAR; PG8_SCHED;
;             PG8_LDB(B0, 1, 0); PG8_LDB(B1, 1, 1); PG8_SCHED; PG8_LDA(At, 1, 0); PG8_STAGE(PG8_SA(0, 1), a2 + hstep, voffA);
;             PG8_WAIT_V(8); PG8_WAIT_L(0); PG8_BAR; PG8_MMA(0, 0, At, B0); PG8_MMA(0, 1, At, B1); PG8_BAR; PG8_SCHED;
	v_mfma_f32_16x16x32_bf16 v[62:65], v[98:101], v[196:199], v[62:65]
	v_mfma_f32_16x16x32_bf16 v[58:61], v[106:109], v[196:199], v[58:61]
	v_mfma_f32_16x16x32_bf16 v[50:53], v[98:101], v[204:207], v[50:53]
	v_mfma_f32_16x16x32_bf16 v[42:45], v[106:109], v[204:207], v[42:45]
	v_mfma_f32_16x16x32_bf16 v[34:37], v[98:101], v[212:215], v[34:37]
	v_mfma_f32_16x16x32_bf16 v[24:27], v[106:109], v[212:215], v[24:27]
	v_mfma_f32_16x16x32_bf16 v[12:15], v[98:101], v[220:223], v[12:15]
	v_mfma_f32_16x16x32_bf16 v[8:11], v[106:109], v[220:223], v[8:11]
	v_mfma_f32_16x16x32_bf16 v[62:65], v[102:105], v[200:203], v[62:65]
	v_mfma_f32_16x16x32_bf16 v[58:61], v[110:113], v[200:203], v[58:61]
	v_mfma_f32_16x16x32_bf16 v[50:53], v[102:105], v[208:211], v[50:53]
	v_mfma_f32_16x16x32_bf16 v[42:45], v[110:113], v[208:211], v[42:45]
	v_mfma_f32_16x16x32_bf16 v[34:37], v[102:105], v[216:219], v[34:37]
	v_mfma_f32_16x16x32_bf16 v[24:27], v[110:113], v[216:219], v[24:27]
	v_mfma_f32_16x16x32_bf16 v[12:15], v[102:105], v[224:227], v[12:15]
	v_mfma_f32_16x16x32_bf16 v[8:11], v[110:113], v[224:227], v[8:11]
	v_mfma_f32_16x16x32_bf16 v[54:57], v[158:161], v[196:199], v[54:57]
	v_mfma_f32_16x16x32_bf16 v[46:49], v[178:181], v[196:199], v[46:49]
	v_mfma_f32_16x16x32_bf16 v[38:41], v[158:161], v[204:207], v[38:41]
	v_mfma_f32_16x16x32_bf16 v[28:31], v[178:181], v[204:207], v[28:31]
	v_mfma_f32_16x16x32_bf16 v[20:23], v[158:161], v[212:215], v[20:23]
	v_mfma_f32_16x16x32_bf16 v[16:19], v[178:181], v[212:215], v[16:19]
	v_mfma_f32_16x16x32_bf16 v[4:7], v[158:161], v[220:223], v[4:7]
	v_mfma_f32_16x16x32_bf16 v[0:3], v[178:181], v[220:223], v[0:3]
	v_mfma_f32_16x16x32_bf16 v[54:57], v[174:177], v[200:203], v[54:57]
	v_mfma_f32_16x16x32_bf16 v[46:49], v[182:185], v[200:203], v[46:49]
	v_mfma_f32_16x16x32_bf16 v[38:41], v[174:177], v[208:211], v[38:41]
	v_mfma_f32_16x16x32_bf16 v[28:31], v[182:185], v[208:211], v[28:31]
	v_mfma_f32_16x16x32_bf16 v[20:23], v[174:177], v[216:219], v[20:23]
	v_mfma_f32_16x16x32_bf16 v[16:19], v[182:185], v[216:219], v[16:19]
	v_mfma_f32_16x16x32_bf16 v[4:7], v[174:177], v[224:227], v[4:7]
	v_mfma_f32_16x16x32_bf16 v[0:3], v[182:185], v[224:227], v[0:3]
	s_barrier
	s_add_i32 s61, 0, 0x18000
	s_add_i32 s72, 0, 0x1c000
	v_add_u32_e32 v110, s61, v170
	v_add_u32_e32 v173, s72, v170
	ds_read_b128 v[98:101], v110
	ds_read_b128 v[102:105], v110 offset:1024
	ds_read_b128 v[106:109], v110 offset:2048
	ds_read_b128 v[110:113], v110 offset:3072
	ds_read_b128 v[158:161], v173
	ds_read_b128 v[174:177], v173 offset:1024
	ds_read_b128 v[178:181], v173 offset:2048
	ds_read_b128 v[182:185], v173 offset:3072
	s_add_u32 s50, s50, 0x40000
	s_addc_u32 s51, s51, 0
	s_mov_b32 m0, s97
	ds_read_b128 v[196:199], v172 offset:32768
	ds_read_b128 v[200:203], v172 offset:33792
	ds_read_b128 v[204:207], v172 offset:34816
	ds_read_b128 v[208:211], v172 offset:35840
	ds_read_b128 v[212:215], v172 offset:36864
	ds_read_b128 v[216:219], v172 offset:37888
	ds_read_b128 v[220:223], v172 offset:38912
	ds_read_b128 v[224:227], v172 offset:39936
	global_load_lds_dwordx4 v146, s[50:51]
	s_mov_b32 m0, s2
	s_nop 0
	global_load_lds_dwordx4 v150, s[50:51]
	s_waitcnt vmcnt(8)
	s_waitcnt lgkmcnt(0)
	s_barrier
	v_mfma_f32_16x16x32_bf16 v[142:145], v[98:101], v[196:199], v[142:145]
	v_mfma_f32_16x16x32_bf16 v[138:141], v[106:109], v[196:199], v[138:141]
	v_mfma_f32_16x16x32_bf16 v[126:129], v[98:101], v[204:207], v[126:129]
	v_mfma_f32_16x16x32_bf16 v[122:125], v[106:109], v[204:207], v[122:125]
	v_mfma_f32_16x16x32_bf16 v[94:97], v[98:101], v[212:215], v[94:97]
	v_mfma_f32_16x16x32_bf16 v[90:93], v[106:109], v[212:215], v[90:93]
	v_mfma_f32_16x16x32_bf16 v[78:81], v[98:101], v[220:223], v[78:81]
	v_mfma_f32_16x16x32_bf16 v[74:77], v[106:109], v[220:223], v[74:77]
	v_mfma_f32_16x16x32_bf16 v[142:145], v[102:105], v[200:203], v[142:145]
	v_mfma_f32_16x16x32_bf16 v[138:141], v[110:113], v[200:203], v[138:141]
	v_mfma_f32_16x16x32_bf16 v[126:129], v[102:105], v[208:211], v[126:129]
	v_mfma_f32_16x16x32_bf16 v[122:125], v[110:113], v[208:211], v[122:125]
	v_mfma_f32_16x16x32_bf16 v[94:97], v[102:105], v[216:219], v[94:97]
	v_mfma_f32_16x16x32_bf16 v[90:93], v[110:113], v[216:219], v[90:93]
	v_mfma_f32_16x16x32_bf16 v[78:81], v[102:105], v[224:227], v[78:81]
	v_mfma_f32_16x16x32_bf16 v[74:77], v[110:113], v[224:227], v[74:77]
	v_mfma_f32_16x16x32_bf16 v[134:137], v[158:161], v[196:199], v[134:137]
	v_mfma_f32_16x16x32_bf16 v[130:133], v[178:181], v[196:199], v[130:133]
	v_mfma_f32_16x16x32_bf16 v[118:121], v[158:161], v[204:207], v[118:121]
	v_mfma_f32_16x16x32_bf16 v[114:117], v[178:181], v[204:207], v[114:117]
	v_mfma_f32_16x16x32_bf16 v[86:89], v[158:161], v[212:215], v[86:89]
	v_mfma_f32_16x16x32_bf16 v[82:85], v[178:181], v[212:215], v[82:85]
	v_mfma_f32_16x16x32_bf16 v[70:73], v[158:161], v[220:223], v[70:73]
	v_mfma_f32_16x16x32_bf16 v[66:69], v[178:181], v[220:223], v[66:69]
	v_mfma_f32_16x16x32_bf16 v[134:137], v[174:177], v[200:203], v[134:137]
	v_mfma_f32_16x16x32_bf16 v[130:133], v[182:185], v[200:203], v[130:133]
	v_mfma_f32_16x16x32_bf16 v[118:121], v[174:177], v[208:211], v[118:121]
	v_mfma_f32_16x16x32_bf16 v[114:117], v[182:185], v[208:211], v[114:117]
	v_mfma_f32_16x16x32_bf16 v[86:89], v[174:177], v[216:219], v[86:89]
	v_mfma_f32_16x16x32_bf16 v[82:85], v[182:185], v[216:219], v[82:85]
	v_mfma_f32_16x16x32_bf16 v[70:73], v[174:177], v[224:227], v[70:73]
	v_mfma_f32_16x16x32_bf16 v[66:69], v[182:185], v[224:227], v[66:69]
	s_barrier
; #define PG8_STAGE(bufoff, gbase, voff) do { _Pragma("unroll") for (int _i = 0; _i < 2; ++_i) \
;         __builtin_amdgcn_global_load_lds((const unsigned*)((const char*)(gbase) + (voff)[_i]), (PG8_LAS unsigned*)(lds + (bufoff) + ldsw + _i * 8192), 16, 0, 0); } while (0)
; #define PG8_LDA(dst, b, h) do { _Pragma("unroll") for (int m = 0; m < 4; ++m) _Pragma("unroll") for (int k = 0; k < 2; ++k) dst[m][k] = *(const PG8_LAS bf16x8*)(lds + PG8_SA(b, h) + aoff + m * 2048 + k * 1024); } while (0)
; #define PG8_MMA(ai, bj, At, Bt) do { __builtin_amdgcn_s_setprio(1); _Pragma("unroll") for (int m = 0; m < 4; ++m) _Pragma("unroll") for (int n = 0; n < 2; ++n) _Pragma("unroll") for (int k = 0; k < 2; ++k) \
;         acc[ai][bj][m][n] = __builtin_amdgcn_mfma_f32_16x16x32_bf16(Bt[n][k], At[m][k], acc[ai][bj][m][n], 0, 0, 0); __builtin_amdgcn_s_setprio(0); } while (0)
; #define PG8_WAIT_V(n) asm volatile("s_waitcnt vmcnt(" #n ")" ::: "memory")
; #define PG8_WAIT_L(n) asm volatile("s_waitcnt lgkmcnt(" #n ")" ::: "memory")
; #define PG8_BAR __builtin_amdgcn_s_barrier()
; #define PG8_SCHED __builtin_amdgcn_sched_barrier(0)
; template <class Epi, class Sched, bool ALIGN_EPI = false, bool SP2 = false>
; __device__ __forceinline__ void gemm_phase(PG8_LAS unsigned char* lds, const Gemm g, const Sched& S, const Epi& E) {
;     ...
;             PG8_LDA(At, 1, 1); PG8_STAGE(PG8_SB(1, 0), b3, voffB); PG8_STAGE(PG8_SB(1, 1), b3 + hstep, voffB); PG8_STAGE(PG8_SA(1, 0), a3, voffA);
;             PG8_WAIT_V(8); PG8_WAIT_L(0); PG8_BAR; PG8_MMA(1, 0, At, B0); PG8_MMA(1, 1, At, B1); PG8_BAR; PG8_SCHED;
;     ...
;         if constexpr (ALIGN_EPI) { if (wr == 0) PG8_BAR; }
	s_add_i32 s50, s61, s8
	v_lshl_add_u64 v[228:229], v[228:229], 0, s[34:35]
	s_mov_b32 m0, s50
	ds_read_b128 v[196:199], v172 offset:49152
	ds_read_b128 v[200:203], v172 offset:50176
	ds_read_b128 v[204:207], v172 offset:51200
	ds_read_b128 v[208:211], v172 offset:52224
	ds_read_b128 v[212:215], v172 offset:53248
	ds_read_b128 v[216:219], v172 offset:54272
	ds_read_b128 v[220:223], v172 offset:55296
	ds_read_b128 v[224:227], v172 offset:56320
	global_load_lds_dwordx4 v[228:229], off
	s_add_i32 m0, s50, 0x2000
	s_add_u32 s48, s48, 0x40080
	v_lshl_add_u64 v[228:229], v[230:231], 0, s[34:35]
	s_addc_u32 s49, s49, 0
	s_add_i32 s50, s72, s8
	global_load_lds_dwordx4 v[228:229], off
	s_mov_b32 m0, s50
	s_nop 0
	global_load_lds_dwordx4 v148, s[48:49]
	s_add_i32 m0, s50, 0x2000
	s_nop 0
	global_load_lds_dwordx4 v152, s[48:49]
	v_lshl_add_u64 v[228:229], v[232:233], 0, s[34:35]
	s_mov_b32 m0, s0
	s_nop 0
	global_load_lds_dwordx4 v[228:229], off
	v_lshl_add_u64 v[228:229], v[234:235], 0, s[34:35]
	s_mov_b32 m0, s3
	s_nop 0
	global_load_lds_dwordx4 v[228:229], off
	s_waitcnt vmcnt(8)
	s_waitcnt lgkmcnt(0)
	s_barrier
	v_mfma_f32_16x16x32_bf16 v[62:65], v[98:101], v[196:199], v[62:65]
	v_mfma_f32_16x16x32_bf16 v[58:61], v[106:109], v[196:199], v[58:61]
	v_mfma_f32_16x16x32_bf16 v[50:53], v[98:101], v[204:207], v[50:53]
	v_mfma_f32_16x16x32_bf16 v[42:45], v[106:109], v[204:207], v[42:45]
	v_mfma_f32_16x16x32_bf16 v[34:37], v[98:101], v[212:215], v[34:37]
	v_mfma_f32_16x16x32_bf16 v[24:27], v[106:109], v[212:215], v[24:27]
	v_mfma_f32_16x16x32_bf16 v[12:15], v[98:101], v[220:223], v[12:15]
	v_mfma_f32_16x16x32_bf16 v[8:11], v[106:109], v[220:223], v[8:11]
	v_mfma_f32_16x16x32_bf16 v[62:65], v[102:105], v[200:203], v[62:65]
	v_mfma_f32_16x16x32_bf16 v[58:61], v[110:113], v[200:203], v[58:61]
	v_mfma_f32_16x16x32_bf16 v[50:53], v[102:105], v[208:211], v[50:53]
	v_mfma_f32_16x16x32_bf16 v[42:45], v[110:113], v[208:211], v[42:45]
	v_mfma_f32_16x16x32_bf16 v[34:37], v[102:105], v[216:219], v[34:37]
	v_mfma_f32_16x16x32_bf16 v[24:27], v[110:113], v[216:219], v[24:27]
	v_mfma_f32_16x16x32_bf16 v[12:15], v[102:105], v[224:227], v[12:15]
	v_mfma_f32_16x16x32_bf16 v[8:11], v[110:113], v[224:227], v[8:11]
	v_mfma_f32_16x16x32_bf16 v[54:57], v[158:161], v[196:199], v[54:57]
	v_mfma_f32_16x16x32_bf16 v[46:49], v[178:181], v[196:199], v[46:49]
	v_mfma_f32_16x16x32_bf16 v[38:41], v[158:161], v[204:207], v[38:41]
	v_mfma_f32_16x16x32_bf16 v[28:31], v[178:181], v[204:207], v[28:31]
	v_mfma_f32_16x16x32_bf16 v[20:23], v[158:161], v[212:215], v[20:23]
	v_mfma_f32_16x16x32_bf16 v[16:19], v[178:181], v[212:215], v[16:19]
	v_mfma_f32_16x16x32_bf16 v[4:7], v[158:161], v[220:223], v[4:7]
	v_mfma_f32_16x16x32_bf16 v[0:3], v[178:181], v[220:223], v[0:3]
	v_mfma_f32_16x16x32_bf16 v[54:57], v[174:177], v[200:203], v[54:57]
	v_mfma_f32_16x16x32_bf16 v[46:49], v[182:185], v[200:203], v[46:49]
	v_mfma_f32_16x16x32_bf16 v[38:41], v[174:177], v[208:211], v[38:41]
	v_mfma_f32_16x16x32_bf16 v[28:31], v[182:185], v[208:211], v[28:31]
	v_mfma_f32_16x16x32_bf16 v[20:23], v[174:177], v[216:219], v[20:23]
	v_mfma_f32_16x16x32_bf16 v[16:19], v[182:185], v[216:219], v[16:19]
	v_mfma_f32_16x16x32_bf16 v[4:7], v[174:177], v[224:227], v[4:7]
	v_mfma_f32_16x16x32_bf16 v[0:3], v[182:185], v[224:227], v[0:3]
	s_barrier
	s_add_i32 s80, s80, 2
	s_add_u32 s5, s5, 0x100
	s_addc_u32 s7, s7, 0
	s_add_u32 s46, s46, 0x100
	s_addc_u32 s47, s47, 0
	s_cmp_gt_u32 s80, 13
	s_cbranch_scc0 .LBB0_91
	s_and_b64 vcc, exec, s[38:39]
	s_cbranch_vccz .LBB0_94
	s_barrier

; #define PG8_STAGE(bufoff, gbase, voff) do { _Pragma("unroll") for (int _i = 0; _i < 2; ++_i) \
;         __builtin_amdgcn_global_load_lds((const unsigned*)((const char*)(gbase) + (voff)[_i]), (PG8_LAS unsigned*)(lds + (bufoff) + ldsw + _i * 8192), 16, 0, 0); } while (0)
; #define PG8_LDA(dst, b, h) do { _Pragma("unroll") for (int m = 0; m < 4; ++m) _Pragma("unroll") for (int k = 0; k < 2; ++k) dst[m][k] = *(const PG8_LAS bf16x8*)(lds + PG8_SA(b, h) + aoff + m * 2048 + k * 1024); } while (0)
; #define PG8_LDB(dst, b, h) do { _Pragma("unroll") for (int n = 0; n < 2; ++n) _Pragma("unroll") for (int k = 0; k < 2; ++k) dst[n][k] = *(const PG8_LAS bf16x8*)(lds + PG8_SB(b, h) + boff + n * 2048 + k * 1024); } while (0)
; #define PG8_MMA(ai, bj, At, Bt) do { __builtin_amdgcn_s_setprio(1); _Pragma("unroll") for (int m = 0; m < 4; ++m) _Pragma("unroll") for (int n = 0; n < 2; ++n) _Pragma("unroll") for (int k = 0; k < 2; ++k) \
;         acc[ai][bj][m][n] = __builtin_amdgcn_mfma_f32_16x16x32_bf16(Bt[n][k], At[m][k], acc[ai][bj][m][n], 0, 0, 0); __builtin_amdgcn_s_setprio(0); } while (0)
; #define PG8_WAIT_V(n) asm volatile("s_waitcnt vmcnt(" #n ")" ::: "memory")
; #define PG8_WAIT_L(n) asm volatile("s_waitcnt lgkmcnt(" #n ")" ::: "memory")
; template <class Epi, class Sched, bool ALIGN_EPI = false, bool SP2 = false>
; __device__ __forceinline__ void gemm_phase(PG8_LAS unsigned char* lds, const Gemm g, const Sched& S, const Epi& E) {
;     ...
;             const bool last = (t == nt - 2);
;             const char* a1 = cA + (size_t)(t + 1) * kstep;
;             const char* a2 = last ? nA : cA + (size_t)(t + 2) * kstep; const char* b2 = last ? nB : cB + (size_t)(t + 2) * kstep;
;             const char* a3 = a2 + kstep; const char* b3 = b2 + kstep;
;             if (last && has_next) S.a_ready(nxt);
;             if constexpr (SP2) {
;             PG8_LDB(B0, 0, 0); PG8_LDB(B1, 0, 1); PG8_SCHED; PG8_LDA(At, 0, 0); PG8_STAGE(PG8_SA(1, 1), a1 + hstep, voffA);
;             PG8_WAIT_V(8); PG8_WAIT_L(0); PG8_BAR; PG8_MMA(0, 0, At, B0); PG8_MMA(0, 1, At, B1); PG8_BAR; PG8_SCHED;
;             PG8_LDA(At, 0, 1); PG8_STAGE(PG8_SB(0, 0), b2, voffB); PG8_STAGE(PG8_SB(0, 1), b2 + hstep, voffB); PG8_STAGE(PG8_SA(0, 0), a2, voffA);
;             PG8_WAIT_V(8); PG8_WAIT_L(0); PG8_BAR; PG8_MMA(1, 0, At, B0); PG8_MMA(1, 1, At, B1); PG8_BAR; PG8_SCHED;
.LBB0_118:
	s_add_u32 s48, s46, 0xfffc0080
	s_addc_u32 s49, s47, -1
	s_add_i32 s61, 0, 0x10000
	s_cmp_eq_u32 vcc_lo, 12
	s_cselect_b32 s51, s5, s49
	s_cselect_b32 s50, s7, s48
	v_add_u32_e32 v150, s61, v145
	s_cselect_b32 s49, s8, s91
	s_cselect_b32 s48, s45, s89
	s_add_i32 s72, 0, 0x14000
	ds_read_b128 v[174:177], v150
	ds_read_b128 v[178:181], v150 offset:1024
	ds_read_b128 v[182:185], v150 offset:2048
	ds_read_b128 v[196:199], v150 offset:3072
	v_add_u32_e32 v150, s72, v145
	ds_read_b128 v[200:203], v150
	ds_read_b128 v[204:207], v150 offset:1024
	ds_read_b128 v[208:211], v150 offset:2048
	ds_read_b128 v[212:215], v150 offset:3072
	s_add_i32 m0, s39, 0xc000
	ds_read_b128 v[216:219], v149
	ds_read_b128 v[220:223], v149 offset:1024
	ds_read_b128 v[224:227], v149 offset:2048
	ds_read_b128 v[228:231], v149 offset:3072
	ds_read_b128 v[232:235], v149 offset:4096
	ds_read_b128 v[236:239], v149 offset:5120
	ds_read_b128 v[240:243], v149 offset:6144
	ds_read_b128 v[244:247], v149 offset:7168
	global_load_lds_dwordx4 v142, s[46:47]
	s_add_i32 m0, s39, 0xe000
	s_nop 0
	global_load_lds_dwordx4 v140, s[46:47]
	s_waitcnt vmcnt(8)
	s_waitcnt lgkmcnt(0)
	s_barrier
	v_mfma_f32_16x16x32_bf16 v[126:129], v[174:177], v[216:219], v[126:129]
	v_mfma_f32_16x16x32_bf16 v[122:125], v[182:185], v[216:219], v[122:125]
	v_mfma_f32_16x16x32_bf16 v[110:113], v[174:177], v[224:227], v[110:113]
	v_mfma_f32_16x16x32_bf16 v[106:109], v[182:185], v[224:227], v[106:109]
	v_mfma_f32_16x16x32_bf16 v[94:97], v[174:177], v[232:235], v[94:97]
	v_mfma_f32_16x16x32_bf16 v[90:93], v[182:185], v[232:235], v[90:93]
	v_mfma_f32_16x16x32_bf16 v[78:81], v[174:177], v[240:243], v[78:81]
	v_mfma_f32_16x16x32_bf16 v[74:77], v[182:185], v[240:243], v[74:77]
	v_mfma_f32_16x16x32_bf16 v[126:129], v[178:181], v[220:223], v[126:129]
	v_mfma_f32_16x16x32_bf16 v[122:125], v[196:199], v[220:223], v[122:125]
	v_mfma_f32_16x16x32_bf16 v[110:113], v[178:181], v[228:231], v[110:113]
	v_mfma_f32_16x16x32_bf16 v[106:109], v[196:199], v[228:231], v[106:109]
	v_mfma_f32_16x16x32_bf16 v[94:97], v[178:181], v[236:239], v[94:97]
	v_mfma_f32_16x16x32_bf16 v[90:93], v[196:199], v[236:239], v[90:93]
	v_mfma_f32_16x16x32_bf16 v[78:81], v[178:181], v[244:247], v[78:81]
	v_mfma_f32_16x16x32_bf16 v[74:77], v[196:199], v[244:247], v[74:77]
	v_mfma_f32_16x16x32_bf16 v[118:121], v[200:203], v[216:219], v[118:121]
	v_mfma_f32_16x16x32_bf16 v[114:117], v[208:211], v[216:219], v[114:117]
	v_mfma_f32_16x16x32_bf16 v[102:105], v[200:203], v[224:227], v[102:105]
	v_mfma_f32_16x16x32_bf16 v[98:101], v[208:211], v[224:227], v[98:101]
	v_mfma_f32_16x16x32_bf16 v[86:89], v[200:203], v[232:235], v[86:89]
	v_mfma_f32_16x16x32_bf16 v[82:85], v[208:211], v[232:235], v[82:85]
	v_mfma_f32_16x16x32_bf16 v[70:73], v[200:203], v[240:243], v[70:73]
	v_mfma_f32_16x16x32_bf16 v[66:69], v[208:211], v[240:243], v[66:69]
	v_mfma_f32_16x16x32_bf16 v[118:121], v[204:207], v[220:223], v[118:121]
	v_mfma_f32_16x16x32_bf16 v[114:117], v[212:215], v[220:223], v[114:117]
	v_mfma_f32_16x16x32_bf16 v[102:105], v[204:207], v[228:231], v[102:105]
	v_mfma_f32_16x16x32_bf16 v[98:101], v[212:215], v[228:231], v[98:101]
	v_mfma_f32_16x16x32_bf16 v[86:89], v[204:207], v[236:239], v[86:89]
	v_mfma_f32_16x16x32_bf16 v[82:85], v[212:215], v[236:239], v[82:85]
	v_mfma_f32_16x16x32_bf16 v[70:73], v[204:207], v[244:247], v[70:73]
	v_mfma_f32_16x16x32_bf16 v[66:69], v[212:215], v[244:247], v[66:69]
	s_barrier
	s_add_i32 s61, s61, s38
	v_lshl_add_u64 v[150:151], s[48:49], 0, v[132:133]
	s_mov_b32 m0, s61
	ds_read_b128 v[216:219], v149 offset:16384
	ds_read_b128 v[220:223], v149 offset:17408
	ds_read_b128 v[224:227], v149 offset:18432
	ds_read_b128 v[228:231], v149 offset:19456
	ds_read_b128 v[232:235], v149 offset:20480
	ds_read_b128 v[236:239], v149 offset:21504
	ds_read_b128 v[240:243], v149 offset:22528
	ds_read_b128 v[244:247], v149 offset:23552
	global_load_lds_dwordx4 v[150:151], off
	s_add_i32 m0, s61, 0x2000
	s_add_u32 s80, s48, 0x40000
	v_lshl_add_u64 v[160:161], s[48:49], 0, v[136:137]
	s_addc_u32 s81, s49, 0
	s_add_i32 s61, s72, s38
	global_load_lds_dwordx4 v[160:161], off
	s_mov_b32 m0, s61
	v_lshl_add_u64 v[248:249], s[50:51], 0, v[134:135]
	global_load_lds_dwordx4 v132, s[80:81]
	s_add_i32 m0, s61, 0x2000
	s_nop 0
	global_load_lds_dwordx4 v136, s[80:81]
	v_lshl_add_u64 v[170:171], s[50:51], 0, v[130:131]
	s_mov_b32 m0, s39
	s_nop 0
	global_load_lds_dwordx4 v[170:171], off
	s_mov_b32 m0, s2
	s_nop 0
	global_load_lds_dwordx4 v[248:249], off
	s_waitcnt vmcnt(8)
	s_waitcnt lgkmcnt(0)
	s_barrier
; #define PG8_STAGE(bufoff, gbase, voff) do { _Pragma("unroll") for (int _i = 0; _i < 2; ++_i) \
;         __builtin_amdgcn_global_load_lds((const unsigned*)((const char*)(gbase) + (voff)[_i]), (PG8_LAS unsigned*)(lds + (bufoff) + ldsw + _i * 8192), 16, 0, 0); } while (0)
; #define PG8_LDA(dst, b, h) do { _Pragma("unroll") for (int m = 0; m < 4; ++m) _Pragma("unroll") for (int k = 0; k < 2; ++k) dst[m][k] = *(const PG8_LAS bf16x8*)(lds + PG8_SA(b, h) + aoff + m * 2048 + k * 1024); } while (0)
; #define PG8_LDB(dst, b, h) do { _Pragma("unroll") for (int n = 0; n < 2; ++n) _Pragma("unroll") for (int k = 0; k < 2; ++k) dst[n][k] = *(const PG8_LAS bf16x8*)(lds + PG8_SB(b, h) + boff + n * 2048 + k * 1024); } while (0)
; #define PG8_MMA(ai, bj, At, Bt) do { __builtin_amdgcn_s_setprio(1); _Pragma("unroll") for (int m = 0; m < 4; ++m) _Pragma("unroll") for (int n = 0; n < 2; ++n) _Pragma("unroll") for (int k = 0; k < 2; ++k) \
;         acc[ai][bj][m][n] = __builtin_amdgcn_mfma_f32_16x16x32_bf16(Bt[n][k], At[m][k], acc[ai][bj][m][n], 0, 0, 0); __builtin_amdgcn_s_setprio(0); } while (0)
; #define PG8_WAIT_V(n) asm volatile("s_waitcnt vmcnt(" #n ")" ::: "memory")
; #define PG8_WAIT_L(n) asm volatile("s_waitcnt lgkmcnt(" #n ")" ::: "memory")
; #define PG8_BAR __builtin_amdgcn_s_barrier()
; #define PG8_SCHED __builtin_amdgcn_sched_barrier(0)
; template <class Epi, class Sched, bool ALIGN_EPI = false, bool SP2 = false>
; __device__ __forceinline__ void gemm_phase(PG8_LAS unsigned char* lds, const Gemm g, const Sched& S, const Epi& E) {
;     ...
;             PG8_WAIT_V(8); PG8_WAIT_L(0); PG8_BAR; PG8_MMA(1, 0, At, B0); PG8_MMA(1, 1, At, B1); PG8_BAR; PG8_SCHED;
;             PG8_LDB(B0, 1, 0); PG8_LDB(B1, 1, 1); PG8_SCHED; PG8_LDA(At, 1, 0); PG8_STAGE(PG8_SA(0, 1), a2 + hstep, voffA);
;             PG8_WAIT_V(8); PG8_WAIT_L(0); PG8_BAR; PG8_MMA(0, 0, At, B0); PG8_MMA(0, 1, At, B1); PG8_BAR; PG8_SCHED;
	v_mfma_f32_16x16x32_bf16 v[62:65], v[174:177], v[216:219], v[62:65]
	v_mfma_f32_16x16x32_bf16 v[58:61], v[182:185], v[216:219], v[58:61]
	v_mfma_f32_16x16x32_bf16 v[46:49], v[174:177], v[224:227], v[46:49]
	v_mfma_f32_16x16x32_bf16 v[42:45], v[182:185], v[224:227], v[42:45]
	v_mfma_f32_16x16x32_bf16 v[28:31], v[174:177], v[232:235], v[28:31]
	v_mfma_f32_16x16x32_bf16 v[24:27], v[182:185], v[232:235], v[24:27]
	v_mfma_f32_16x16x32_bf16 v[12:15], v[174:177], v[240:243], v[12:15]
	v_mfma_f32_16x16x32_bf16 v[8:11], v[182:185], v[240:243], v[8:11]
	v_mfma_f32_16x16x32_bf16 v[62:65], v[178:181], v[220:223], v[62:65]
	v_mfma_f32_16x16x32_bf16 v[58:61], v[196:199], v[220:223], v[58:61]
	v_mfma_f32_16x16x32_bf16 v[46:49], v[178:181], v[228:231], v[46:49]
	v_mfma_f32_16x16x32_bf16 v[42:45], v[196:199], v[228:231], v[42:45]
	v_mfma_f32_16x16x32_bf16 v[28:31], v[178:181], v[236:239], v[28:31]
	v_mfma_f32_16x16x32_bf16 v[24:27], v[196:199], v[236:239], v[24:27]
	v_mfma_f32_16x16x32_bf16 v[12:15], v[178:181], v[244:247], v[12:15]
	v_mfma_f32_16x16x32_bf16 v[8:11], v[196:199], v[244:247], v[8:11]
	v_mfma_f32_16x16x32_bf16 v[54:57], v[200:203], v[216:219], v[54:57]
	v_mfma_f32_16x16x32_bf16 v[50:53], v[208:211], v[216:219], v[50:53]
	v_mfma_f32_16x16x32_bf16 v[38:41], v[200:203], v[224:227], v[38:41]
	v_mfma_f32_16x16x32_bf16 v[34:37], v[208:211], v[224:227], v[34:37]
	v_mfma_f32_16x16x32_bf16 v[20:23], v[200:203], v[232:235], v[20:23]
	v_mfma_f32_16x16x32_bf16 v[16:19], v[208:211], v[232:235], v[16:19]
	v_mfma_f32_16x16x32_bf16 v[4:7], v[200:203], v[240:243], v[4:7]
	v_mfma_f32_16x16x32_bf16 v[0:3], v[208:211], v[240:243], v[0:3]
	v_mfma_f32_16x16x32_bf16 v[54:57], v[204:207], v[220:223], v[54:57]
	v_mfma_f32_16x16x32_bf16 v[50:53], v[212:215], v[220:223], v[50:53]
	v_mfma_f32_16x16x32_bf16 v[38:41], v[204:207], v[228:231], v[38:41]
	v_mfma_f32_16x16x32_bf16 v[34:37], v[212:215], v[228:231], v[34:37]
	v_mfma_f32_16x16x32_bf16 v[20:23], v[204:207], v[236:239], v[20:23]
	v_mfma_f32_16x16x32_bf16 v[16:19], v[212:215], v[236:239], v[16:19]
	v_mfma_f32_16x16x32_bf16 v[4:7], v[204:207], v[244:247], v[4:7]
	v_mfma_f32_16x16x32_bf16 v[0:3], v[212:215], v[244:247], v[0:3]
	s_barrier
	s_add_i32 s61, 0, 0x18000
	v_add_u32_e32 v153, s61, v145
	s_add_i32 s72, 0, 0x1c000
	ds_read_b128 v[174:177], v153
	ds_read_b128 v[178:181], v153 offset:1024
	ds_read_b128 v[182:185], v153 offset:2048
	ds_read_b128 v[196:199], v153 offset:3072
	v_add_u32_e32 v153, s72, v145
	ds_read_b128 v[200:203], v153
	ds_read_b128 v[204:207], v153 offset:1024
	ds_read_b128 v[208:211], v153 offset:2048
	ds_read_b128 v[212:215], v153 offset:3072
	s_add_u32 s50, s50, 0x40000
	s_addc_u32 s51, s51, 0
	s_mov_b32 m0, s3
	ds_read_b128 v[216:219], v149 offset:32768
	ds_read_b128 v[220:223], v149 offset:33792
	ds_read_b128 v[224:227], v149 offset:34816
	ds_read_b128 v[228:231], v149 offset:35840
	ds_read_b128 v[232:235], v149 offset:36864
	ds_read_b128 v[236:239], v149 offset:37888
	ds_read_b128 v[240:243], v149 offset:38912
	ds_read_b128 v[244:247], v149 offset:39936
	global_load_lds_dwordx4 v130, s[50:51]
	s_mov_b32 m0, s87
	s_nop 0
	global_load_lds_dwordx4 v134, s[50:51]
	s_waitcnt vmcnt(8)
	s_waitcnt lgkmcnt(0)
	s_barrier
	v_mfma_f32_16x16x32_bf16 v[126:129], v[174:177], v[216:219], v[126:129]
	v_mfma_f32_16x16x32_bf16 v[122:125], v[182:185], v[216:219], v[122:125]
	v_mfma_f32_16x16x32_bf16 v[110:113], v[174:177], v[224:227], v[110:113]
	v_mfma_f32_16x16x32_bf16 v[106:109], v[182:185], v[224:227], v[106:109]
	v_mfma_f32_16x16x32_bf16 v[94:97], v[174:177], v[232:235], v[94:97]
	v_mfma_f32_16x16x32_bf16 v[90:93], v[182:185], v[232:235], v[90:93]
	v_mfma_f32_16x16x32_bf16 v[78:81], v[174:177], v[240:243], v[78:81]
	v_mfma_f32_16x16x32_bf16 v[74:77], v[182:185], v[240:243], v[74:77]
	v_mfma_f32_16x16x32_bf16 v[126:129], v[178:181], v[220:223], v[126:129]
	v_mfma_f32_16x16x32_bf16 v[122:125], v[196:199], v[220:223], v[122:125]
	v_mfma_f32_16x16x32_bf16 v[110:113], v[178:181], v[228:231], v[110:113]
	v_mfma_f32_16x16x32_bf16 v[106:109], v[196:199], v[228:231], v[106:109]
	v_mfma_f32_16x16x32_bf16 v[94:97], v[178:181], v[236:239], v[94:97]
	v_mfma_f32_16x16x32_bf16 v[90:93], v[196:199], v[236:239], v[90:93]
	v_mfma_f32_16x16x32_bf16 v[78:81], v[178:181], v[244:247], v[78:81]
	v_mfma_f32_16x16x32_bf16 v[74:77], v[196:199], v[244:247], v[74:77]
	v_mfma_f32_16x16x32_bf16 v[118:121], v[200:203], v[216:219], v[118:121]
	v_mfma_f32_16x16x32_bf16 v[114:117], v[208:211], v[216:219], v[114:117]
	v_mfma_f32_16x16x32_bf16 v[102:105], v[200:203], v[224:227], v[102:105]
	v_mfma_f32_16x16x32_bf16 v[98:101], v[208:211], v[224:227], v[98:101]
	v_mfma_f32_16x16x32_bf16 v[86:89], v[200:203], v[232:235], v[86:89]
	v_mfma_f32_16x16x32_bf16 v[82:85], v[208:211], v[232:235], v[82:85]
	v_mfma_f32_16x16x32_bf16 v[70:73], v[200:203], v[240:243], v[70:73]
	v_mfma_f32_16x16x32_bf16 v[66:69], v[208:211], v[240:243], v[66:69]
	v_mfma_f32_16x16x32_bf16 v[118:121], v[204:207], v[220:223], v[118:121]
	v_mfma_f32_16x16x32_bf16 v[114:117], v[212:215], v[220:223], v[114:117]
	v_mfma_f32_16x16x32_bf16 v[102:105], v[204:207], v[228:231], v[102:105]
	v_mfma_f32_16x16x32_bf16 v[98:101], v[212:215], v[228:231], v[98:101]
	v_mfma_f32_16x16x32_bf16 v[86:89], v[204:207], v[236:239], v[86:89]
	v_mfma_f32_16x16x32_bf16 v[82:85], v[212:215], v[236:239], v[82:85]
	v_mfma_f32_16x16x32_bf16 v[70:73], v[204:207], v[244:247], v[70:73]
	v_mfma_f32_16x16x32_bf16 v[66:69], v[212:215], v[244:247], v[66:69]
	s_barrier
; #define PG8_STAGE(bufoff, gbase, voff) do { _Pragma("unroll") for (int _i = 0; _i < 2; ++_i) \
;         __builtin_amdgcn_global_load_lds((const unsigned*)((const char*)(gbase) + (voff)[_i]), (PG8_LAS unsigned*)(lds + (bufoff) + ldsw + _i * 8192), 16, 0, 0); } while (0)
; #define PG8_LDA(dst, b, h) do { _Pragma("unroll") for (int m = 0; m < 4; ++m) _Pragma("unroll") for (int k = 0; k < 2; ++k) dst[m][k] = *(const PG8_LAS bf16x8*)(lds + PG8_SA(b, h) + aoff + m * 2048 + k * 1024); } while (0)
; #define PG8_MMA(ai, bj, At, Bt) do { __builtin_amdgcn_s_setprio(1); _Pragma("unroll") for (int m = 0; m < 4; ++m) _Pragma("unroll") for (int n = 0; n < 2; ++n) _Pragma("unroll") for (int k = 0; k < 2; ++k) \
;         acc[ai][bj][m][n] = __builtin_amdgcn_mfma_f32_16x16x32_bf16(Bt[n][k], At[m][k], acc[ai][bj][m][n], 0, 0, 0); __builtin_amdgcn_s_setprio(0); } while (0)
; #define PG8_WAIT_V(n) asm volatile("s_waitcnt vmcnt(" #n ")" ::: "memory")
; #define PG8_WAIT_L(n) asm volatile("s_waitcnt lgkmcnt(" #n ")" ::: "memory")
; #define PG8_BAR __builtin_amdgcn_s_barrier()
; #define PG8_SCHED __builtin_amdgcn_sched_barrier(0)
; template <class Epi, class Sched, bool ALIGN_EPI = false, bool SP2 = false>
; __device__ __forceinline__ void gemm_phase(PG8_LAS unsigned char* lds, const Gemm g, const Sched& S, const Epi& E) {
;     ...
;             PG8_LDA(At, 1, 1); PG8_STAGE(PG8_SB(1, 0), b3, voffB); PG8_STAGE(PG8_SB(1, 1), b3 + hstep, voffB); PG8_STAGE(PG8_SA(1, 0), a3, voffA);
;             PG8_WAIT_V(8); PG8_WAIT_L(0); PG8_BAR; PG8_MMA(1, 0, At, B0); PG8_MMA(1, 1, At, B1); PG8_BAR; PG8_SCHED;
;     ...
;         if constexpr (ALIGN_EPI) { if (wr == 0) PG8_BAR; }
	s_add_i32 s50, s61, s38
	v_lshl_add_u64 v[150:151], v[150:151], 0, s[34:35]
	s_mov_b32 m0, s50
	ds_read_b128 v[216:219], v149 offset:49152
	ds_read_b128 v[220:223], v149 offset:50176
	ds_read_b128 v[224:227], v149 offset:51200
	ds_read_b128 v[228:231], v149 offset:52224
	ds_read_b128 v[232:235], v149 offset:53248
	ds_read_b128 v[236:239], v149 offset:54272
	ds_read_b128 v[240:243], v149 offset:55296
	ds_read_b128 v[244:247], v149 offset:56320
	global_load_lds_dwordx4 v[150:151], off
	s_add_i32 m0, s50, 0x2000
	s_add_u32 s48, s48, 0x40080
	v_lshl_add_u64 v[150:151], v[160:161], 0, s[34:35]
	s_addc_u32 s49, s49, 0
	s_add_i32 s50, s72, s38
	global_load_lds_dwordx4 v[150:151], off
	s_mov_b32 m0, s50
	s_nop 0
	global_load_lds_dwordx4 v132, s[48:49]
	s_add_i32 m0, s50, 0x2000
	s_nop 0
	global_load_lds_dwordx4 v136, s[48:49]
	v_lshl_add_u64 v[150:151], v[170:171], 0, s[34:35]
	s_mov_b32 m0, s0
	s_nop 0
	global_load_lds_dwordx4 v[150:151], off
	v_lshl_add_u64 v[150:151], v[248:249], 0, s[34:35]
	s_mov_b32 m0, s86
	s_nop 0
	global_load_lds_dwordx4 v[150:151], off
	s_waitcnt vmcnt(8)
	s_waitcnt lgkmcnt(0)
	s_barrier
	v_mfma_f32_16x16x32_bf16 v[62:65], v[174:177], v[216:219], v[62:65]
	v_mfma_f32_16x16x32_bf16 v[58:61], v[182:185], v[216:219], v[58:61]
	v_mfma_f32_16x16x32_bf16 v[46:49], v[174:177], v[224:227], v[46:49]
	v_mfma_f32_16x16x32_bf16 v[42:45], v[182:185], v[224:227], v[42:45]
	v_mfma_f32_16x16x32_bf16 v[28:31], v[174:177], v[232:235], v[28:31]
	v_mfma_f32_16x16x32_bf16 v[24:27], v[182:185], v[232:235], v[24:27]
	v_mfma_f32_16x16x32_bf16 v[12:15], v[174:177], v[240:243], v[12:15]
	v_mfma_f32_16x16x32_bf16 v[8:11], v[182:185], v[240:243], v[8:11]
	v_mfma_f32_16x16x32_bf16 v[62:65], v[178:181], v[220:223], v[62:65]
	v_mfma_f32_16x16x32_bf16 v[58:61], v[196:199], v[220:223], v[58:61]
	v_mfma_f32_16x16x32_bf16 v[46:49], v[178:181], v[228:231], v[46:49]
	v_mfma_f32_16x16x32_bf16 v[42:45], v[196:199], v[228:231], v[42:45]
	v_mfma_f32_16x16x32_bf16 v[28:31], v[178:181], v[236:239], v[28:31]
	v_mfma_f32_16x16x32_bf16 v[24:27], v[196:199], v[236:239], v[24:27]
	v_mfma_f32_16x16x32_bf16 v[12:15], v[178:181], v[244:247], v[12:15]
	v_mfma_f32_16x16x32_bf16 v[8:11], v[196:199], v[244:247], v[8:11]
	v_mfma_f32_16x16x32_bf16 v[54:57], v[200:203], v[216:219], v[54:57]
	v_mfma_f32_16x16x32_bf16 v[50:53], v[208:211], v[216:219], v[50:53]
	v_mfma_f32_16x16x32_bf16 v[38:41], v[200:203], v[224:227], v[38:41]
	v_mfma_f32_16x16x32_bf16 v[34:37], v[208:211], v[224:227], v[34:37]
	v_mfma_f32_16x16x32_bf16 v[20:23], v[200:203], v[232:235], v[20:23]
	v_mfma_f32_16x16x32_bf16 v[16:19], v[208:211], v[232:235], v[16:19]
	v_mfma_f32_16x16x32_bf16 v[4:7], v[200:203], v[240:243], v[4:7]
	v_mfma_f32_16x16x32_bf16 v[0:3], v[208:211], v[240:243], v[0:3]
	v_mfma_f32_16x16x32_bf16 v[54:57], v[204:207], v[220:223], v[54:57]
	v_mfma_f32_16x16x32_bf16 v[50:53], v[212:215], v[220:223], v[50:53]
	v_mfma_f32_16x16x32_bf16 v[38:41], v[204:207], v[228:231], v[38:41]
	v_mfma_f32_16x16x32_bf16 v[34:37], v[212:215], v[228:231], v[34:37]
	v_mfma_f32_16x16x32_bf16 v[20:23], v[204:207], v[236:239], v[20:23]
	v_mfma_f32_16x16x32_bf16 v[16:19], v[212:215], v[236:239], v[16:19]
	v_mfma_f32_16x16x32_bf16 v[4:7], v[204:207], v[244:247], v[4:7]
	v_mfma_f32_16x16x32_bf16 v[0:3], v[212:215], v[244:247], v[0:3]
	s_barrier
	s_add_i32 vcc_lo, vcc_lo, 2
	s_add_u32 s89, s89, 0x100
	s_addc_u32 s91, s91, 0
	s_add_u32 s46, s46, 0x100
	s_addc_u32 s47, s47, 0
	s_cmp_gt_u32 vcc_lo, 13
	s_cbranch_scc0 .LBB0_118
	v_readlane_b32 s46, v254, 51
	v_readlane_b32 s47, v254, 52
	s_and_b64 vcc, exec, s[46:47]
	s_cbranch_vccz .LBB0_121
	s_barrier

; #define PG8_STAGE(bufoff, gbase, voff) do { _Pragma("unroll") for (int _i = 0; _i < 2; ++_i) \
;         __builtin_amdgcn_global_load_lds((const unsigned*)((const char*)(gbase) + (voff)[_i]), (PG8_LAS unsigned*)(lds + (bufoff) + ldsw + _i * 8192), 16, 0, 0); } while (0)
; #define PG8_LDA(dst, b, h) do { _Pragma("unroll") for (int m = 0; m < 4; ++m) _Pragma("unroll") for (int k = 0; k < 2; ++k) dst[m][k] = *(const PG8_LAS bf16x8*)(lds + PG8_SA(b, h) + aoff + m * 2048 + k * 1024); } while (0)
; #define PG8_LDB(dst, b, h) do { _Pragma("unroll") for (int n = 0; n < 2; ++n) _Pragma("unroll") for (int k = 0; k < 2; ++k) dst[n][k] = *(const PG8_LAS bf16x8*)(lds + PG8_SB(b, h) + boff + n * 2048 + k * 1024); } while (0)
; #define PG8_MMA(ai, bj, At, Bt) do { __builtin_amdgcn_s_setprio(1); _Pragma("unroll") for (int m = 0; m < 4; ++m) _Pragma("unroll") for (int n = 0; n < 2; ++n) _Pragma("unroll") for (int k = 0; k < 2; ++k) \
;         acc[ai][bj][m][n] = __builtin_amdgcn_mfma_f32_16x16x32_bf16(Bt[n][k], At[m][k], acc[ai][bj][m][n], 0, 0, 0); __builtin_amdgcn_s_setprio(0); } while (0)
; #define PG8_WAIT_V(n) asm volatile("s_waitcnt vmcnt(" #n ")" ::: "memory")
; #define PG8_WAIT_L(n) asm volatile("s_waitcnt lgkmcnt(" #n ")" ::: "memory")
; template <class Epi, class Sched, bool ALIGN_EPI = false, bool SP2 = false>
; __device__ __forceinline__ void gemm_phase(PG8_LAS unsigned char* lds, const Gemm g, const Sched& S, const Epi& E) {
;     ...
;             const bool last = (t == nt - 2);
;             const char* a1 = cA + (size_t)(t + 1) * kstep;
;             const char* a2 = last ? nA : cA + (size_t)(t + 2) * kstep; const char* b2 = last ? nB : cB + (size_t)(t + 2) * kstep;
;             const char* a3 = a2 + kstep; const char* b3 = b2 + kstep;
;             if (last && has_next) S.a_ready(nxt);
;             if constexpr (SP2) {
;             PG8_LDB(B0, 0, 0); PG8_LDB(B1, 0, 1); PG8_SCHED; PG8_LDA(At, 0, 0); PG8_STAGE(PG8_SA(1, 1), a1 + hstep, voffA);
;             PG8_WAIT_V(8); PG8_WAIT_L(0); PG8_BAR; PG8_MMA(0, 0, At, B0); PG8_MMA(0, 1, At, B1); PG8_BAR; PG8_SCHED;
;             PG8_LDA(At, 0, 1); PG8_STAGE(PG8_SB(0, 0), b2, voffB); PG8_STAGE(PG8_SB(0, 1), b2 + hstep, voffB); PG8_STAGE(PG8_SA(0, 0), a2, voffA);
;             PG8_WAIT_V(8); PG8_WAIT_L(0); PG8_BAR; PG8_MMA(1, 0, At, B0); PG8_MMA(1, 1, At, B1); PG8_BAR; PG8_SCHED;
.LBB0_145:
	s_add_u32 s48, s46, 0xfffc0080
	s_addc_u32 s49, s47, -1
	s_add_i32 s61, 0, 0x10000
	s_cmp_eq_u32 s80, 12
	s_cselect_b32 s51, s3, s49
	s_cselect_b32 s50, s45, s48
	s_cselect_b32 s49, s89, s7
	s_cselect_b32 s48, vcc_lo, vcc_hi
	s_add_i32 s72, 0, 0x14000
	v_add_u32_e32 v70, s61, v176
	v_add_u32_e32 v174, s72, v176
	ds_read_b128 v[50:53], v70
	ds_read_b128 v[54:57], v70 offset:1024
	ds_read_b128 v[66:69], v70 offset:2048
	ds_read_b128 v[70:73], v70 offset:3072
	ds_read_b128 v[158:161], v174
	ds_read_b128 v[170:173], v174 offset:1024
	ds_read_b128 v[180:183], v174 offset:2048
	ds_read_b128 v[196:199], v174 offset:3072
	s_add_i32 m0, s5, 0xc000
	ds_read_b128 v[200:203], v178
	ds_read_b128 v[204:207], v178 offset:1024
	ds_read_b128 v[208:211], v178 offset:2048
	ds_read_b128 v[212:215], v178 offset:3072
	ds_read_b128 v[216:219], v178 offset:4096
	ds_read_b128 v[220:223], v178 offset:5120
	ds_read_b128 v[224:227], v178 offset:6144
	ds_read_b128 v[228:231], v178 offset:7168
	global_load_lds_dwordx4 v156, s[46:47]
	s_add_i32 m0, s5, 0xe000
	s_nop 0
	global_load_lds_dwordx4 v154, s[46:47]
	s_waitcnt vmcnt(8)
	s_waitcnt lgkmcnt(0)
	s_barrier
	v_mfma_f32_16x16x32_bf16 v[142:145], v[50:53], v[200:203], v[142:145]
	v_mfma_f32_16x16x32_bf16 v[138:141], v[66:69], v[200:203], v[138:141]
	v_mfma_f32_16x16x32_bf16 v[126:129], v[50:53], v[208:211], v[126:129]
	v_mfma_f32_16x16x32_bf16 v[122:125], v[66:69], v[208:211], v[122:125]
	v_mfma_f32_16x16x32_bf16 v[110:113], v[50:53], v[216:219], v[110:113]
	v_mfma_f32_16x16x32_bf16 v[106:109], v[66:69], v[216:219], v[106:109]
	v_mfma_f32_16x16x32_bf16 v[94:97], v[50:53], v[224:227], v[94:97]
	v_mfma_f32_16x16x32_bf16 v[90:93], v[66:69], v[224:227], v[90:93]
	v_mfma_f32_16x16x32_bf16 v[142:145], v[54:57], v[204:207], v[142:145]
	v_mfma_f32_16x16x32_bf16 v[138:141], v[70:73], v[204:207], v[138:141]
	v_mfma_f32_16x16x32_bf16 v[126:129], v[54:57], v[212:215], v[126:129]
	v_mfma_f32_16x16x32_bf16 v[122:125], v[70:73], v[212:215], v[122:125]
	v_mfma_f32_16x16x32_bf16 v[110:113], v[54:57], v[220:223], v[110:113]
	v_mfma_f32_16x16x32_bf16 v[106:109], v[70:73], v[220:223], v[106:109]
	v_mfma_f32_16x16x32_bf16 v[94:97], v[54:57], v[228:231], v[94:97]
	v_mfma_f32_16x16x32_bf16 v[90:93], v[70:73], v[228:231], v[90:93]
	v_mfma_f32_16x16x32_bf16 v[134:137], v[158:161], v[200:203], v[134:137]
	v_mfma_f32_16x16x32_bf16 v[130:133], v[180:183], v[200:203], v[130:133]
	v_mfma_f32_16x16x32_bf16 v[118:121], v[158:161], v[208:211], v[118:121]
	v_mfma_f32_16x16x32_bf16 v[114:117], v[180:183], v[208:211], v[114:117]
	v_mfma_f32_16x16x32_bf16 v[102:105], v[158:161], v[216:219], v[102:105]
	v_mfma_f32_16x16x32_bf16 v[98:101], v[180:183], v[216:219], v[98:101]
	v_mfma_f32_16x16x32_bf16 v[86:89], v[158:161], v[224:227], v[86:89]
	v_mfma_f32_16x16x32_bf16 v[82:85], v[180:183], v[224:227], v[82:85]
	v_mfma_f32_16x16x32_bf16 v[134:137], v[170:173], v[204:207], v[134:137]
	v_mfma_f32_16x16x32_bf16 v[130:133], v[196:199], v[204:207], v[130:133]
	v_mfma_f32_16x16x32_bf16 v[118:121], v[170:173], v[212:215], v[118:121]
	v_mfma_f32_16x16x32_bf16 v[114:117], v[196:199], v[212:215], v[114:117]
	v_mfma_f32_16x16x32_bf16 v[102:105], v[170:173], v[220:223], v[102:105]
	v_mfma_f32_16x16x32_bf16 v[98:101], v[196:199], v[220:223], v[98:101]
	v_mfma_f32_16x16x32_bf16 v[86:89], v[170:173], v[228:231], v[86:89]
	v_mfma_f32_16x16x32_bf16 v[82:85], v[196:199], v[228:231], v[82:85]
	s_barrier
	s_add_i32 s61, s61, s4
	v_lshl_add_u64 v[174:175], s[48:49], 0, v[148:149]
	s_mov_b32 m0, s61
	ds_read_b128 v[200:203], v178 offset:16384
	ds_read_b128 v[204:207], v178 offset:17408
	ds_read_b128 v[208:211], v178 offset:18432
	ds_read_b128 v[212:215], v178 offset:19456
	ds_read_b128 v[216:219], v178 offset:20480
	ds_read_b128 v[220:223], v178 offset:21504
	ds_read_b128 v[224:227], v178 offset:22528
	ds_read_b128 v[228:231], v178 offset:23552
	global_load_lds_dwordx4 v[174:175], off
	s_add_i32 m0, s61, 0x2000
	s_add_u32 s76, s48, 0x40000
	v_lshl_add_u64 v[184:185], s[48:49], 0, v[152:153]
	s_addc_u32 s77, s49, 0
	s_add_i32 s61, s72, s4
	global_load_lds_dwordx4 v[184:185], off
	s_mov_b32 m0, s61
	v_lshl_add_u64 v[234:235], s[50:51], 0, v[150:151]
	global_load_lds_dwordx4 v148, s[76:77]
	s_add_i32 m0, s61, 0x2000
	s_nop 0
	global_load_lds_dwordx4 v152, s[76:77]
	v_lshl_add_u64 v[232:233], s[50:51], 0, v[146:147]
	s_mov_b32 m0, s5
	s_nop 0
	global_load_lds_dwordx4 v[232:233], off
	s_mov_b32 m0, s91
	s_nop 0
	global_load_lds_dwordx4 v[234:235], off
	s_waitcnt vmcnt(8)
	s_waitcnt lgkmcnt(0)
	s_barrier
	v_mfma_f32_16x16x32_bf16 v[78:81], v[50:53], v[200:203], v[78:81]
	v_mfma_f32_16x16x32_bf16 v[74:77], v[66:69], v[200:203], v[74:77]
	v_mfma_f32_16x16x32_bf16 v[46:49], v[50:53], v[208:211], v[46:49]
	v_mfma_f32_16x16x32_bf16 v[42:45], v[66:69], v[208:211], v[42:45]
	v_mfma_f32_16x16x32_bf16 v[28:31], v[50:53], v[216:219], v[28:31]
	v_mfma_f32_16x16x32_bf16 v[24:27], v[66:69], v[216:219], v[24:27]
	v_mfma_f32_16x16x32_bf16 v[12:15], v[50:53], v[224:227], v[12:15]
	v_mfma_f32_16x16x32_bf16 v[8:11], v[66:69], v[224:227], v[8:11]
	v_mfma_f32_16x16x32_bf16 v[78:81], v[54:57], v[204:207], v[78:81]
	v_mfma_f32_16x16x32_bf16 v[74:77], v[70:73], v[204:207], v[74:77]
	v_mfma_f32_16x16x32_bf16 v[46:49], v[54:57], v[212:215], v[46:49]
	v_mfma_f32_16x16x32_bf16 v[42:45], v[70:73], v[212:215], v[42:45]
	v_mfma_f32_16x16x32_bf16 v[28:31], v[54:57], v[220:223], v[28:31]
	v_mfma_f32_16x16x32_bf16 v[24:27], v[70:73], v[220:223], v[24:27]
	v_mfma_f32_16x16x32_bf16 v[12:15], v[54:57], v[228:231], v[12:15]
	v_mfma_f32_16x16x32_bf16 v[8:11], v[70:73], v[228:231], v[8:11]
	v_mfma_f32_16x16x32_bf16 v[38:41], v[158:161], v[208:211], v[38:41]
	v_mfma_f32_16x16x32_bf16 v[34:37], v[180:183], v[208:211], v[34:37]
	v_mfma_f32_16x16x32_bf16 v[20:23], v[158:161], v[216:219], v[20:23]
	v_mfma_f32_16x16x32_bf16 v[16:19], v[180:183], v[216:219], v[16:19]
	v_mfma_f32_16x16x32_bf16 v[4:7], v[158:161], v[224:227], v[4:7]
	v_mfma_f32_16x16x32_bf16 v[0:3], v[180:183], v[224:227], v[0:3]
	v_mfma_f32_16x16x32_bf16 v[50:53], v[158:161], v[200:203], v[62:65]
	v_mfma_f32_16x16x32_bf16 v[54:57], v[180:183], v[200:203], v[58:61]
	v_mfma_f32_16x16x32_bf16 v[38:41], v[170:173], v[212:215], v[38:41]
	v_mfma_f32_16x16x32_bf16 v[34:37], v[196:199], v[212:215], v[34:37]
	v_mfma_f32_16x16x32_bf16 v[20:23], v[170:173], v[220:223], v[20:23]
	v_mfma_f32_16x16x32_bf16 v[16:19], v[196:199], v[220:223], v[16:19]
	v_mfma_f32_16x16x32_bf16 v[4:7], v[170:173], v[228:231], v[4:7]
	v_mfma_f32_16x16x32_bf16 v[0:3], v[196:199], v[228:231], v[0:3]
	v_mfma_f32_16x16x32_bf16 v[50:53], v[170:173], v[204:207], v[50:53]
	v_mfma_f32_16x16x32_bf16 v[54:57], v[196:199], v[204:207], v[54:57]
	s_barrier
; #define PG8_STAGE(bufoff, gbase, voff) do { _Pragma("unroll") for (int _i = 0; _i < 2; ++_i) \
;         __builtin_amdgcn_global_load_lds((const unsigned*)((const char*)(gbase) + (voff)[_i]), (PG8_LAS unsigned*)(lds + (bufoff) + ldsw + _i * 8192), 16, 0, 0); } while (0)
; #define PG8_LDA(dst, b, h) do { _Pragma("unroll") for (int m = 0; m < 4; ++m) _Pragma("unroll") for (int k = 0; k < 2; ++k) dst[m][k] = *(const PG8_LAS bf16x8*)(lds + PG8_SA(b, h) + aoff + m * 2048 + k * 1024); } while (0)
; #define PG8_LDB(dst, b, h) do { _Pragma("unroll") for (int n = 0; n < 2; ++n) _Pragma("unroll") for (int k = 0; k < 2; ++k) dst[n][k] = *(const PG8_LAS bf16x8*)(lds + PG8_SB(b, h) + boff + n * 2048 + k * 1024); } while (0)
; #define PG8_MMA(ai, bj, At, Bt) do { __builtin_amdgcn_s_setprio(1); _Pragma("unroll") for (int m = 0; m < 4; ++m) _Pragma("unroll") for (int n = 0; n < 2; ++n) _Pragma("unroll") for (int k = 0; k < 2; ++k) \
;         acc[ai][bj][m][n] = __builtin_amdgcn_mfma_f32_16x16x32_bf16(Bt[n][k], At[m][k], acc[ai][bj][m][n], 0, 0, 0); __builtin_amdgcn_s_setprio(0); } while (0)
; #define PG8_WAIT_V(n) asm volatile("s_waitcnt vmcnt(" #n ")" ::: "memory")
; #define PG8_WAIT_L(n) asm volatile("s_waitcnt lgkmcnt(" #n ")" ::: "memory")
; #define PG8_BAR __builtin_amdgcn_s_barrier()
; #define PG8_SCHED __builtin_amdgcn_sched_barrier(0)
; template <class Epi, class Sched, bool ALIGN_EPI = false, bool SP2 = false>
; __device__ __forceinline__ void gemm_phase(PG8_LAS unsigned char* lds, const Gemm g, const Sched& S, const Epi& E) {
;     ...
;             PG8_LDB(B0, 1, 0); PG8_LDB(B1, 1, 1); PG8_SCHED; PG8_LDA(At, 1, 0); PG8_STAGE(PG8_SA(0, 1), a2 + hstep, voffA);
;             PG8_WAIT_V(8); PG8_WAIT_L(0); PG8_BAR; PG8_MMA(0, 0, At, B0); PG8_MMA(0, 1, At, B1); PG8_BAR; PG8_SCHED;
;             PG8_LDA(At, 1, 1); PG8_STAGE(PG8_SB(1, 0), b3, voffB); PG8_STAGE(PG8_SB(1, 1), b3 + hstep, voffB); PG8_STAGE(PG8_SA(1, 0), a3, voffA);
;             PG8_WAIT_V(8); PG8_WAIT_L(0); PG8_BAR; PG8_MMA(1, 0, At, B0); PG8_MMA(1, 1, At, B1); PG8_BAR; PG8_SCHED;
;     ...
;         if constexpr (ALIGN_EPI) { if (wr == 0) PG8_BAR; }
	s_add_i32 s61, 0, 0x18000
	s_add_i32 s72, 0, 0x1c000
	v_add_u32_e32 v70, s61, v176
	v_add_u32_e32 v179, s72, v176
	ds_read_b128 v[58:61], v70
	ds_read_b128 v[62:65], v70 offset:1024
	ds_read_b128 v[66:69], v70 offset:2048
	ds_read_b128 v[70:73], v70 offset:3072
	ds_read_b128 v[158:161], v179
	ds_read_b128 v[170:173], v179 offset:1024
	ds_read_b128 v[180:183], v179 offset:2048
	ds_read_b128 v[196:199], v179 offset:3072
	s_add_u32 s50, s50, 0x40000
	s_addc_u32 s51, s51, 0
	s_mov_b32 m0, s8
	ds_read_b128 v[200:203], v178 offset:32768
	ds_read_b128 v[204:207], v178 offset:33792
	ds_read_b128 v[208:211], v178 offset:34816
	ds_read_b128 v[212:215], v178 offset:35840
	ds_read_b128 v[216:219], v178 offset:36864
	ds_read_b128 v[220:223], v178 offset:37888
	ds_read_b128 v[224:227], v178 offset:38912
	ds_read_b128 v[228:231], v178 offset:39936
	global_load_lds_dwordx4 v146, s[50:51]
	s_mov_b32 m0, s0
	s_nop 0
	global_load_lds_dwordx4 v150, s[50:51]
	s_waitcnt vmcnt(8)
	s_waitcnt lgkmcnt(0)
	s_barrier
	v_mfma_f32_16x16x32_bf16 v[142:145], v[58:61], v[200:203], v[142:145]
	v_mfma_f32_16x16x32_bf16 v[138:141], v[66:69], v[200:203], v[138:141]
	v_mfma_f32_16x16x32_bf16 v[126:129], v[58:61], v[208:211], v[126:129]
	v_mfma_f32_16x16x32_bf16 v[122:125], v[66:69], v[208:211], v[122:125]
	v_mfma_f32_16x16x32_bf16 v[110:113], v[58:61], v[216:219], v[110:113]
	v_mfma_f32_16x16x32_bf16 v[106:109], v[66:69], v[216:219], v[106:109]
	v_mfma_f32_16x16x32_bf16 v[94:97], v[58:61], v[224:227], v[94:97]
	v_mfma_f32_16x16x32_bf16 v[90:93], v[66:69], v[224:227], v[90:93]
	v_mfma_f32_16x16x32_bf16 v[142:145], v[62:65], v[204:207], v[142:145]
	v_mfma_f32_16x16x32_bf16 v[138:141], v[70:73], v[204:207], v[138:141]
	v_mfma_f32_16x16x32_bf16 v[126:129], v[62:65], v[212:215], v[126:129]
	v_mfma_f32_16x16x32_bf16 v[122:125], v[70:73], v[212:215], v[122:125]
	v_mfma_f32_16x16x32_bf16 v[110:113], v[62:65], v[220:223], v[110:113]
	v_mfma_f32_16x16x32_bf16 v[106:109], v[70:73], v[220:223], v[106:109]
	v_mfma_f32_16x16x32_bf16 v[94:97], v[62:65], v[228:231], v[94:97]
	v_mfma_f32_16x16x32_bf16 v[90:93], v[70:73], v[228:231], v[90:93]
	v_mfma_f32_16x16x32_bf16 v[134:137], v[158:161], v[200:203], v[134:137]
	v_mfma_f32_16x16x32_bf16 v[130:133], v[180:183], v[200:203], v[130:133]
	v_mfma_f32_16x16x32_bf16 v[118:121], v[158:161], v[208:211], v[118:121]
	v_mfma_f32_16x16x32_bf16 v[114:117], v[180:183], v[208:211], v[114:117]
	v_mfma_f32_16x16x32_bf16 v[102:105], v[158:161], v[216:219], v[102:105]
	v_mfma_f32_16x16x32_bf16 v[98:101], v[180:183], v[216:219], v[98:101]
	v_mfma_f32_16x16x32_bf16 v[86:89], v[158:161], v[224:227], v[86:89]
	v_mfma_f32_16x16x32_bf16 v[82:85], v[180:183], v[224:227], v[82:85]
	v_mfma_f32_16x16x32_bf16 v[134:137], v[170:173], v[204:207], v[134:137]
	v_mfma_f32_16x16x32_bf16 v[130:133], v[196:199], v[204:207], v[130:133]
	v_mfma_f32_16x16x32_bf16 v[118:121], v[170:173], v[212:215], v[118:121]
	v_mfma_f32_16x16x32_bf16 v[114:117], v[196:199], v[212:215], v[114:117]
	v_mfma_f32_16x16x32_bf16 v[102:105], v[170:173], v[220:223], v[102:105]
	v_mfma_f32_16x16x32_bf16 v[98:101], v[196:199], v[220:223], v[98:101]
	v_mfma_f32_16x16x32_bf16 v[86:89], v[170:173], v[228:231], v[86:89]
	v_mfma_f32_16x16x32_bf16 v[82:85], v[196:199], v[228:231], v[82:85]
	s_barrier
	s_add_i32 s50, s61, s4
	v_lshl_add_u64 v[174:175], v[174:175], 0, s[34:35]
	s_mov_b32 m0, s50
	ds_read_b128 v[200:203], v178 offset:49152
	ds_read_b128 v[204:207], v178 offset:50176
	ds_read_b128 v[208:211], v178 offset:51200
	ds_read_b128 v[212:215], v178 offset:52224
	ds_read_b128 v[216:219], v178 offset:53248
	ds_read_b128 v[220:223], v178 offset:54272
	ds_read_b128 v[224:227], v178 offset:55296
	ds_read_b128 v[228:231], v178 offset:56320
	global_load_lds_dwordx4 v[174:175], off
	s_add_i32 m0, s50, 0x2000
	s_add_u32 s48, s48, 0x40080
	v_lshl_add_u64 v[174:175], v[184:185], 0, s[34:35]
	s_addc_u32 s49, s49, 0
	s_add_i32 s50, s72, s4
	global_load_lds_dwordx4 v[174:175], off
	s_mov_b32 m0, s50
	s_nop 0
	global_load_lds_dwordx4 v148, s[48:49]
	s_add_i32 m0, s50, 0x2000
	s_nop 0
	global_load_lds_dwordx4 v152, s[48:49]
	v_lshl_add_u64 v[174:175], v[232:233], 0, s[34:35]
	s_mov_b32 m0, s9
	s_nop 0
	global_load_lds_dwordx4 v[174:175], off
	v_lshl_add_u64 v[174:175], v[234:235], 0, s[34:35]
	s_mov_b32 m0, s86
	s_nop 0
	global_load_lds_dwordx4 v[174:175], off
	s_waitcnt vmcnt(8)
	s_waitcnt lgkmcnt(0)
	s_barrier
	v_mfma_f32_16x16x32_bf16 v[78:81], v[58:61], v[200:203], v[78:81]
	v_mfma_f32_16x16x32_bf16 v[74:77], v[66:69], v[200:203], v[74:77]
	v_mfma_f32_16x16x32_bf16 v[46:49], v[58:61], v[208:211], v[46:49]
	v_mfma_f32_16x16x32_bf16 v[42:45], v[66:69], v[208:211], v[42:45]
	v_mfma_f32_16x16x32_bf16 v[28:31], v[58:61], v[216:219], v[28:31]
	v_mfma_f32_16x16x32_bf16 v[24:27], v[66:69], v[216:219], v[24:27]
	v_mfma_f32_16x16x32_bf16 v[12:15], v[58:61], v[224:227], v[12:15]
	v_mfma_f32_16x16x32_bf16 v[8:11], v[66:69], v[224:227], v[8:11]
	v_mfma_f32_16x16x32_bf16 v[78:81], v[62:65], v[204:207], v[78:81]
	v_mfma_f32_16x16x32_bf16 v[74:77], v[70:73], v[204:207], v[74:77]
	v_mfma_f32_16x16x32_bf16 v[46:49], v[62:65], v[212:215], v[46:49]
	v_mfma_f32_16x16x32_bf16 v[42:45], v[70:73], v[212:215], v[42:45]
	v_mfma_f32_16x16x32_bf16 v[28:31], v[62:65], v[220:223], v[28:31]
	v_mfma_f32_16x16x32_bf16 v[24:27], v[70:73], v[220:223], v[24:27]
	v_mfma_f32_16x16x32_bf16 v[12:15], v[62:65], v[228:231], v[12:15]
	v_mfma_f32_16x16x32_bf16 v[8:11], v[70:73], v[228:231], v[8:11]
	v_mfma_f32_16x16x32_bf16 v[50:53], v[158:161], v[200:203], v[50:53]
	v_mfma_f32_16x16x32_bf16 v[62:65], v[170:173], v[204:207], v[50:53]
	v_mfma_f32_16x16x32_bf16 v[50:53], v[180:183], v[200:203], v[54:57]
	v_mfma_f32_16x16x32_bf16 v[38:41], v[158:161], v[208:211], v[38:41]
	v_mfma_f32_16x16x32_bf16 v[34:37], v[180:183], v[208:211], v[34:37]
	v_mfma_f32_16x16x32_bf16 v[20:23], v[158:161], v[216:219], v[20:23]
	v_mfma_f32_16x16x32_bf16 v[16:19], v[180:183], v[216:219], v[16:19]
	v_mfma_f32_16x16x32_bf16 v[4:7], v[158:161], v[224:227], v[4:7]
	v_mfma_f32_16x16x32_bf16 v[0:3], v[180:183], v[224:227], v[0:3]
	v_mfma_f32_16x16x32_bf16 v[58:61], v[196:199], v[204:207], v[50:53]
	v_mfma_f32_16x16x32_bf16 v[38:41], v[170:173], v[212:215], v[38:41]
	v_mfma_f32_16x16x32_bf16 v[34:37], v[196:199], v[212:215], v[34:37]
	v_mfma_f32_16x16x32_bf16 v[20:23], v[170:173], v[220:223], v[20:23]
	v_mfma_f32_16x16x32_bf16 v[16:19], v[196:199], v[220:223], v[16:19]
	v_mfma_f32_16x16x32_bf16 v[4:7], v[170:173], v[228:231], v[4:7]
	v_mfma_f32_16x16x32_bf16 v[0:3], v[196:199], v[228:231], v[0:3]
	s_barrier
	s_add_i32 s80, s80, 2
	s_add_u32 vcc_hi, vcc_hi, 0x100
	s_addc_u32 s7, s7, 0
	s_add_u32 s46, s46, 0x100
	s_addc_u32 s47, s47, 0
	s_cmp_gt_u32 s80, 13
	s_cbranch_scc0 .LBB0_145
	v_readlane_b32 s46, v254, 51
	v_readlane_b32 s47, v254, 52
	s_and_b64 vcc, exec, s[46:47]
	s_cbranch_vccz .LBB0_148
	s_barrier

; #define PG8_STAGE(bufoff, gbase, voff) do { _Pragma("unroll") for (int _i = 0; _i < 2; ++_i) \
;         __builtin_amdgcn_global_load_lds((const unsigned*)((const char*)(gbase) + (voff)[_i]), (PG8_LAS unsigned*)(lds + (bufoff) + ldsw + _i * 8192), 16, 0, 0); } while (0)
; #define PG8_LDA(dst, b, h) do { _Pragma("unroll") for (int m = 0; m < 4; ++m) _Pragma("unroll") for (int k = 0; k < 2; ++k) dst[m][k] = *(const PG8_LAS bf16x8*)(lds + PG8_SA(b, h) + aoff + m * 2048 + k * 1024); } while (0)
; #define PG8_LDB(dst, b, h) do { _Pragma("unroll") for (int n = 0; n < 2; ++n) _Pragma("unroll") for (int k = 0; k < 2; ++k) dst[n][k] = *(const PG8_LAS bf16x8*)(lds + PG8_SB(b, h) + boff + n * 2048 + k * 1024); } while (0)
; #define PG8_MMA(ai, bj, At, Bt) do { __builtin_amdgcn_s_setprio(1); _Pragma("unroll") for (int m = 0; m < 4; ++m) _Pragma("unroll") for (int n = 0; n < 2; ++n) _Pragma("unroll") for (int k = 0; k < 2; ++k) \
;         acc[ai][bj][m][n] = __builtin_amdgcn_mfma_f32_16x16x32_bf16(Bt[n][k], At[m][k], acc[ai][bj][m][n], 0, 0, 0); __builtin_amdgcn_s_setprio(0); } while (0)
; #define PG8_WAIT_V(n) asm volatile("s_waitcnt vmcnt(" #n ")" ::: "memory")
; #define PG8_WAIT_L(n) asm volatile("s_waitcnt lgkmcnt(" #n ")" ::: "memory")
; template <class Epi, class Sched, bool ALIGN_EPI = false, bool SP2 = false>
; __device__ __forceinline__ void gemm_phase(PG8_LAS unsigned char* lds, const Gemm g, const Sched& S, const Epi& E) {
;     ...
;             const bool last = (t == nt - 2);
;             const char* a1 = cA + (size_t)(t + 1) * kstep;
;             const char* a2 = last ? nA : cA + (size_t)(t + 2) * kstep; const char* b2 = last ? nB : cB + (size_t)(t + 2) * kstep;
;             const char* a3 = a2 + kstep; const char* b3 = b2 + kstep;
;             if (last && has_next) S.a_ready(nxt);
;             if constexpr (SP2) {
;             PG8_LDB(B0, 0, 0); PG8_LDB(B1, 0, 1); PG8_SCHED; PG8_LDA(At, 0, 0); PG8_STAGE(PG8_SA(1, 1), a1 + hstep, voffA);
;             PG8_WAIT_V(8); PG8_WAIT_L(0); PG8_BAR; PG8_MMA(0, 0, At, B0); PG8_MMA(0, 1, At, B1); PG8_BAR; PG8_SCHED;
;             PG8_LDA(At, 0, 1); PG8_STAGE(PG8_SB(0, 0), b2, voffB); PG8_STAGE(PG8_SB(0, 1), b2 + hstep, voffB); PG8_STAGE(PG8_SA(0, 0), a2, voffA);
;             PG8_WAIT_V(8); PG8_WAIT_L(0); PG8_BAR; PG8_MMA(1, 0, At, B0); PG8_MMA(1, 1, At, B1); PG8_BAR; PG8_SCHED;
.LBB0_369:
	s_add_i32 s92, s46, 2
	s_add_u32 s61, s44, 0x80
	s_addc_u32 s47, s45, 0
	s_add_i32 s72, 0, 0x10000
	s_cmp_eq_u32 s87, s46
	s_cselect_b32 s47, s43, s47
	s_cselect_b32 s46, s42, s61
	v_add_u32_e32 v149, s72, v146
	s_cselect_b32 s95, s77, s91
	s_cselect_b32 s94, s76, s90
	s_add_i32 s61, 0, 0x14000
	ds_read_b128 v[142:145], v149
	ds_read_b128 v[150:153], v149 offset:1024
	ds_read_b128 v[154:157], v149 offset:2048
	ds_read_b128 v[158:161], v149 offset:3072
	v_add_u32_e32 v149, s61, v146
	ds_read_b128 v[170:173], v149
	ds_read_b128 v[174:177], v149 offset:1024
	ds_read_b128 v[178:181], v149 offset:2048
	ds_read_b128 v[182:185], v149 offset:3072
	s_add_i32 m0, s51, 0xc000
	ds_read_b128 v[196:199], v148
	ds_read_b128 v[200:203], v148 offset:1024
	ds_read_b128 v[204:207], v148 offset:2048
	ds_read_b128 v[208:211], v148 offset:3072
	ds_read_b128 v[212:215], v148 offset:4096
	ds_read_b128 v[216:219], v148 offset:5120
	ds_read_b128 v[220:223], v148 offset:6144
	ds_read_b128 v[224:227], v148 offset:7168
	global_load_lds_dwordx4 v140, s[44:45]
	s_add_i32 m0, s51, 0xe000
	s_nop 0
	global_load_lds_dwordx4 v138, s[44:45]
	s_waitcnt vmcnt(8)
	s_waitcnt lgkmcnt(0)
	s_barrier
	v_mfma_f32_16x16x32_bf16 v[126:129], v[142:145], v[196:199], v[126:129]
	v_mfma_f32_16x16x32_bf16 v[122:125], v[154:157], v[196:199], v[122:125]
	v_mfma_f32_16x16x32_bf16 v[110:113], v[142:145], v[204:207], v[110:113]
	v_mfma_f32_16x16x32_bf16 v[106:109], v[154:157], v[204:207], v[106:109]
	v_mfma_f32_16x16x32_bf16 v[94:97], v[142:145], v[212:215], v[94:97]
	v_mfma_f32_16x16x32_bf16 v[90:93], v[154:157], v[212:215], v[90:93]
	v_mfma_f32_16x16x32_bf16 v[78:81], v[142:145], v[220:223], v[78:81]
	v_mfma_f32_16x16x32_bf16 v[74:77], v[154:157], v[220:223], v[74:77]
	v_mfma_f32_16x16x32_bf16 v[126:129], v[150:153], v[200:203], v[126:129]
	v_mfma_f32_16x16x32_bf16 v[122:125], v[158:161], v[200:203], v[122:125]
	v_mfma_f32_16x16x32_bf16 v[110:113], v[150:153], v[208:211], v[110:113]
	v_mfma_f32_16x16x32_bf16 v[106:109], v[158:161], v[208:211], v[106:109]
	v_mfma_f32_16x16x32_bf16 v[94:97], v[150:153], v[216:219], v[94:97]
	v_mfma_f32_16x16x32_bf16 v[90:93], v[158:161], v[216:219], v[90:93]
	v_mfma_f32_16x16x32_bf16 v[78:81], v[150:153], v[224:227], v[78:81]
	v_mfma_f32_16x16x32_bf16 v[74:77], v[158:161], v[224:227], v[74:77]
	v_mfma_f32_16x16x32_bf16 v[118:121], v[170:173], v[196:199], v[118:121]
	v_mfma_f32_16x16x32_bf16 v[114:117], v[178:181], v[196:199], v[114:117]
	v_mfma_f32_16x16x32_bf16 v[102:105], v[170:173], v[204:207], v[102:105]
	v_mfma_f32_16x16x32_bf16 v[98:101], v[178:181], v[204:207], v[98:101]
	v_mfma_f32_16x16x32_bf16 v[86:89], v[170:173], v[212:215], v[86:89]
	v_mfma_f32_16x16x32_bf16 v[82:85], v[178:181], v[212:215], v[82:85]
	v_mfma_f32_16x16x32_bf16 v[70:73], v[170:173], v[220:223], v[70:73]
	v_mfma_f32_16x16x32_bf16 v[66:69], v[178:181], v[220:223], v[66:69]
	v_mfma_f32_16x16x32_bf16 v[118:121], v[174:177], v[200:203], v[118:121]
	v_mfma_f32_16x16x32_bf16 v[114:117], v[182:185], v[200:203], v[114:117]
	v_mfma_f32_16x16x32_bf16 v[102:105], v[174:177], v[208:211], v[102:105]
	v_mfma_f32_16x16x32_bf16 v[98:101], v[182:185], v[208:211], v[98:101]
	v_mfma_f32_16x16x32_bf16 v[86:89], v[174:177], v[216:219], v[86:89]
	v_mfma_f32_16x16x32_bf16 v[82:85], v[182:185], v[216:219], v[82:85]
	v_mfma_f32_16x16x32_bf16 v[70:73], v[174:177], v[224:227], v[70:73]
	v_mfma_f32_16x16x32_bf16 v[66:69], v[182:185], v[224:227], v[66:69]
	s_barrier
	s_add_i32 s72, s72, s50
	v_lshl_add_u64 v[228:229], s[94:95], 0, v[132:133]
	s_mov_b32 m0, s72
	ds_read_b128 v[196:199], v148 offset:16384
	ds_read_b128 v[200:203], v148 offset:17408
	ds_read_b128 v[204:207], v148 offset:18432
	ds_read_b128 v[208:211], v148 offset:19456
	ds_read_b128 v[212:215], v148 offset:20480
	ds_read_b128 v[216:219], v148 offset:21504
	ds_read_b128 v[220:223], v148 offset:22528
	ds_read_b128 v[224:227], v148 offset:23552
	global_load_lds_dwordx4 v[228:229], off
	s_add_i32 m0, s72, 0x2000
	v_lshl_add_u64 v[230:231], s[94:95], 0, v[136:137]
	s_add_u32 s94, s94, s8
	s_addc_u32 s95, s95, 0
	s_add_i32 s61, s61, s50
	global_load_lds_dwordx4 v[230:231], off
	v_lshl_add_u64 v[232:233], s[94:95], 0, v[132:133]
	s_mov_b32 m0, s61
	v_lshl_add_u64 v[234:235], s[94:95], 0, v[136:137]
	global_load_lds_dwordx4 v[232:233], off
	s_add_i32 m0, s61, 0x2000
	v_lshl_add_u64 v[236:237], s[46:47], 0, v[130:131]
	global_load_lds_dwordx4 v[234:235], off
	s_mov_b32 m0, s51
	v_lshl_add_u64 v[238:239], s[46:47], 0, v[134:135]
	global_load_lds_dwordx4 v[236:237], off
	s_mov_b32 m0, s78
	s_nop 0
	global_load_lds_dwordx4 v[238:239], off
	s_waitcnt vmcnt(8)
	s_waitcnt lgkmcnt(0)
	s_barrier
; #define PG8_STAGE(bufoff, gbase, voff) do { _Pragma("unroll") for (int _i = 0; _i < 2; ++_i) \
;         __builtin_amdgcn_global_load_lds((const unsigned*)((const char*)(gbase) + (voff)[_i]), (PG8_LAS unsigned*)(lds + (bufoff) + ldsw + _i * 8192), 16, 0, 0); } while (0)
; #define PG8_LDA(dst, b, h) do { _Pragma("unroll") for (int m = 0; m < 4; ++m) _Pragma("unroll") for (int k = 0; k < 2; ++k) dst[m][k] = *(const PG8_LAS bf16x8*)(lds + PG8_SA(b, h) + aoff + m * 2048 + k * 1024); } while (0)
; #define PG8_LDB(dst, b, h) do { _Pragma("unroll") for (int n = 0; n < 2; ++n) _Pragma("unroll") for (int k = 0; k < 2; ++k) dst[n][k] = *(const PG8_LAS bf16x8*)(lds + PG8_SB(b, h) + boff + n * 2048 + k * 1024); } while (0)
; #define PG8_MMA(ai, bj, At, Bt) do { __builtin_amdgcn_s_setprio(1); _Pragma("unroll") for (int m = 0; m < 4; ++m) _Pragma("unroll") for (int n = 0; n < 2; ++n) _Pragma("unroll") for (int k = 0; k < 2; ++k) \
;         acc[ai][bj][m][n] = __builtin_amdgcn_mfma_f32_16x16x32_bf16(Bt[n][k], At[m][k], acc[ai][bj][m][n], 0, 0, 0); __builtin_amdgcn_s_setprio(0); } while (0)
; #define PG8_WAIT_V(n) asm volatile("s_waitcnt vmcnt(" #n ")" ::: "memory")
; #define PG8_WAIT_L(n) asm volatile("s_waitcnt lgkmcnt(" #n ")" ::: "memory")
; #define PG8_BAR __builtin_amdgcn_s_barrier()
; #define PG8_SCHED __builtin_amdgcn_sched_barrier(0)
; template <class Epi, class Sched, bool ALIGN_EPI = false, bool SP2 = false>
; __device__ __forceinline__ void gemm_phase(PG8_LAS unsigned char* lds, const Gemm g, const Sched& S, const Epi& E) {
;     ...
;             PG8_WAIT_V(8); PG8_WAIT_L(0); PG8_BAR; PG8_MMA(1, 0, At, B0); PG8_MMA(1, 1, At, B1); PG8_BAR; PG8_SCHED;
;             PG8_LDB(B0, 1, 0); PG8_LDB(B1, 1, 1); PG8_SCHED; PG8_LDA(At, 1, 0); PG8_STAGE(PG8_SA(0, 1), a2 + hstep, voffA);
;             PG8_WAIT_V(8); PG8_WAIT_L(0); PG8_BAR; PG8_MMA(0, 0, At, B0); PG8_MMA(0, 1, At, B1); PG8_BAR; PG8_SCHED;
	v_mfma_f32_16x16x32_bf16 v[62:65], v[142:145], v[196:199], v[62:65]
	v_mfma_f32_16x16x32_bf16 v[58:61], v[154:157], v[196:199], v[58:61]
	v_mfma_f32_16x16x32_bf16 v[46:49], v[142:145], v[204:207], v[46:49]
	v_mfma_f32_16x16x32_bf16 v[42:45], v[154:157], v[204:207], v[42:45]
	v_mfma_f32_16x16x32_bf16 v[28:31], v[142:145], v[212:215], v[28:31]
	v_mfma_f32_16x16x32_bf16 v[24:27], v[154:157], v[212:215], v[24:27]
	v_mfma_f32_16x16x32_bf16 v[12:15], v[142:145], v[220:223], v[12:15]
	v_mfma_f32_16x16x32_bf16 v[8:11], v[154:157], v[220:223], v[8:11]
	v_mfma_f32_16x16x32_bf16 v[62:65], v[150:153], v[200:203], v[62:65]
	v_mfma_f32_16x16x32_bf16 v[58:61], v[158:161], v[200:203], v[58:61]
	v_mfma_f32_16x16x32_bf16 v[46:49], v[150:153], v[208:211], v[46:49]
	v_mfma_f32_16x16x32_bf16 v[42:45], v[158:161], v[208:211], v[42:45]
	v_mfma_f32_16x16x32_bf16 v[28:31], v[150:153], v[216:219], v[28:31]
	v_mfma_f32_16x16x32_bf16 v[24:27], v[158:161], v[216:219], v[24:27]
	v_mfma_f32_16x16x32_bf16 v[12:15], v[150:153], v[224:227], v[12:15]
	v_mfma_f32_16x16x32_bf16 v[8:11], v[158:161], v[224:227], v[8:11]
	v_mfma_f32_16x16x32_bf16 v[54:57], v[170:173], v[196:199], v[54:57]
	v_mfma_f32_16x16x32_bf16 v[50:53], v[178:181], v[196:199], v[50:53]
	v_mfma_f32_16x16x32_bf16 v[38:41], v[170:173], v[204:207], v[38:41]
	v_mfma_f32_16x16x32_bf16 v[34:37], v[178:181], v[204:207], v[34:37]
	v_mfma_f32_16x16x32_bf16 v[20:23], v[170:173], v[212:215], v[20:23]
	v_mfma_f32_16x16x32_bf16 v[16:19], v[178:181], v[212:215], v[16:19]
	v_mfma_f32_16x16x32_bf16 v[4:7], v[170:173], v[220:223], v[4:7]
	v_mfma_f32_16x16x32_bf16 v[0:3], v[178:181], v[220:223], v[0:3]
	v_mfma_f32_16x16x32_bf16 v[54:57], v[174:177], v[200:203], v[54:57]
	v_mfma_f32_16x16x32_bf16 v[50:53], v[182:185], v[200:203], v[50:53]
	v_mfma_f32_16x16x32_bf16 v[38:41], v[174:177], v[208:211], v[38:41]
	v_mfma_f32_16x16x32_bf16 v[34:37], v[182:185], v[208:211], v[34:37]
	v_mfma_f32_16x16x32_bf16 v[20:23], v[174:177], v[216:219], v[20:23]
	v_mfma_f32_16x16x32_bf16 v[16:19], v[182:185], v[216:219], v[16:19]
	v_mfma_f32_16x16x32_bf16 v[4:7], v[174:177], v[224:227], v[4:7]
	v_mfma_f32_16x16x32_bf16 v[0:3], v[182:185], v[224:227], v[0:3]
	s_barrier
	s_add_i32 s61, 0, 0x18000
	v_add_u32_e32 v149, s61, v146
	s_add_i32 s72, 0, 0x1c000
	ds_read_b128 v[142:145], v149
	ds_read_b128 v[150:153], v149 offset:1024
	ds_read_b128 v[154:157], v149 offset:2048
	ds_read_b128 v[158:161], v149 offset:3072
	v_add_u32_e32 v149, s72, v146
	ds_read_b128 v[170:173], v149
	ds_read_b128 v[174:177], v149 offset:1024
	ds_read_b128 v[178:181], v149 offset:2048
	ds_read_b128 v[182:185], v149 offset:3072
	s_add_u32 s46, s46, s8
	s_addc_u32 s47, s47, 0
	s_mov_b32 m0, s79
	ds_read_b128 v[196:199], v148 offset:32768
	ds_read_b128 v[200:203], v148 offset:33792
	ds_read_b128 v[204:207], v148 offset:34816
	ds_read_b128 v[208:211], v148 offset:35840
	ds_read_b128 v[212:215], v148 offset:36864
	ds_read_b128 v[216:219], v148 offset:37888
	ds_read_b128 v[220:223], v148 offset:38912
	ds_read_b128 v[224:227], v148 offset:39936
	global_load_lds_dwordx4 v130, s[46:47]
	s_mov_b32 m0, s80
	s_nop 0
	global_load_lds_dwordx4 v134, s[46:47]
	s_waitcnt vmcnt(8)
	s_waitcnt lgkmcnt(0)
	s_barrier
	v_mfma_f32_16x16x32_bf16 v[126:129], v[142:145], v[196:199], v[126:129]
	v_mfma_f32_16x16x32_bf16 v[122:125], v[154:157], v[196:199], v[122:125]
	v_mfma_f32_16x16x32_bf16 v[110:113], v[142:145], v[204:207], v[110:113]
	v_mfma_f32_16x16x32_bf16 v[106:109], v[154:157], v[204:207], v[106:109]
	v_mfma_f32_16x16x32_bf16 v[94:97], v[142:145], v[212:215], v[94:97]
	v_mfma_f32_16x16x32_bf16 v[90:93], v[154:157], v[212:215], v[90:93]
	v_mfma_f32_16x16x32_bf16 v[78:81], v[142:145], v[220:223], v[78:81]
	v_mfma_f32_16x16x32_bf16 v[74:77], v[154:157], v[220:223], v[74:77]
	v_mfma_f32_16x16x32_bf16 v[126:129], v[150:153], v[200:203], v[126:129]
	v_mfma_f32_16x16x32_bf16 v[122:125], v[158:161], v[200:203], v[122:125]
	v_mfma_f32_16x16x32_bf16 v[110:113], v[150:153], v[208:211], v[110:113]
	v_mfma_f32_16x16x32_bf16 v[106:109], v[158:161], v[208:211], v[106:109]
	v_mfma_f32_16x16x32_bf16 v[94:97], v[150:153], v[216:219], v[94:97]
	v_mfma_f32_16x16x32_bf16 v[90:93], v[158:161], v[216:219], v[90:93]
	v_mfma_f32_16x16x32_bf16 v[78:81], v[150:153], v[224:227], v[78:81]
	v_mfma_f32_16x16x32_bf16 v[74:77], v[158:161], v[224:227], v[74:77]
	v_mfma_f32_16x16x32_bf16 v[118:121], v[170:173], v[196:199], v[118:121]
	v_mfma_f32_16x16x32_bf16 v[114:117], v[178:181], v[196:199], v[114:117]
	v_mfma_f32_16x16x32_bf16 v[102:105], v[170:173], v[204:207], v[102:105]
	v_mfma_f32_16x16x32_bf16 v[98:101], v[178:181], v[204:207], v[98:101]
	v_mfma_f32_16x16x32_bf16 v[86:89], v[170:173], v[212:215], v[86:89]
	v_mfma_f32_16x16x32_bf16 v[82:85], v[178:181], v[212:215], v[82:85]
	v_mfma_f32_16x16x32_bf16 v[70:73], v[170:173], v[220:223], v[70:73]
	v_mfma_f32_16x16x32_bf16 v[66:69], v[178:181], v[220:223], v[66:69]
	v_mfma_f32_16x16x32_bf16 v[118:121], v[174:177], v[200:203], v[118:121]
	v_mfma_f32_16x16x32_bf16 v[114:117], v[182:185], v[200:203], v[114:117]
	v_mfma_f32_16x16x32_bf16 v[102:105], v[174:177], v[208:211], v[102:105]
	v_mfma_f32_16x16x32_bf16 v[98:101], v[182:185], v[208:211], v[98:101]
	v_mfma_f32_16x16x32_bf16 v[86:89], v[174:177], v[216:219], v[86:89]
	v_mfma_f32_16x16x32_bf16 v[82:85], v[182:185], v[216:219], v[82:85]
	v_mfma_f32_16x16x32_bf16 v[70:73], v[174:177], v[224:227], v[70:73]
	v_mfma_f32_16x16x32_bf16 v[66:69], v[182:185], v[224:227], v[66:69]
	s_barrier
; #define PG8_STAGE(bufoff, gbase, voff) do { _Pragma("unroll") for (int _i = 0; _i < 2; ++_i) \
;         __builtin_amdgcn_global_load_lds((const unsigned*)((const char*)(gbase) + (voff)[_i]), (PG8_LAS unsigned*)(lds + (bufoff) + ldsw + _i * 8192), 16, 0, 0); } while (0)
; #define PG8_LDA(dst, b, h) do { _Pragma("unroll") for (int m = 0; m < 4; ++m) _Pragma("unroll") for (int k = 0; k < 2; ++k) dst[m][k] = *(const PG8_LAS bf16x8*)(lds + PG8_SA(b, h) + aoff + m * 2048 + k * 1024); } while (0)
; #define PG8_MMA(ai, bj, At, Bt) do { __builtin_amdgcn_s_setprio(1); _Pragma("unroll") for (int m = 0; m < 4; ++m) _Pragma("unroll") for (int n = 0; n < 2; ++n) _Pragma("unroll") for (int k = 0; k < 2; ++k) \
;         acc[ai][bj][m][n] = __builtin_amdgcn_mfma_f32_16x16x32_bf16(Bt[n][k], At[m][k], acc[ai][bj][m][n], 0, 0, 0); __builtin_amdgcn_s_setprio(0); } while (0)
; #define PG8_WAIT_V(n) asm volatile("s_waitcnt vmcnt(" #n ")" ::: "memory")
; #define PG8_WAIT_L(n) asm volatile("s_waitcnt lgkmcnt(" #n ")" ::: "memory")
; #define PG8_BAR __builtin_amdgcn_s_barrier()
; #define PG8_SCHED __builtin_amdgcn_sched_barrier(0)
; template <class Epi, class Sched, bool ALIGN_EPI = false, bool SP2 = false>
; __device__ __forceinline__ void gemm_phase(PG8_LAS unsigned char* lds, const Gemm g, const Sched& S, const Epi& E) {
;     ...
;             PG8_LDA(At, 1, 1); PG8_STAGE(PG8_SB(1, 0), b3, voffB); PG8_STAGE(PG8_SB(1, 1), b3 + hstep, voffB); PG8_STAGE(PG8_SA(1, 0), a3, voffA);
;             PG8_WAIT_V(8); PG8_WAIT_L(0); PG8_BAR; PG8_MMA(1, 0, At, B0); PG8_MMA(1, 1, At, B1); PG8_BAR; PG8_SCHED;
;     ...
;         if constexpr (ALIGN_EPI) { if (wr == 0) PG8_BAR; }
	s_add_i32 s46, s61, s50
	v_lshl_add_u64 v[228:229], v[228:229], 0, s[34:35]
	s_mov_b32 m0, s46
	ds_read_b128 v[196:199], v148 offset:49152
	ds_read_b128 v[200:203], v148 offset:50176
	ds_read_b128 v[204:207], v148 offset:51200
	ds_read_b128 v[208:211], v148 offset:52224
	ds_read_b128 v[212:215], v148 offset:53248
	ds_read_b128 v[216:219], v148 offset:54272
	ds_read_b128 v[220:223], v148 offset:55296
	ds_read_b128 v[224:227], v148 offset:56320
	global_load_lds_dwordx4 v[228:229], off
	v_lshl_add_u64 v[228:229], v[230:231], 0, s[34:35]
	s_add_i32 m0, s46, 0x2000
	s_add_i32 s46, s72, s50
	global_load_lds_dwordx4 v[228:229], off
	v_lshl_add_u64 v[228:229], v[232:233], 0, s[34:35]
	s_mov_b32 m0, s46
	s_nop 0
	global_load_lds_dwordx4 v[228:229], off
	v_lshl_add_u64 v[228:229], v[234:235], 0, s[34:35]
	s_add_i32 m0, s46, 0x2000
	s_nop 0
	global_load_lds_dwordx4 v[228:229], off
	v_lshl_add_u64 v[228:229], v[236:237], 0, s[34:35]
	s_mov_b32 m0, s85
	s_nop 0
	global_load_lds_dwordx4 v[228:229], off
	v_lshl_add_u64 v[228:229], v[238:239], 0, s[34:35]
	s_mov_b32 m0, s86
	s_nop 0
	global_load_lds_dwordx4 v[228:229], off
	s_waitcnt vmcnt(8)
	s_waitcnt lgkmcnt(0)
	s_barrier
	v_mfma_f32_16x16x32_bf16 v[62:65], v[142:145], v[196:199], v[62:65]
	v_mfma_f32_16x16x32_bf16 v[58:61], v[154:157], v[196:199], v[58:61]
	v_mfma_f32_16x16x32_bf16 v[46:49], v[142:145], v[204:207], v[46:49]
	v_mfma_f32_16x16x32_bf16 v[42:45], v[154:157], v[204:207], v[42:45]
	v_mfma_f32_16x16x32_bf16 v[28:31], v[142:145], v[212:215], v[28:31]
	v_mfma_f32_16x16x32_bf16 v[24:27], v[154:157], v[212:215], v[24:27]
	v_mfma_f32_16x16x32_bf16 v[12:15], v[142:145], v[220:223], v[12:15]
	v_mfma_f32_16x16x32_bf16 v[8:11], v[154:157], v[220:223], v[8:11]
	v_mfma_f32_16x16x32_bf16 v[62:65], v[150:153], v[200:203], v[62:65]
	v_mfma_f32_16x16x32_bf16 v[58:61], v[158:161], v[200:203], v[58:61]
	v_mfma_f32_16x16x32_bf16 v[46:49], v[150:153], v[208:211], v[46:49]
	v_mfma_f32_16x16x32_bf16 v[42:45], v[158:161], v[208:211], v[42:45]
	v_mfma_f32_16x16x32_bf16 v[28:31], v[150:153], v[216:219], v[28:31]
	v_mfma_f32_16x16x32_bf16 v[24:27], v[158:161], v[216:219], v[24:27]
	v_mfma_f32_16x16x32_bf16 v[12:15], v[150:153], v[224:227], v[12:15]
	v_mfma_f32_16x16x32_bf16 v[8:11], v[158:161], v[224:227], v[8:11]
	v_mfma_f32_16x16x32_bf16 v[54:57], v[170:173], v[196:199], v[54:57]
	v_mfma_f32_16x16x32_bf16 v[50:53], v[178:181], v[196:199], v[50:53]
	v_mfma_f32_16x16x32_bf16 v[38:41], v[170:173], v[204:207], v[38:41]
	v_mfma_f32_16x16x32_bf16 v[34:37], v[178:181], v[204:207], v[34:37]
	v_mfma_f32_16x16x32_bf16 v[20:23], v[170:173], v[212:215], v[20:23]
	v_mfma_f32_16x16x32_bf16 v[16:19], v[178:181], v[212:215], v[16:19]
	v_mfma_f32_16x16x32_bf16 v[4:7], v[170:173], v[220:223], v[4:7]
	v_mfma_f32_16x16x32_bf16 v[0:3], v[178:181], v[220:223], v[0:3]
	v_mfma_f32_16x16x32_bf16 v[54:57], v[174:177], v[200:203], v[54:57]
	v_mfma_f32_16x16x32_bf16 v[50:53], v[182:185], v[200:203], v[50:53]
	v_mfma_f32_16x16x32_bf16 v[38:41], v[174:177], v[208:211], v[38:41]
	v_mfma_f32_16x16x32_bf16 v[34:37], v[182:185], v[208:211], v[34:37]
	v_mfma_f32_16x16x32_bf16 v[20:23], v[174:177], v[216:219], v[20:23]
	v_mfma_f32_16x16x32_bf16 v[16:19], v[182:185], v[216:219], v[16:19]
	v_mfma_f32_16x16x32_bf16 v[4:7], v[174:177], v[224:227], v[4:7]
	v_mfma_f32_16x16x32_bf16 v[0:3], v[182:185], v[224:227], v[0:3]
	s_barrier
	s_add_u32 s90, s90, 0x100
	s_addc_u32 s91, s91, 0
	s_add_u32 s44, s44, 0x100
	s_addc_u32 s45, s45, 0
	s_cmp_ge_u32 s92, s82
	s_mov_b32 s46, s92
	s_cbranch_scc0 .LBB0_369
	s_and_b64 vcc, exec, s[40:41]
	s_cbranch_vccz .LBB0_372
	s_barrier

; #define PG8_STAGE(bufoff, gbase, voff) do { _Pragma("unroll") for (int _i = 0; _i < 2; ++_i) \
;         __builtin_amdgcn_global_load_lds((const unsigned*)((const char*)(gbase) + (voff)[_i]), (PG8_LAS unsigned*)(lds + (bufoff) + ldsw + _i * 8192), 16, 0, 0); } while (0)
; #define PG8_LDA(dst, b, h) do { _Pragma("unroll") for (int m = 0; m < 4; ++m) _Pragma("unroll") for (int k = 0; k < 2; ++k) dst[m][k] = *(const PG8_LAS bf16x8*)(lds + PG8_SA(b, h) + aoff + m * 2048 + k * 1024); } while (0)
; #define PG8_LDB(dst, b, h) do { _Pragma("unroll") for (int n = 0; n < 2; ++n) _Pragma("unroll") for (int k = 0; k < 2; ++k) dst[n][k] = *(const PG8_LAS bf16x8*)(lds + PG8_SB(b, h) + boff + n * 2048 + k * 1024); } while (0)
; #define PG8_MMA(ai, bj, At, Bt) do { __builtin_amdgcn_s_setprio(1); _Pragma("unroll") for (int m = 0; m < 4; ++m) _Pragma("unroll") for (int n = 0; n < 2; ++n) _Pragma("unroll") for (int k = 0; k < 2; ++k) \
;         acc[ai][bj][m][n] = __builtin_amdgcn_mfma_f32_16x16x32_bf16(Bt[n][k], At[m][k], acc[ai][bj][m][n], 0, 0, 0); __builtin_amdgcn_s_setprio(0); } while (0)
; #define PG8_WAIT_V(n) asm volatile("s_waitcnt vmcnt(" #n ")" ::: "memory")
; #define PG8_WAIT_L(n) asm volatile("s_waitcnt lgkmcnt(" #n ")" ::: "memory")
; template <class Epi, class Sched, bool ALIGN_EPI = false, bool SP2 = false>
; __device__ __forceinline__ void gemm_phase(PG8_LAS unsigned char* lds, const Gemm g, const Sched& S, const Epi& E) {
;     ...
;             const bool last = (t == nt - 2);
;             const char* a1 = cA + (size_t)(t + 1) * kstep;
;             const char* a2 = last ? nA : cA + (size_t)(t + 2) * kstep; const char* b2 = last ? nB : cB + (size_t)(t + 2) * kstep;
;             const char* a3 = a2 + kstep; const char* b3 = b2 + kstep;
;             if (last && has_next) S.a_ready(nxt);
;             if constexpr (SP2) {
;             PG8_LDB(B0, 0, 0); PG8_LDB(B1, 0, 1); PG8_SCHED; PG8_LDA(At, 0, 0); PG8_STAGE(PG8_SA(1, 1), a1 + hstep, voffA);
;             PG8_WAIT_V(8); PG8_WAIT_L(0); PG8_BAR; PG8_MMA(0, 0, At, B0); PG8_MMA(0, 1, At, B1); PG8_BAR; PG8_SCHED;
;             PG8_LDA(At, 0, 1); PG8_STAGE(PG8_SB(0, 0), b2, voffB); PG8_STAGE(PG8_SB(0, 1), b2 + hstep, voffB); PG8_STAGE(PG8_SA(0, 0), a2, voffA);
;             PG8_WAIT_V(8); PG8_WAIT_L(0); PG8_BAR; PG8_MMA(1, 0, At, B0); PG8_MMA(1, 1, At, B1); PG8_BAR; PG8_SCHED;
.LBB0_411:
	s_add_i32 vcc_lo, s46, 2
	s_add_u32 s38, s44, 0x80
	s_addc_u32 s39, s45, 0
	s_add_i32 vcc_hi, 0, 0x10000
	s_cmp_eq_u32 s92, s46
	s_cselect_b32 s47, s79, s39
	s_cselect_b32 s46, s78, s38
	v_add_u32_e32 v149, vcc_hi, v146
	s_cselect_b32 s39, s81, s49
	s_cselect_b32 s38, s80, s48
	s_add_i32 s61, 0, 0x14000
	ds_read_b128 v[142:145], v149
	ds_read_b128 v[150:153], v149 offset:1024
	ds_read_b128 v[154:157], v149 offset:2048
	ds_read_b128 v[158:161], v149 offset:3072
	v_add_u32_e32 v149, s61, v146
	ds_read_b128 v[170:173], v149
	ds_read_b128 v[174:177], v149 offset:1024
	ds_read_b128 v[178:181], v149 offset:2048
	ds_read_b128 v[182:185], v149 offset:3072
	s_add_i32 m0, s82, 0xc000
	ds_read_b128 v[196:199], v148
	ds_read_b128 v[200:203], v148 offset:1024
	ds_read_b128 v[204:207], v148 offset:2048
	ds_read_b128 v[208:211], v148 offset:3072
	ds_read_b128 v[212:215], v148 offset:4096
	ds_read_b128 v[216:219], v148 offset:5120
	ds_read_b128 v[220:223], v148 offset:6144
	ds_read_b128 v[224:227], v148 offset:7168
	global_load_lds_dwordx4 v140, s[44:45]
	s_add_i32 m0, s82, 0xe000
	s_nop 0
	global_load_lds_dwordx4 v138, s[44:45]
	s_waitcnt vmcnt(8)
	s_waitcnt lgkmcnt(0)
	s_barrier
	v_mfma_f32_16x16x32_bf16 v[126:129], v[142:145], v[196:199], v[126:129]
	v_mfma_f32_16x16x32_bf16 v[122:125], v[154:157], v[196:199], v[122:125]
	v_mfma_f32_16x16x32_bf16 v[110:113], v[142:145], v[204:207], v[110:113]
	v_mfma_f32_16x16x32_bf16 v[106:109], v[154:157], v[204:207], v[106:109]
	v_mfma_f32_16x16x32_bf16 v[94:97], v[142:145], v[212:215], v[94:97]
	v_mfma_f32_16x16x32_bf16 v[90:93], v[154:157], v[212:215], v[90:93]
	v_mfma_f32_16x16x32_bf16 v[78:81], v[142:145], v[220:223], v[78:81]
	v_mfma_f32_16x16x32_bf16 v[74:77], v[154:157], v[220:223], v[74:77]
	v_mfma_f32_16x16x32_bf16 v[126:129], v[150:153], v[200:203], v[126:129]
	v_mfma_f32_16x16x32_bf16 v[122:125], v[158:161], v[200:203], v[122:125]
	v_mfma_f32_16x16x32_bf16 v[110:113], v[150:153], v[208:211], v[110:113]
	v_mfma_f32_16x16x32_bf16 v[106:109], v[158:161], v[208:211], v[106:109]
	v_mfma_f32_16x16x32_bf16 v[94:97], v[150:153], v[216:219], v[94:97]
	v_mfma_f32_16x16x32_bf16 v[90:93], v[158:161], v[216:219], v[90:93]
	v_mfma_f32_16x16x32_bf16 v[78:81], v[150:153], v[224:227], v[78:81]
	v_mfma_f32_16x16x32_bf16 v[74:77], v[158:161], v[224:227], v[74:77]
	v_mfma_f32_16x16x32_bf16 v[118:121], v[170:173], v[196:199], v[118:121]
	v_mfma_f32_16x16x32_bf16 v[114:117], v[178:181], v[196:199], v[114:117]
	v_mfma_f32_16x16x32_bf16 v[102:105], v[170:173], v[204:207], v[102:105]
	v_mfma_f32_16x16x32_bf16 v[98:101], v[178:181], v[204:207], v[98:101]
	v_mfma_f32_16x16x32_bf16 v[86:89], v[170:173], v[212:215], v[86:89]
	v_mfma_f32_16x16x32_bf16 v[82:85], v[178:181], v[212:215], v[82:85]
	v_mfma_f32_16x16x32_bf16 v[70:73], v[170:173], v[220:223], v[70:73]
	v_mfma_f32_16x16x32_bf16 v[66:69], v[178:181], v[220:223], v[66:69]
	v_mfma_f32_16x16x32_bf16 v[118:121], v[174:177], v[200:203], v[118:121]
	v_mfma_f32_16x16x32_bf16 v[114:117], v[182:185], v[200:203], v[114:117]
	v_mfma_f32_16x16x32_bf16 v[102:105], v[174:177], v[208:211], v[102:105]
	v_mfma_f32_16x16x32_bf16 v[98:101], v[182:185], v[208:211], v[98:101]
	v_mfma_f32_16x16x32_bf16 v[86:89], v[174:177], v[216:219], v[86:89]
	v_mfma_f32_16x16x32_bf16 v[82:85], v[182:185], v[216:219], v[82:85]
	v_mfma_f32_16x16x32_bf16 v[70:73], v[174:177], v[224:227], v[70:73]
	v_mfma_f32_16x16x32_bf16 v[66:69], v[182:185], v[224:227], v[66:69]
	s_barrier
	s_add_i32 vcc_hi, vcc_hi, s51
	v_lshl_add_u64 v[228:229], s[38:39], 0, v[132:133]
	s_mov_b32 m0, vcc_hi
	ds_read_b128 v[196:199], v148 offset:16384
	ds_read_b128 v[200:203], v148 offset:17408
	ds_read_b128 v[204:207], v148 offset:18432
	ds_read_b128 v[208:211], v148 offset:19456
	ds_read_b128 v[212:215], v148 offset:20480
	ds_read_b128 v[216:219], v148 offset:21504
	ds_read_b128 v[220:223], v148 offset:22528
	ds_read_b128 v[224:227], v148 offset:23552
	global_load_lds_dwordx4 v[228:229], off
	s_add_i32 m0, vcc_hi, 0x2000
	v_lshl_add_u64 v[230:231], s[38:39], 0, v[136:137]
	s_add_u32 s38, s38, s8
	s_addc_u32 s39, s39, 0
	s_add_i32 s61, s61, s51
	global_load_lds_dwordx4 v[230:231], off
	v_lshl_add_u64 v[232:233], s[38:39], 0, v[132:133]
	s_mov_b32 m0, s61
	v_lshl_add_u64 v[234:235], s[38:39], 0, v[136:137]
	global_load_lds_dwordx4 v[232:233], off
	s_add_i32 m0, s61, 0x2000
	v_lshl_add_u64 v[236:237], s[46:47], 0, v[130:131]
	global_load_lds_dwordx4 v[234:235], off
	s_mov_b32 m0, s82
	v_lshl_add_u64 v[238:239], s[46:47], 0, v[134:135]
	global_load_lds_dwordx4 v[236:237], off
	s_mov_b32 m0, s83
	s_nop 0
	global_load_lds_dwordx4 v[238:239], off
	s_waitcnt vmcnt(8)
	s_waitcnt lgkmcnt(0)
	s_barrier
; #define PG8_STAGE(bufoff, gbase, voff) do { _Pragma("unroll") for (int _i = 0; _i < 2; ++_i) \
;         __builtin_amdgcn_global_load_lds((const unsigned*)((const char*)(gbase) + (voff)[_i]), (PG8_LAS unsigned*)(lds + (bufoff) + ldsw + _i * 8192), 16, 0, 0); } while (0)
; #define PG8_LDA(dst, b, h) do { _Pragma("unroll") for (int m = 0; m < 4; ++m) _Pragma("unroll") for (int k = 0; k < 2; ++k) dst[m][k] = *(const PG8_LAS bf16x8*)(lds + PG8_SA(b, h) + aoff + m * 2048 + k * 1024); } while (0)
; #define PG8_LDB(dst, b, h) do { _Pragma("unroll") for (int n = 0; n < 2; ++n) _Pragma("unroll") for (int k = 0; k < 2; ++k) dst[n][k] = *(const PG8_LAS bf16x8*)(lds + PG8_SB(b, h) + boff + n * 2048 + k * 1024); } while (0)
; #define PG8_MMA(ai, bj, At, Bt) do { __builtin_amdgcn_s_setprio(1); _Pragma("unroll") for (int m = 0; m < 4; ++m) _Pragma("unroll") for (int n = 0; n < 2; ++n) _Pragma("unroll") for (int k = 0; k < 2; ++k) \
;         acc[ai][bj][m][n] = __builtin_amdgcn_mfma_f32_16x16x32_bf16(Bt[n][k], At[m][k], acc[ai][bj][m][n], 0, 0, 0); __builtin_amdgcn_s_setprio(0); } while (0)
; #define PG8_WAIT_V(n) asm volatile("s_waitcnt vmcnt(" #n ")" ::: "memory")
; #define PG8_WAIT_L(n) asm volatile("s_waitcnt lgkmcnt(" #n ")" ::: "memory")
; #define PG8_BAR __builtin_amdgcn_s_barrier()
; #define PG8_SCHED __builtin_amdgcn_sched_barrier(0)
; template <class Epi, class Sched, bool ALIGN_EPI = false, bool SP2 = false>
; __device__ __forceinline__ void gemm_phase(PG8_LAS unsigned char* lds, const Gemm g, const Sched& S, const Epi& E) {
;     ...
;             PG8_WAIT_V(8); PG8_WAIT_L(0); PG8_BAR; PG8_MMA(1, 0, At, B0); PG8_MMA(1, 1, At, B1); PG8_BAR; PG8_SCHED;
;             PG8_LDB(B0, 1, 0); PG8_LDB(B1, 1, 1); PG8_SCHED; PG8_LDA(At, 1, 0); PG8_STAGE(PG8_SA(0, 1), a2 + hstep, voffA);
;             PG8_WAIT_V(8); PG8_WAIT_L(0); PG8_BAR; PG8_MMA(0, 0, At, B0); PG8_MMA(0, 1, At, B1); PG8_BAR; PG8_SCHED;
	v_mfma_f32_16x16x32_bf16 v[62:65], v[142:145], v[196:199], v[62:65]
	v_mfma_f32_16x16x32_bf16 v[58:61], v[154:157], v[196:199], v[58:61]
	v_mfma_f32_16x16x32_bf16 v[46:49], v[142:145], v[204:207], v[46:49]
	v_mfma_f32_16x16x32_bf16 v[42:45], v[154:157], v[204:207], v[42:45]
	v_mfma_f32_16x16x32_bf16 v[28:31], v[142:145], v[212:215], v[28:31]
	v_mfma_f32_16x16x32_bf16 v[24:27], v[154:157], v[212:215], v[24:27]
	v_mfma_f32_16x16x32_bf16 v[12:15], v[142:145], v[220:223], v[12:15]
	v_mfma_f32_16x16x32_bf16 v[8:11], v[154:157], v[220:223], v[8:11]
	v_mfma_f32_16x16x32_bf16 v[62:65], v[150:153], v[200:203], v[62:65]
	v_mfma_f32_16x16x32_bf16 v[58:61], v[158:161], v[200:203], v[58:61]
	v_mfma_f32_16x16x32_bf16 v[46:49], v[150:153], v[208:211], v[46:49]
	v_mfma_f32_16x16x32_bf16 v[42:45], v[158:161], v[208:211], v[42:45]
	v_mfma_f32_16x16x32_bf16 v[28:31], v[150:153], v[216:219], v[28:31]
	v_mfma_f32_16x16x32_bf16 v[24:27], v[158:161], v[216:219], v[24:27]
	v_mfma_f32_16x16x32_bf16 v[12:15], v[150:153], v[224:227], v[12:15]
	v_mfma_f32_16x16x32_bf16 v[8:11], v[158:161], v[224:227], v[8:11]
	v_mfma_f32_16x16x32_bf16 v[54:57], v[170:173], v[196:199], v[54:57]
	v_mfma_f32_16x16x32_bf16 v[50:53], v[178:181], v[196:199], v[50:53]
	v_mfma_f32_16x16x32_bf16 v[38:41], v[170:173], v[204:207], v[38:41]
	v_mfma_f32_16x16x32_bf16 v[34:37], v[178:181], v[204:207], v[34:37]
	v_mfma_f32_16x16x32_bf16 v[20:23], v[170:173], v[212:215], v[20:23]
	v_mfma_f32_16x16x32_bf16 v[16:19], v[178:181], v[212:215], v[16:19]
	v_mfma_f32_16x16x32_bf16 v[4:7], v[170:173], v[220:223], v[4:7]
	v_mfma_f32_16x16x32_bf16 v[0:3], v[178:181], v[220:223], v[0:3]
	v_mfma_f32_16x16x32_bf16 v[54:57], v[174:177], v[200:203], v[54:57]
	v_mfma_f32_16x16x32_bf16 v[50:53], v[182:185], v[200:203], v[50:53]
	v_mfma_f32_16x16x32_bf16 v[38:41], v[174:177], v[208:211], v[38:41]
	v_mfma_f32_16x16x32_bf16 v[34:37], v[182:185], v[208:211], v[34:37]
	v_mfma_f32_16x16x32_bf16 v[20:23], v[174:177], v[216:219], v[20:23]
	v_mfma_f32_16x16x32_bf16 v[16:19], v[182:185], v[216:219], v[16:19]
	v_mfma_f32_16x16x32_bf16 v[4:7], v[174:177], v[224:227], v[4:7]
	v_mfma_f32_16x16x32_bf16 v[0:3], v[182:185], v[224:227], v[0:3]
	s_barrier
	s_add_i32 s61, 0, 0x18000
	v_add_u32_e32 v149, s61, v146
	s_add_i32 vcc_hi, 0, 0x1c000
	ds_read_b128 v[142:145], v149
	ds_read_b128 v[150:153], v149 offset:1024
	ds_read_b128 v[154:157], v149 offset:2048
	ds_read_b128 v[158:161], v149 offset:3072
	v_add_u32_e32 v149, vcc_hi, v146
	ds_read_b128 v[170:173], v149
	ds_read_b128 v[174:177], v149 offset:1024
	ds_read_b128 v[178:181], v149 offset:2048
	ds_read_b128 v[182:185], v149 offset:3072
	s_add_u32 s38, s46, s8
	s_addc_u32 s39, s47, 0
	s_mov_b32 m0, s87
	ds_read_b128 v[196:199], v148 offset:32768
	ds_read_b128 v[200:203], v148 offset:33792
	ds_read_b128 v[204:207], v148 offset:34816
	ds_read_b128 v[208:211], v148 offset:35840
	ds_read_b128 v[212:215], v148 offset:36864
	ds_read_b128 v[216:219], v148 offset:37888
	ds_read_b128 v[220:223], v148 offset:38912
	ds_read_b128 v[224:227], v148 offset:39936
	global_load_lds_dwordx4 v130, s[38:39]
	s_mov_b32 m0, s88
	s_nop 0
	global_load_lds_dwordx4 v134, s[38:39]
	s_waitcnt vmcnt(8)
	s_waitcnt lgkmcnt(0)
	s_barrier
	v_mfma_f32_16x16x32_bf16 v[126:129], v[142:145], v[196:199], v[126:129]
	v_mfma_f32_16x16x32_bf16 v[122:125], v[154:157], v[196:199], v[122:125]
	v_mfma_f32_16x16x32_bf16 v[110:113], v[142:145], v[204:207], v[110:113]
	v_mfma_f32_16x16x32_bf16 v[106:109], v[154:157], v[204:207], v[106:109]
	v_mfma_f32_16x16x32_bf16 v[94:97], v[142:145], v[212:215], v[94:97]
	v_mfma_f32_16x16x32_bf16 v[90:93], v[154:157], v[212:215], v[90:93]
	v_mfma_f32_16x16x32_bf16 v[78:81], v[142:145], v[220:223], v[78:81]
	v_mfma_f32_16x16x32_bf16 v[74:77], v[154:157], v[220:223], v[74:77]
	v_mfma_f32_16x16x32_bf16 v[126:129], v[150:153], v[200:203], v[126:129]
	v_mfma_f32_16x16x32_bf16 v[122:125], v[158:161], v[200:203], v[122:125]
	v_mfma_f32_16x16x32_bf16 v[110:113], v[150:153], v[208:211], v[110:113]
	v_mfma_f32_16x16x32_bf16 v[106:109], v[158:161], v[208:211], v[106:109]
	v_mfma_f32_16x16x32_bf16 v[94:97], v[150:153], v[216:219], v[94:97]
	v_mfma_f32_16x16x32_bf16 v[90:93], v[158:161], v[216:219], v[90:93]
	v_mfma_f32_16x16x32_bf16 v[78:81], v[150:153], v[224:227], v[78:81]
	v_mfma_f32_16x16x32_bf16 v[74:77], v[158:161], v[224:227], v[74:77]
	v_mfma_f32_16x16x32_bf16 v[118:121], v[170:173], v[196:199], v[118:121]
	v_mfma_f32_16x16x32_bf16 v[114:117], v[178:181], v[196:199], v[114:117]
	v_mfma_f32_16x16x32_bf16 v[102:105], v[170:173], v[204:207], v[102:105]
	v_mfma_f32_16x16x32_bf16 v[98:101], v[178:181], v[204:207], v[98:101]
	v_mfma_f32_16x16x32_bf16 v[86:89], v[170:173], v[212:215], v[86:89]
	v_mfma_f32_16x16x32_bf16 v[82:85], v[178:181], v[212:215], v[82:85]
	v_mfma_f32_16x16x32_bf16 v[70:73], v[170:173], v[220:223], v[70:73]
	v_mfma_f32_16x16x32_bf16 v[66:69], v[178:181], v[220:223], v[66:69]
	v_mfma_f32_16x16x32_bf16 v[118:121], v[174:177], v[200:203], v[118:121]
	v_mfma_f32_16x16x32_bf16 v[114:117], v[182:185], v[200:203], v[114:117]
	v_mfma_f32_16x16x32_bf16 v[102:105], v[174:177], v[208:211], v[102:105]
	v_mfma_f32_16x16x32_bf16 v[98:101], v[182:185], v[208:211], v[98:101]
	v_mfma_f32_16x16x32_bf16 v[86:89], v[174:177], v[216:219], v[86:89]
	v_mfma_f32_16x16x32_bf16 v[82:85], v[182:185], v[216:219], v[82:85]
	v_mfma_f32_16x16x32_bf16 v[70:73], v[174:177], v[224:227], v[70:73]
	v_mfma_f32_16x16x32_bf16 v[66:69], v[182:185], v[224:227], v[66:69]
	s_barrier
; #define PG8_STAGE(bufoff, gbase, voff) do { _Pragma("unroll") for (int _i = 0; _i < 2; ++_i) \
;         __builtin_amdgcn_global_load_lds((const unsigned*)((const char*)(gbase) + (voff)[_i]), (PG8_LAS unsigned*)(lds + (bufoff) + ldsw + _i * 8192), 16, 0, 0); } while (0)
; #define PG8_LDA(dst, b, h) do { _Pragma("unroll") for (int m = 0; m < 4; ++m) _Pragma("unroll") for (int k = 0; k < 2; ++k) dst[m][k] = *(const PG8_LAS bf16x8*)(lds + PG8_SA(b, h) + aoff + m * 2048 + k * 1024); } while (0)
; #define PG8_MMA(ai, bj, At, Bt) do { __builtin_amdgcn_s_setprio(1); _Pragma("unroll") for (int m = 0; m < 4; ++m) _Pragma("unroll") for (int n = 0; n < 2; ++n) _Pragma("unroll") for (int k = 0; k < 2; ++k) \
;         acc[ai][bj][m][n] = __builtin_amdgcn_mfma_f32_16x16x32_bf16(Bt[n][k], At[m][k], acc[ai][bj][m][n], 0, 0, 0); __builtin_amdgcn_s_setprio(0); } while (0)
; #define PG8_WAIT_V(n) asm volatile("s_waitcnt vmcnt(" #n ")" ::: "memory")
; #define PG8_WAIT_L(n) asm volatile("s_waitcnt lgkmcnt(" #n ")" ::: "memory")
; #define PG8_BAR __builtin_amdgcn_s_barrier()
; #define PG8_SCHED __builtin_amdgcn_sched_barrier(0)
; template <class Epi, class Sched, bool ALIGN_EPI = false, bool SP2 = false>
; __device__ __forceinline__ void gemm_phase(PG8_LAS unsigned char* lds, const Gemm g, const Sched& S, const Epi& E) {
;     ...
;             PG8_LDA(At, 1, 1); PG8_STAGE(PG8_SB(1, 0), b3, voffB); PG8_STAGE(PG8_SB(1, 1), b3 + hstep, voffB); PG8_STAGE(PG8_SA(1, 0), a3, voffA);
;             PG8_WAIT_V(8); PG8_WAIT_L(0); PG8_BAR; PG8_MMA(1, 0, At, B0); PG8_MMA(1, 1, At, B1); PG8_BAR; PG8_SCHED;
;     ...
;         if constexpr (ALIGN_EPI) { if (wr == 0) PG8_BAR; }
	s_add_i32 s38, s61, s51
	v_lshl_add_u64 v[228:229], v[228:229], 0, s[34:35]
	s_mov_b32 m0, s38
	ds_read_b128 v[196:199], v148 offset:49152
	ds_read_b128 v[200:203], v148 offset:50176
	ds_read_b128 v[204:207], v148 offset:51200
	ds_read_b128 v[208:211], v148 offset:52224
	ds_read_b128 v[212:215], v148 offset:53248
	ds_read_b128 v[216:219], v148 offset:54272
	ds_read_b128 v[220:223], v148 offset:55296
	ds_read_b128 v[224:227], v148 offset:56320
	global_load_lds_dwordx4 v[228:229], off
	v_lshl_add_u64 v[228:229], v[230:231], 0, s[34:35]
	s_add_i32 m0, s38, 0x2000
	s_add_i32 s38, vcc_hi, s51
	global_load_lds_dwordx4 v[228:229], off
	v_lshl_add_u64 v[228:229], v[232:233], 0, s[34:35]
	s_mov_b32 m0, s38
	s_nop 0
	global_load_lds_dwordx4 v[228:229], off
	v_lshl_add_u64 v[228:229], v[234:235], 0, s[34:35]
	s_add_i32 m0, s38, 0x2000
	s_nop 0
	global_load_lds_dwordx4 v[228:229], off
	v_lshl_add_u64 v[228:229], v[236:237], 0, s[34:35]
	s_mov_b32 m0, s90
	s_nop 0
	global_load_lds_dwordx4 v[228:229], off
	v_lshl_add_u64 v[228:229], v[238:239], 0, s[34:35]
	s_mov_b32 m0, s91
	s_nop 0
	global_load_lds_dwordx4 v[228:229], off
	s_waitcnt vmcnt(8)
	s_waitcnt lgkmcnt(0)
	s_barrier
	v_mfma_f32_16x16x32_bf16 v[62:65], v[142:145], v[196:199], v[62:65]
	v_mfma_f32_16x16x32_bf16 v[58:61], v[154:157], v[196:199], v[58:61]
	v_mfma_f32_16x16x32_bf16 v[46:49], v[142:145], v[204:207], v[46:49]
	v_mfma_f32_16x16x32_bf16 v[42:45], v[154:157], v[204:207], v[42:45]
	v_mfma_f32_16x16x32_bf16 v[28:31], v[142:145], v[212:215], v[28:31]
	v_mfma_f32_16x16x32_bf16 v[24:27], v[154:157], v[212:215], v[24:27]
	v_mfma_f32_16x16x32_bf16 v[12:15], v[142:145], v[220:223], v[12:15]
	v_mfma_f32_16x16x32_bf16 v[8:11], v[154:157], v[220:223], v[8:11]
	v_mfma_f32_16x16x32_bf16 v[62:65], v[150:153], v[200:203], v[62:65]
	v_mfma_f32_16x16x32_bf16 v[58:61], v[158:161], v[200:203], v[58:61]
	v_mfma_f32_16x16x32_bf16 v[46:49], v[150:153], v[208:211], v[46:49]
	v_mfma_f32_16x16x32_bf16 v[42:45], v[158:161], v[208:211], v[42:45]
	v_mfma_f32_16x16x32_bf16 v[28:31], v[150:153], v[216:219], v[28:31]
	v_mfma_f32_16x16x32_bf16 v[24:27], v[158:161], v[216:219], v[24:27]
	v_mfma_f32_16x16x32_bf16 v[12:15], v[150:153], v[224:227], v[12:15]
	v_mfma_f32_16x16x32_bf16 v[8:11], v[158:161], v[224:227], v[8:11]
	v_mfma_f32_16x16x32_bf16 v[54:57], v[170:173], v[196:199], v[54:57]
	v_mfma_f32_16x16x32_bf16 v[50:53], v[178:181], v[196:199], v[50:53]
	v_mfma_f32_16x16x32_bf16 v[38:41], v[170:173], v[204:207], v[38:41]
	v_mfma_f32_16x16x32_bf16 v[34:37], v[178:181], v[204:207], v[34:37]
	v_mfma_f32_16x16x32_bf16 v[20:23], v[170:173], v[212:215], v[20:23]
	v_mfma_f32_16x16x32_bf16 v[16:19], v[178:181], v[212:215], v[16:19]
	v_mfma_f32_16x16x32_bf16 v[4:7], v[170:173], v[220:223], v[4:7]
	v_mfma_f32_16x16x32_bf16 v[0:3], v[178:181], v[220:223], v[0:3]
	v_mfma_f32_16x16x32_bf16 v[54:57], v[174:177], v[200:203], v[54:57]
	v_mfma_f32_16x16x32_bf16 v[50:53], v[182:185], v[200:203], v[50:53]
	v_mfma_f32_16x16x32_bf16 v[38:41], v[174:177], v[208:211], v[38:41]
	v_mfma_f32_16x16x32_bf16 v[34:37], v[182:185], v[208:211], v[34:37]
	v_mfma_f32_16x16x32_bf16 v[20:23], v[174:177], v[216:219], v[20:23]
	v_mfma_f32_16x16x32_bf16 v[16:19], v[182:185], v[216:219], v[16:19]
	v_mfma_f32_16x16x32_bf16 v[4:7], v[174:177], v[224:227], v[4:7]
	v_mfma_f32_16x16x32_bf16 v[0:3], v[182:185], v[224:227], v[0:3]
	s_barrier
	s_add_u32 s48, s48, 0x100
	s_addc_u32 s49, s49, 0
	s_add_u32 s44, s44, 0x100
	s_addc_u32 s45, s45, 0
	s_cmp_ge_u32 vcc_lo, s85
	s_mov_b32 s46, vcc_lo
	s_cbranch_scc0 .LBB0_411
	s_and_b64 vcc, exec, s[42:43]
	s_cbranch_vccz .LBB0_414
	s_barrier

; #define PG8_STAGE(bufoff, gbase, voff) do { _Pragma("unroll") for (int _i = 0; _i < 2; ++_i) \
;         __builtin_amdgcn_global_load_lds((const unsigned*)((const char*)(gbase) + (voff)[_i]), (PG8_LAS unsigned*)(lds + (bufoff) + ldsw + _i * 8192), 16, 0, 0); } while (0)
; #define PG8_LDA(dst, b, h) do { _Pragma("unroll") for (int m = 0; m < 4; ++m) _Pragma("unroll") for (int k = 0; k < 2; ++k) dst[m][k] = *(const PG8_LAS bf16x8*)(lds + PG8_SA(b, h) + aoff + m * 2048 + k * 1024); } while (0)
; #define PG8_LDB(dst, b, h) do { _Pragma("unroll") for (int n = 0; n < 2; ++n) _Pragma("unroll") for (int k = 0; k < 2; ++k) dst[n][k] = *(const PG8_LAS bf16x8*)(lds + PG8_SB(b, h) + boff + n * 2048 + k * 1024); } while (0)
; #define PG8_MMA(ai, bj, At, Bt) do { __builtin_amdgcn_s_setprio(1); _Pragma("unroll") for (int m = 0; m < 4; ++m) _Pragma("unroll") for (int n = 0; n < 2; ++n) _Pragma("unroll") for (int k = 0; k < 2; ++k) \
;         acc[ai][bj][m][n] = __builtin_amdgcn_mfma_f32_16x16x32_bf16(Bt[n][k], At[m][k], acc[ai][bj][m][n], 0, 0, 0); __builtin_amdgcn_s_setprio(0); } while (0)
; #define PG8_WAIT_V(n) asm volatile("s_waitcnt vmcnt(" #n ")" ::: "memory")
; #define PG8_WAIT_L(n) asm volatile("s_waitcnt lgkmcnt(" #n ")" ::: "memory")
; template <class Epi, class Sched, bool ALIGN_EPI = false, bool SP2 = false>
; __device__ __forceinline__ void gemm_phase(PG8_LAS unsigned char* lds, const Gemm g, const Sched& S, const Epi& E) {
;     ...
;             const bool last = (t == nt - 2);
;             const char* a1 = cA + (size_t)(t + 1) * kstep;
;             const char* a2 = last ? nA : cA + (size_t)(t + 2) * kstep; const char* b2 = last ? nB : cB + (size_t)(t + 2) * kstep;
;             const char* a3 = a2 + kstep; const char* b3 = b2 + kstep;
;             if (last && has_next) S.a_ready(nxt);
;             if constexpr (SP2) {
;             PG8_LDB(B0, 0, 0); PG8_LDB(B1, 0, 1); PG8_SCHED; PG8_LDA(At, 0, 0); PG8_STAGE(PG8_SA(1, 1), a1 + hstep, voffA);
;             PG8_WAIT_V(8); PG8_WAIT_L(0); PG8_BAR; PG8_MMA(0, 0, At, B0); PG8_MMA(0, 1, At, B1); PG8_BAR; PG8_SCHED;
;             PG8_LDA(At, 0, 1); PG8_STAGE(PG8_SB(0, 0), b2, voffB); PG8_STAGE(PG8_SB(0, 1), b2 + hstep, voffB); PG8_STAGE(PG8_SA(0, 0), a2, voffA);
;             PG8_WAIT_V(8); PG8_WAIT_L(0); PG8_BAR; PG8_MMA(1, 0, At, B0); PG8_MMA(1, 1, At, B1); PG8_BAR; PG8_SCHED;
.LBB0_444:
	s_add_u32 s38, s48, 0xfffc0080
	s_addc_u32 s39, s49, -1
	s_add_i32 s61, 0, 0x10000
	s_cmp_eq_u32 vcc_hi, 12
	s_cselect_b32 s83, s43, s39
	s_cselect_b32 s82, s45, s38
	v_add_u32_e32 v151, s61, v145
	s_cselect_b32 s51, s41, vcc_lo
	s_cselect_b32 s50, s96, s97
	s_add_i32 s72, 0, 0x14000
	ds_read_b128 v[170:173], v151
	ds_read_b128 v[174:177], v151 offset:1024
	ds_read_b128 v[178:181], v151 offset:2048
	ds_read_b128 v[182:185], v151 offset:3072
	v_add_u32_e32 v151, s72, v145
	ds_read_b128 v[196:199], v151
	ds_read_b128 v[200:203], v151 offset:1024
	ds_read_b128 v[204:207], v151 offset:2048
	ds_read_b128 v[208:211], v151 offset:3072
	s_add_i32 m0, s47, 0xc000
	ds_read_b128 v[212:215], v149
	ds_read_b128 v[216:219], v149 offset:1024
	ds_read_b128 v[220:223], v149 offset:2048
	ds_read_b128 v[224:227], v149 offset:3072
	ds_read_b128 v[228:231], v149 offset:4096
	ds_read_b128 v[232:235], v149 offset:5120
	ds_read_b128 v[236:239], v149 offset:6144
	ds_read_b128 v[240:243], v149 offset:7168
	global_load_lds_dwordx4 v142, s[48:49]
	s_add_i32 m0, s47, 0xe000
	s_nop 0
	global_load_lds_dwordx4 v140, s[48:49]
	s_waitcnt vmcnt(8)
	s_waitcnt lgkmcnt(0)
	s_barrier
	v_mfma_f32_16x16x32_bf16 v[126:129], v[170:173], v[212:215], v[126:129]
	v_mfma_f32_16x16x32_bf16 v[122:125], v[178:181], v[212:215], v[122:125]
	v_mfma_f32_16x16x32_bf16 v[110:113], v[170:173], v[220:223], v[110:113]
	v_mfma_f32_16x16x32_bf16 v[106:109], v[178:181], v[220:223], v[106:109]
	v_mfma_f32_16x16x32_bf16 v[94:97], v[170:173], v[228:231], v[94:97]
	v_mfma_f32_16x16x32_bf16 v[90:93], v[178:181], v[228:231], v[90:93]
	v_mfma_f32_16x16x32_bf16 v[78:81], v[170:173], v[236:239], v[78:81]
	v_mfma_f32_16x16x32_bf16 v[74:77], v[178:181], v[236:239], v[74:77]
	v_mfma_f32_16x16x32_bf16 v[126:129], v[174:177], v[216:219], v[126:129]
	v_mfma_f32_16x16x32_bf16 v[122:125], v[182:185], v[216:219], v[122:125]
	v_mfma_f32_16x16x32_bf16 v[110:113], v[174:177], v[224:227], v[110:113]
	v_mfma_f32_16x16x32_bf16 v[106:109], v[182:185], v[224:227], v[106:109]
	v_mfma_f32_16x16x32_bf16 v[94:97], v[174:177], v[232:235], v[94:97]
	v_mfma_f32_16x16x32_bf16 v[90:93], v[182:185], v[232:235], v[90:93]
	v_mfma_f32_16x16x32_bf16 v[78:81], v[174:177], v[240:243], v[78:81]
	v_mfma_f32_16x16x32_bf16 v[74:77], v[182:185], v[240:243], v[74:77]
	v_mfma_f32_16x16x32_bf16 v[118:121], v[196:199], v[212:215], v[118:121]
	v_mfma_f32_16x16x32_bf16 v[114:117], v[204:207], v[212:215], v[114:117]
	v_mfma_f32_16x16x32_bf16 v[102:105], v[196:199], v[220:223], v[102:105]
	v_mfma_f32_16x16x32_bf16 v[98:101], v[204:207], v[220:223], v[98:101]
	v_mfma_f32_16x16x32_bf16 v[86:89], v[196:199], v[228:231], v[86:89]
	v_mfma_f32_16x16x32_bf16 v[82:85], v[204:207], v[228:231], v[82:85]
	v_mfma_f32_16x16x32_bf16 v[70:73], v[196:199], v[236:239], v[70:73]
	v_mfma_f32_16x16x32_bf16 v[66:69], v[204:207], v[236:239], v[66:69]
	v_mfma_f32_16x16x32_bf16 v[118:121], v[200:203], v[216:219], v[118:121]
	v_mfma_f32_16x16x32_bf16 v[114:117], v[208:211], v[216:219], v[114:117]
	v_mfma_f32_16x16x32_bf16 v[102:105], v[200:203], v[224:227], v[102:105]
	v_mfma_f32_16x16x32_bf16 v[98:101], v[208:211], v[224:227], v[98:101]
	v_mfma_f32_16x16x32_bf16 v[86:89], v[200:203], v[232:235], v[86:89]
	v_mfma_f32_16x16x32_bf16 v[82:85], v[208:211], v[232:235], v[82:85]
	v_mfma_f32_16x16x32_bf16 v[70:73], v[200:203], v[240:243], v[70:73]
	v_mfma_f32_16x16x32_bf16 v[66:69], v[208:211], v[240:243], v[66:69]
	s_barrier
	s_add_i32 s38, s61, s89
	v_lshl_add_u64 v[160:161], s[50:51], 0, v[134:135]
	s_mov_b32 m0, s38
	ds_read_b128 v[212:215], v149 offset:16384
	ds_read_b128 v[216:219], v149 offset:17408
	ds_read_b128 v[220:223], v149 offset:18432
	ds_read_b128 v[224:227], v149 offset:19456
	ds_read_b128 v[228:231], v149 offset:20480
	ds_read_b128 v[232:235], v149 offset:21504
	ds_read_b128 v[236:239], v149 offset:22528
	ds_read_b128 v[240:243], v149 offset:23552
	global_load_lds_dwordx4 v[160:161], off
	s_add_i32 m0, s38, 0x2000
	s_add_u32 s38, s50, 0x40000
	v_lshl_add_u64 v[244:245], s[50:51], 0, v[130:131]
	s_addc_u32 s39, s51, 0
	s_add_i32 s61, s72, s89
	global_load_lds_dwordx4 v[244:245], off
	s_mov_b32 m0, s61
	v_lshl_add_u64 v[248:249], s[82:83], 0, v[132:133]
	global_load_lds_dwordx4 v134, s[38:39]
	s_add_i32 m0, s61, 0x2000
	s_nop 0
	global_load_lds_dwordx4 v130, s[38:39]
	v_lshl_add_u64 v[246:247], s[82:83], 0, v[136:137]
	s_mov_b32 m0, s47
	s_nop 0
	global_load_lds_dwordx4 v[246:247], off
	s_mov_b32 m0, s90
	s_nop 0
	global_load_lds_dwordx4 v[248:249], off
	s_waitcnt vmcnt(8)
	s_waitcnt lgkmcnt(0)
	s_barrier
; #define PG8_STAGE(bufoff, gbase, voff) do { _Pragma("unroll") for (int _i = 0; _i < 2; ++_i) \
;         __builtin_amdgcn_global_load_lds((const unsigned*)((const char*)(gbase) + (voff)[_i]), (PG8_LAS unsigned*)(lds + (bufoff) + ldsw + _i * 8192), 16, 0, 0); } while (0)
; #define PG8_LDA(dst, b, h) do { _Pragma("unroll") for (int m = 0; m < 4; ++m) _Pragma("unroll") for (int k = 0; k < 2; ++k) dst[m][k] = *(const PG8_LAS bf16x8*)(lds + PG8_SA(b, h) + aoff + m * 2048 + k * 1024); } while (0)
; #define PG8_LDB(dst, b, h) do { _Pragma("unroll") for (int n = 0; n < 2; ++n) _Pragma("unroll") for (int k = 0; k < 2; ++k) dst[n][k] = *(const PG8_LAS bf16x8*)(lds + PG8_SB(b, h) + boff + n * 2048 + k * 1024); } while (0)
; #define PG8_MMA(ai, bj, At, Bt) do { __builtin_amdgcn_s_setprio(1); _Pragma("unroll") for (int m = 0; m < 4; ++m) _Pragma("unroll") for (int n = 0; n < 2; ++n) _Pragma("unroll") for (int k = 0; k < 2; ++k) \
;         acc[ai][bj][m][n] = __builtin_amdgcn_mfma_f32_16x16x32_bf16(Bt[n][k], At[m][k], acc[ai][bj][m][n], 0, 0, 0); __builtin_amdgcn_s_setprio(0); } while (0)
; #define PG8_WAIT_V(n) asm volatile("s_waitcnt vmcnt(" #n ")" ::: "memory")
; #define PG8_WAIT_L(n) asm volatile("s_waitcnt lgkmcnt(" #n ")" ::: "memory")
; #define PG8_BAR __builtin_amdgcn_s_barrier()
; #define PG8_SCHED __builtin_amdgcn_sched_barrier(0)
; template <class Epi, class Sched, bool ALIGN_EPI = false, bool SP2 = false>
; __device__ __forceinline__ void gemm_phase(PG8_LAS unsigned char* lds, const Gemm g, const Sched& S, const Epi& E) {
;     ...
;             PG8_WAIT_V(8); PG8_WAIT_L(0); PG8_BAR; PG8_MMA(1, 0, At, B0); PG8_MMA(1, 1, At, B1); PG8_BAR; PG8_SCHED;
;             PG8_LDB(B0, 1, 0); PG8_LDB(B1, 1, 1); PG8_SCHED; PG8_LDA(At, 1, 0); PG8_STAGE(PG8_SA(0, 1), a2 + hstep, voffA);
;             PG8_WAIT_V(8); PG8_WAIT_L(0); PG8_BAR; PG8_MMA(0, 0, At, B0); PG8_MMA(0, 1, At, B1); PG8_BAR; PG8_SCHED;
	v_mfma_f32_16x16x32_bf16 v[62:65], v[170:173], v[212:215], v[62:65]
	v_mfma_f32_16x16x32_bf16 v[58:61], v[178:181], v[212:215], v[58:61]
	v_mfma_f32_16x16x32_bf16 v[46:49], v[170:173], v[220:223], v[46:49]
	v_mfma_f32_16x16x32_bf16 v[42:45], v[178:181], v[220:223], v[42:45]
	v_mfma_f32_16x16x32_bf16 v[28:31], v[170:173], v[228:231], v[28:31]
	v_mfma_f32_16x16x32_bf16 v[24:27], v[178:181], v[228:231], v[24:27]
	v_mfma_f32_16x16x32_bf16 v[12:15], v[170:173], v[236:239], v[12:15]
	v_mfma_f32_16x16x32_bf16 v[8:11], v[178:181], v[236:239], v[8:11]
	v_mfma_f32_16x16x32_bf16 v[62:65], v[174:177], v[216:219], v[62:65]
	v_mfma_f32_16x16x32_bf16 v[58:61], v[182:185], v[216:219], v[58:61]
	v_mfma_f32_16x16x32_bf16 v[46:49], v[174:177], v[224:227], v[46:49]
	v_mfma_f32_16x16x32_bf16 v[42:45], v[182:185], v[224:227], v[42:45]
	v_mfma_f32_16x16x32_bf16 v[28:31], v[174:177], v[232:235], v[28:31]
	v_mfma_f32_16x16x32_bf16 v[24:27], v[182:185], v[232:235], v[24:27]
	v_mfma_f32_16x16x32_bf16 v[12:15], v[174:177], v[240:243], v[12:15]
	v_mfma_f32_16x16x32_bf16 v[8:11], v[182:185], v[240:243], v[8:11]
	v_mfma_f32_16x16x32_bf16 v[54:57], v[196:199], v[212:215], v[54:57]
	v_mfma_f32_16x16x32_bf16 v[50:53], v[204:207], v[212:215], v[50:53]
	v_mfma_f32_16x16x32_bf16 v[38:41], v[196:199], v[220:223], v[38:41]
	v_mfma_f32_16x16x32_bf16 v[34:37], v[204:207], v[220:223], v[34:37]
	v_mfma_f32_16x16x32_bf16 v[20:23], v[196:199], v[228:231], v[20:23]
	v_mfma_f32_16x16x32_bf16 v[16:19], v[204:207], v[228:231], v[16:19]
	v_mfma_f32_16x16x32_bf16 v[4:7], v[196:199], v[236:239], v[4:7]
	v_mfma_f32_16x16x32_bf16 v[0:3], v[204:207], v[236:239], v[0:3]
	v_mfma_f32_16x16x32_bf16 v[54:57], v[200:203], v[216:219], v[54:57]
	v_mfma_f32_16x16x32_bf16 v[50:53], v[208:211], v[216:219], v[50:53]
	v_mfma_f32_16x16x32_bf16 v[38:41], v[200:203], v[224:227], v[38:41]
	v_mfma_f32_16x16x32_bf16 v[34:37], v[208:211], v[224:227], v[34:37]
	v_mfma_f32_16x16x32_bf16 v[20:23], v[200:203], v[232:235], v[20:23]
	v_mfma_f32_16x16x32_bf16 v[16:19], v[208:211], v[232:235], v[16:19]
	v_mfma_f32_16x16x32_bf16 v[4:7], v[200:203], v[240:243], v[4:7]
	v_mfma_f32_16x16x32_bf16 v[0:3], v[208:211], v[240:243], v[0:3]
	s_barrier
	s_add_i32 s61, 0, 0x18000
	v_add_u32_e32 v151, s61, v145
	s_add_i32 s72, 0, 0x1c000
	ds_read_b128 v[170:173], v151
	ds_read_b128 v[174:177], v151 offset:1024
	ds_read_b128 v[178:181], v151 offset:2048
	ds_read_b128 v[182:185], v151 offset:3072
	v_add_u32_e32 v151, s72, v145
	ds_read_b128 v[196:199], v151
	ds_read_b128 v[200:203], v151 offset:1024
	ds_read_b128 v[204:207], v151 offset:2048
	ds_read_b128 v[208:211], v151 offset:3072
	s_add_u32 s38, s82, 0x40000
	s_addc_u32 s39, s83, 0
	s_mov_b32 m0, s91
	ds_read_b128 v[212:215], v149 offset:32768
	ds_read_b128 v[216:219], v149 offset:33792
	ds_read_b128 v[220:223], v149 offset:34816
	ds_read_b128 v[224:227], v149 offset:35840
	ds_read_b128 v[228:231], v149 offset:36864
	ds_read_b128 v[232:235], v149 offset:37888
	ds_read_b128 v[236:239], v149 offset:38912
	ds_read_b128 v[240:243], v149 offset:39936
	global_load_lds_dwordx4 v136, s[38:39]
	s_mov_b32 m0, s92
	s_nop 0
	global_load_lds_dwordx4 v132, s[38:39]
	s_waitcnt vmcnt(8)
	s_waitcnt lgkmcnt(0)
	s_barrier
	v_mfma_f32_16x16x32_bf16 v[126:129], v[170:173], v[212:215], v[126:129]
	v_mfma_f32_16x16x32_bf16 v[122:125], v[178:181], v[212:215], v[122:125]
	v_mfma_f32_16x16x32_bf16 v[110:113], v[170:173], v[220:223], v[110:113]
	v_mfma_f32_16x16x32_bf16 v[106:109], v[178:181], v[220:223], v[106:109]
	v_mfma_f32_16x16x32_bf16 v[94:97], v[170:173], v[228:231], v[94:97]
	v_mfma_f32_16x16x32_bf16 v[90:93], v[178:181], v[228:231], v[90:93]
	v_mfma_f32_16x16x32_bf16 v[78:81], v[170:173], v[236:239], v[78:81]
	v_mfma_f32_16x16x32_bf16 v[74:77], v[178:181], v[236:239], v[74:77]
	v_mfma_f32_16x16x32_bf16 v[126:129], v[174:177], v[216:219], v[126:129]
	v_mfma_f32_16x16x32_bf16 v[122:125], v[182:185], v[216:219], v[122:125]
	v_mfma_f32_16x16x32_bf16 v[110:113], v[174:177], v[224:227], v[110:113]
	v_mfma_f32_16x16x32_bf16 v[106:109], v[182:185], v[224:227], v[106:109]
	v_mfma_f32_16x16x32_bf16 v[94:97], v[174:177], v[232:235], v[94:97]
	v_mfma_f32_16x16x32_bf16 v[90:93], v[182:185], v[232:235], v[90:93]
	v_mfma_f32_16x16x32_bf16 v[78:81], v[174:177], v[240:243], v[78:81]
	v_mfma_f32_16x16x32_bf16 v[74:77], v[182:185], v[240:243], v[74:77]
	v_mfma_f32_16x16x32_bf16 v[118:121], v[196:199], v[212:215], v[118:121]
	v_mfma_f32_16x16x32_bf16 v[114:117], v[204:207], v[212:215], v[114:117]
	v_mfma_f32_16x16x32_bf16 v[102:105], v[196:199], v[220:223], v[102:105]
	v_mfma_f32_16x16x32_bf16 v[98:101], v[204:207], v[220:223], v[98:101]
	v_mfma_f32_16x16x32_bf16 v[86:89], v[196:199], v[228:231], v[86:89]
	v_mfma_f32_16x16x32_bf16 v[82:85], v[204:207], v[228:231], v[82:85]
	v_mfma_f32_16x16x32_bf16 v[70:73], v[196:199], v[236:239], v[70:73]
	v_mfma_f32_16x16x32_bf16 v[66:69], v[204:207], v[236:239], v[66:69]
	v_mfma_f32_16x16x32_bf16 v[118:121], v[200:203], v[216:219], v[118:121]
	v_mfma_f32_16x16x32_bf16 v[114:117], v[208:211], v[216:219], v[114:117]
	v_mfma_f32_16x16x32_bf16 v[102:105], v[200:203], v[224:227], v[102:105]
	v_mfma_f32_16x16x32_bf16 v[98:101], v[208:211], v[224:227], v[98:101]
	v_mfma_f32_16x16x32_bf16 v[86:89], v[200:203], v[232:235], v[86:89]
	v_mfma_f32_16x16x32_bf16 v[82:85], v[208:211], v[232:235], v[82:85]
	v_mfma_f32_16x16x32_bf16 v[70:73], v[200:203], v[240:243], v[70:73]
	v_mfma_f32_16x16x32_bf16 v[66:69], v[208:211], v[240:243], v[66:69]
	s_barrier
; #define PG8_STAGE(bufoff, gbase, voff) do { _Pragma("unroll") for (int _i = 0; _i < 2; ++_i) \
;         __builtin_amdgcn_global_load_lds((const unsigned*)((const char*)(gbase) + (voff)[_i]), (PG8_LAS unsigned*)(lds + (bufoff) + ldsw + _i * 8192), 16, 0, 0); } while (0)
; #define PG8_LDA(dst, b, h) do { _Pragma("unroll") for (int m = 0; m < 4; ++m) _Pragma("unroll") for (int k = 0; k < 2; ++k) dst[m][k] = *(const PG8_LAS bf16x8*)(lds + PG8_SA(b, h) + aoff + m * 2048 + k * 1024); } while (0)
; #define PG8_MMA(ai, bj, At, Bt) do { __builtin_amdgcn_s_setprio(1); _Pragma("unroll") for (int m = 0; m < 4; ++m) _Pragma("unroll") for (int n = 0; n < 2; ++n) _Pragma("unroll") for (int k = 0; k < 2; ++k) \
;         acc[ai][bj][m][n] = __builtin_amdgcn_mfma_f32_16x16x32_bf16(Bt[n][k], At[m][k], acc[ai][bj][m][n], 0, 0, 0); __builtin_amdgcn_s_setprio(0); } while (0)
; #define PG8_WAIT_V(n) asm volatile("s_waitcnt vmcnt(" #n ")" ::: "memory")
; #define PG8_WAIT_L(n) asm volatile("s_waitcnt lgkmcnt(" #n ")" ::: "memory")
; #define PG8_BAR __builtin_amdgcn_s_barrier()
; #define PG8_SCHED __builtin_amdgcn_sched_barrier(0)
; template <class Epi, class Sched, bool ALIGN_EPI = false, bool SP2 = false>
; __device__ __forceinline__ void gemm_phase(PG8_LAS unsigned char* lds, const Gemm g, const Sched& S, const Epi& E) {
;     ...
;             PG8_LDA(At, 1, 1); PG8_STAGE(PG8_SB(1, 0), b3, voffB); PG8_STAGE(PG8_SB(1, 1), b3 + hstep, voffB); PG8_STAGE(PG8_SA(1, 0), a3, voffA);
;             PG8_WAIT_V(8); PG8_WAIT_L(0); PG8_BAR; PG8_MMA(1, 0, At, B0); PG8_MMA(1, 1, At, B1); PG8_BAR; PG8_SCHED;
;     ...
;         if constexpr (ALIGN_EPI) { if (wr == 0) PG8_BAR; }
	s_add_i32 s38, s61, s89
	v_lshl_add_u64 v[160:161], v[160:161], 0, s[34:35]
	s_mov_b32 m0, s38
	ds_read_b128 v[212:215], v149 offset:49152
	ds_read_b128 v[216:219], v149 offset:50176
	ds_read_b128 v[220:223], v149 offset:51200
	ds_read_b128 v[224:227], v149 offset:52224
	ds_read_b128 v[228:231], v149 offset:53248
	ds_read_b128 v[232:235], v149 offset:54272
	ds_read_b128 v[236:239], v149 offset:55296
	ds_read_b128 v[240:243], v149 offset:56320
	global_load_lds_dwordx4 v[160:161], off
	s_add_i32 m0, s38, 0x2000
	s_add_u32 s38, s50, 0x40080
	v_lshl_add_u64 v[160:161], v[244:245], 0, s[34:35]
	s_addc_u32 s39, s51, 0
	s_add_i32 s50, s72, s89
	global_load_lds_dwordx4 v[160:161], off
	s_mov_b32 m0, s50
	s_nop 0
	global_load_lds_dwordx4 v134, s[38:39]
	s_add_i32 m0, s50, 0x2000
	s_nop 0
	global_load_lds_dwordx4 v130, s[38:39]
	v_lshl_add_u64 v[160:161], v[246:247], 0, s[34:35]
	s_mov_b32 m0, s93
	s_nop 0
	global_load_lds_dwordx4 v[160:161], off
	v_lshl_add_u64 v[160:161], v[248:249], 0, s[34:35]
	s_mov_b32 m0, s94
	s_nop 0
	global_load_lds_dwordx4 v[160:161], off
	s_waitcnt vmcnt(8)
	s_waitcnt lgkmcnt(0)
	s_barrier
	v_mfma_f32_16x16x32_bf16 v[62:65], v[170:173], v[212:215], v[62:65]
	v_mfma_f32_16x16x32_bf16 v[58:61], v[178:181], v[212:215], v[58:61]
	v_mfma_f32_16x16x32_bf16 v[46:49], v[170:173], v[220:223], v[46:49]
	v_mfma_f32_16x16x32_bf16 v[42:45], v[178:181], v[220:223], v[42:45]
	v_mfma_f32_16x16x32_bf16 v[28:31], v[170:173], v[228:231], v[28:31]
	v_mfma_f32_16x16x32_bf16 v[24:27], v[178:181], v[228:231], v[24:27]
	v_mfma_f32_16x16x32_bf16 v[12:15], v[170:173], v[236:239], v[12:15]
	v_mfma_f32_16x16x32_bf16 v[8:11], v[178:181], v[236:239], v[8:11]
	v_mfma_f32_16x16x32_bf16 v[62:65], v[174:177], v[216:219], v[62:65]
	v_mfma_f32_16x16x32_bf16 v[58:61], v[182:185], v[216:219], v[58:61]
	v_mfma_f32_16x16x32_bf16 v[46:49], v[174:177], v[224:227], v[46:49]
	v_mfma_f32_16x16x32_bf16 v[42:45], v[182:185], v[224:227], v[42:45]
	v_mfma_f32_16x16x32_bf16 v[28:31], v[174:177], v[232:235], v[28:31]
	v_mfma_f32_16x16x32_bf16 v[24:27], v[182:185], v[232:235], v[24:27]
	v_mfma_f32_16x16x32_bf16 v[12:15], v[174:177], v[240:243], v[12:15]
	v_mfma_f32_16x16x32_bf16 v[8:11], v[182:185], v[240:243], v[8:11]
	v_mfma_f32_16x16x32_bf16 v[54:57], v[196:199], v[212:215], v[54:57]
	v_mfma_f32_16x16x32_bf16 v[50:53], v[204:207], v[212:215], v[50:53]
	v_mfma_f32_16x16x32_bf16 v[38:41], v[196:199], v[220:223], v[38:41]
	v_mfma_f32_16x16x32_bf16 v[34:37], v[204:207], v[220:223], v[34:37]
	v_mfma_f32_16x16x32_bf16 v[20:23], v[196:199], v[228:231], v[20:23]
	v_mfma_f32_16x16x32_bf16 v[16:19], v[204:207], v[228:231], v[16:19]
	v_mfma_f32_16x16x32_bf16 v[4:7], v[196:199], v[236:239], v[4:7]
	v_mfma_f32_16x16x32_bf16 v[0:3], v[204:207], v[236:239], v[0:3]
	v_mfma_f32_16x16x32_bf16 v[54:57], v[200:203], v[216:219], v[54:57]
	v_mfma_f32_16x16x32_bf16 v[50:53], v[208:211], v[216:219], v[50:53]
	v_mfma_f32_16x16x32_bf16 v[38:41], v[200:203], v[224:227], v[38:41]
	v_mfma_f32_16x16x32_bf16 v[34:37], v[208:211], v[224:227], v[34:37]
	v_mfma_f32_16x16x32_bf16 v[20:23], v[200:203], v[232:235], v[20:23]
	v_mfma_f32_16x16x32_bf16 v[16:19], v[208:211], v[232:235], v[16:19]
	v_mfma_f32_16x16x32_bf16 v[4:7], v[200:203], v[240:243], v[4:7]
	v_mfma_f32_16x16x32_bf16 v[0:3], v[208:211], v[240:243], v[0:3]
	s_barrier
	s_add_i32 vcc_hi, vcc_hi, 2
	s_add_u32 s97, s97, 0x100
	s_addc_u32 vcc_lo, vcc_lo, 0
	s_add_u32 s48, s48, 0x100
	s_addc_u32 s49, s49, 0
	s_cmp_gt_u32 vcc_hi, 13
	s_cbranch_scc0 .LBB0_444
	s_and_b64 vcc, exec, s[4:5]
	s_cbranch_vccz .LBB0_447
	s_barrier

; #define PG8_STAGE(bufoff, gbase, voff) do { _Pragma("unroll") for (int _i = 0; _i < 2; ++_i) \
;         __builtin_amdgcn_global_load_lds((const unsigned*)((const char*)(gbase) + (voff)[_i]), (PG8_LAS unsigned*)(lds + (bufoff) + ldsw + _i * 8192), 16, 0, 0); } while (0)
; #define PG8_LDA(dst, b, h) do { _Pragma("unroll") for (int m = 0; m < 4; ++m) _Pragma("unroll") for (int k = 0; k < 2; ++k) dst[m][k] = *(const PG8_LAS bf16x8*)(lds + PG8_SA(b, h) + aoff + m * 2048 + k * 1024); } while (0)
; #define PG8_LDB(dst, b, h) do { _Pragma("unroll") for (int n = 0; n < 2; ++n) _Pragma("unroll") for (int k = 0; k < 2; ++k) dst[n][k] = *(const PG8_LAS bf16x8*)(lds + PG8_SB(b, h) + boff + n * 2048 + k * 1024); } while (0)
; #define PG8_MMA(ai, bj, At, Bt) do { __builtin_amdgcn_s_setprio(1); _Pragma("unroll") for (int m = 0; m < 4; ++m) _Pragma("unroll") for (int n = 0; n < 2; ++n) _Pragma("unroll") for (int k = 0; k < 2; ++k) \
;         acc[ai][bj][m][n] = __builtin_amdgcn_mfma_f32_16x16x32_bf16(Bt[n][k], At[m][k], acc[ai][bj][m][n], 0, 0, 0); __builtin_amdgcn_s_setprio(0); } while (0)
; #define PG8_WAIT_V(n) asm volatile("s_waitcnt vmcnt(" #n ")" ::: "memory")
; #define PG8_WAIT_L(n) asm volatile("s_waitcnt lgkmcnt(" #n ")" ::: "memory")
; template <class Epi, class Sched, bool ALIGN_EPI = false, bool SP2 = false>
; __device__ __forceinline__ void gemm_phase(PG8_LAS unsigned char* lds, const Gemm g, const Sched& S, const Epi& E) {
;     ...
;             const bool last = (t == nt - 2);
;             const char* a1 = cA + (size_t)(t + 1) * kstep;
;             const char* a2 = last ? nA : cA + (size_t)(t + 2) * kstep; const char* b2 = last ? nB : cB + (size_t)(t + 2) * kstep;
;             const char* a3 = a2 + kstep; const char* b3 = b2 + kstep;
;             if (last && has_next) S.a_ready(nxt);
;             if constexpr (SP2) {
;             PG8_LDB(B0, 0, 0); PG8_LDB(B1, 0, 1); PG8_SCHED; PG8_LDA(At, 0, 0); PG8_STAGE(PG8_SA(1, 1), a1 + hstep, voffA);
;             PG8_WAIT_V(8); PG8_WAIT_L(0); PG8_BAR; PG8_MMA(0, 0, At, B0); PG8_MMA(0, 1, At, B1); PG8_BAR; PG8_SCHED;
;             PG8_LDA(At, 0, 1); PG8_STAGE(PG8_SB(0, 0), b2, voffB); PG8_STAGE(PG8_SB(0, 1), b2 + hstep, voffB); PG8_STAGE(PG8_SA(0, 0), a2, voffA);
;             PG8_WAIT_V(8); PG8_WAIT_L(0); PG8_BAR; PG8_MMA(1, 0, At, B0); PG8_MMA(1, 1, At, B1); PG8_BAR; PG8_SCHED;
.LBB0_546:
	s_add_i32 s48, s46, 2
	s_add_u32 s49, s44, 0x80
	s_addc_u32 s47, s45, 0
	s_add_i32 s61, 0, 0x10000
	s_cmp_eq_u32 s87, s46
	s_cselect_b32 s47, s43, s47
	s_cselect_b32 s46, s42, s49
	v_add_u32_e32 v149, s61, v146
	s_cselect_b32 s93, s77, s9
	s_cselect_b32 s92, s76, s0
	s_add_i32 s49, 0, 0x14000
	ds_read_b128 v[142:145], v149
	ds_read_b128 v[150:153], v149 offset:1024
	ds_read_b128 v[154:157], v149 offset:2048
	ds_read_b128 v[158:161], v149 offset:3072
	v_add_u32_e32 v149, s49, v146
	ds_read_b128 v[170:173], v149
	ds_read_b128 v[174:177], v149 offset:1024
	ds_read_b128 v[178:181], v149 offset:2048
	ds_read_b128 v[182:185], v149 offset:3072
	s_add_i32 m0, s78, 0xc000
	ds_read_b128 v[196:199], v148
	ds_read_b128 v[200:203], v148 offset:1024
	ds_read_b128 v[204:207], v148 offset:2048
	ds_read_b128 v[208:211], v148 offset:3072
	ds_read_b128 v[212:215], v148 offset:4096
	ds_read_b128 v[216:219], v148 offset:5120
	ds_read_b128 v[220:223], v148 offset:6144
	ds_read_b128 v[224:227], v148 offset:7168
	global_load_lds_dwordx4 v140, s[44:45]
	s_add_i32 m0, s78, 0xe000
	s_nop 0
	global_load_lds_dwordx4 v138, s[44:45]
	s_waitcnt vmcnt(8)
	s_waitcnt lgkmcnt(0)
	s_barrier
	v_mfma_f32_16x16x32_bf16 v[126:129], v[142:145], v[196:199], v[126:129]
	v_mfma_f32_16x16x32_bf16 v[122:125], v[154:157], v[196:199], v[122:125]
	v_mfma_f32_16x16x32_bf16 v[110:113], v[142:145], v[204:207], v[110:113]
	v_mfma_f32_16x16x32_bf16 v[106:109], v[154:157], v[204:207], v[106:109]
	v_mfma_f32_16x16x32_bf16 v[94:97], v[142:145], v[212:215], v[94:97]
	v_mfma_f32_16x16x32_bf16 v[90:93], v[154:157], v[212:215], v[90:93]
	v_mfma_f32_16x16x32_bf16 v[78:81], v[142:145], v[220:223], v[78:81]
	v_mfma_f32_16x16x32_bf16 v[74:77], v[154:157], v[220:223], v[74:77]
	v_mfma_f32_16x16x32_bf16 v[126:129], v[150:153], v[200:203], v[126:129]
	v_mfma_f32_16x16x32_bf16 v[122:125], v[158:161], v[200:203], v[122:125]
	v_mfma_f32_16x16x32_bf16 v[110:113], v[150:153], v[208:211], v[110:113]
	v_mfma_f32_16x16x32_bf16 v[106:109], v[158:161], v[208:211], v[106:109]
	v_mfma_f32_16x16x32_bf16 v[94:97], v[150:153], v[216:219], v[94:97]
	v_mfma_f32_16x16x32_bf16 v[90:93], v[158:161], v[216:219], v[90:93]
	v_mfma_f32_16x16x32_bf16 v[78:81], v[150:153], v[224:227], v[78:81]
	v_mfma_f32_16x16x32_bf16 v[74:77], v[158:161], v[224:227], v[74:77]
	v_mfma_f32_16x16x32_bf16 v[118:121], v[170:173], v[196:199], v[118:121]
	v_mfma_f32_16x16x32_bf16 v[114:117], v[178:181], v[196:199], v[114:117]
	v_mfma_f32_16x16x32_bf16 v[102:105], v[170:173], v[204:207], v[102:105]
	v_mfma_f32_16x16x32_bf16 v[98:101], v[178:181], v[204:207], v[98:101]
	v_mfma_f32_16x16x32_bf16 v[86:89], v[170:173], v[212:215], v[86:89]
	v_mfma_f32_16x16x32_bf16 v[82:85], v[178:181], v[212:215], v[82:85]
	v_mfma_f32_16x16x32_bf16 v[70:73], v[170:173], v[220:223], v[70:73]
	v_mfma_f32_16x16x32_bf16 v[66:69], v[178:181], v[220:223], v[66:69]
	v_mfma_f32_16x16x32_bf16 v[118:121], v[174:177], v[200:203], v[118:121]
	v_mfma_f32_16x16x32_bf16 v[114:117], v[182:185], v[200:203], v[114:117]
	v_mfma_f32_16x16x32_bf16 v[102:105], v[174:177], v[208:211], v[102:105]
	v_mfma_f32_16x16x32_bf16 v[98:101], v[182:185], v[208:211], v[98:101]
	v_mfma_f32_16x16x32_bf16 v[86:89], v[174:177], v[216:219], v[86:89]
	v_mfma_f32_16x16x32_bf16 v[82:85], v[182:185], v[216:219], v[82:85]
	v_mfma_f32_16x16x32_bf16 v[70:73], v[174:177], v[224:227], v[70:73]
	v_mfma_f32_16x16x32_bf16 v[66:69], v[182:185], v[224:227], v[66:69]
	s_barrier
	s_add_i32 s61, s61, s51
	v_lshl_add_u64 v[228:229], s[92:93], 0, v[132:133]
	s_mov_b32 m0, s61
	ds_read_b128 v[196:199], v148 offset:16384
	ds_read_b128 v[200:203], v148 offset:17408
	ds_read_b128 v[204:207], v148 offset:18432
	ds_read_b128 v[208:211], v148 offset:19456
	ds_read_b128 v[212:215], v148 offset:20480
	ds_read_b128 v[216:219], v148 offset:21504
	ds_read_b128 v[220:223], v148 offset:22528
	ds_read_b128 v[224:227], v148 offset:23552
	global_load_lds_dwordx4 v[228:229], off
	s_add_i32 m0, s61, 0x2000
	v_lshl_add_u64 v[230:231], s[92:93], 0, v[136:137]
	s_add_u32 s92, s92, s8
	s_addc_u32 s93, s93, 0
	s_add_i32 s49, s49, s51
	global_load_lds_dwordx4 v[230:231], off
	v_lshl_add_u64 v[232:233], s[92:93], 0, v[132:133]
	s_mov_b32 m0, s49
	v_lshl_add_u64 v[234:235], s[92:93], 0, v[136:137]
	global_load_lds_dwordx4 v[232:233], off
	s_add_i32 m0, s49, 0x2000
	v_lshl_add_u64 v[236:237], s[46:47], 0, v[130:131]
	global_load_lds_dwordx4 v[234:235], off
	s_mov_b32 m0, s78
	v_lshl_add_u64 v[238:239], s[46:47], 0, v[134:135]
	global_load_lds_dwordx4 v[236:237], off
	s_mov_b32 m0, s79
	s_nop 0
	global_load_lds_dwordx4 v[238:239], off
	s_waitcnt vmcnt(8)
	s_waitcnt lgkmcnt(0)
	s_barrier
; #define PG8_STAGE(bufoff, gbase, voff) do { _Pragma("unroll") for (int _i = 0; _i < 2; ++_i) \
;         __builtin_amdgcn_global_load_lds((const unsigned*)((const char*)(gbase) + (voff)[_i]), (PG8_LAS unsigned*)(lds + (bufoff) + ldsw + _i * 8192), 16, 0, 0); } while (0)
; #define PG8_LDA(dst, b, h) do { _Pragma("unroll") for (int m = 0; m < 4; ++m) _Pragma("unroll") for (int k = 0; k < 2; ++k) dst[m][k] = *(const PG8_LAS bf16x8*)(lds + PG8_SA(b, h) + aoff + m * 2048 + k * 1024); } while (0)
; #define PG8_LDB(dst, b, h) do { _Pragma("unroll") for (int n = 0; n < 2; ++n) _Pragma("unroll") for (int k = 0; k < 2; ++k) dst[n][k] = *(const PG8_LAS bf16x8*)(lds + PG8_SB(b, h) + boff + n * 2048 + k * 1024); } while (0)
; #define PG8_MMA(ai, bj, At, Bt) do { __builtin_amdgcn_s_setprio(1); _Pragma("unroll") for (int m = 0; m < 4; ++m) _Pragma("unroll") for (int n = 0; n < 2; ++n) _Pragma("unroll") for (int k = 0; k < 2; ++k) \
;         acc[ai][bj][m][n] = __builtin_amdgcn_mfma_f32_16x16x32_bf16(Bt[n][k], At[m][k], acc[ai][bj][m][n], 0, 0, 0); __builtin_amdgcn_s_setprio(0); } while (0)
; #define PG8_WAIT_V(n) asm volatile("s_waitcnt vmcnt(" #n ")" ::: "memory")
; #define PG8_WAIT_L(n) asm volatile("s_waitcnt lgkmcnt(" #n ")" ::: "memory")
; #define PG8_BAR __builtin_amdgcn_s_barrier()
; #define PG8_SCHED __builtin_amdgcn_sched_barrier(0)
; template <class Epi, class Sched, bool ALIGN_EPI = false, bool SP2 = false>
; __device__ __forceinline__ void gemm_phase(PG8_LAS unsigned char* lds, const Gemm g, const Sched& S, const Epi& E) {
;     ...
;             PG8_WAIT_V(8); PG8_WAIT_L(0); PG8_BAR; PG8_MMA(1, 0, At, B0); PG8_MMA(1, 1, At, B1); PG8_BAR; PG8_SCHED;
;             PG8_LDB(B0, 1, 0); PG8_LDB(B1, 1, 1); PG8_SCHED; PG8_LDA(At, 1, 0); PG8_STAGE(PG8_SA(0, 1), a2 + hstep, voffA);
;             PG8_WAIT_V(8); PG8_WAIT_L(0); PG8_BAR; PG8_MMA(0, 0, At, B0); PG8_MMA(0, 1, At, B1); PG8_BAR; PG8_SCHED;
	v_mfma_f32_16x16x32_bf16 v[62:65], v[142:145], v[196:199], v[62:65]
	v_mfma_f32_16x16x32_bf16 v[58:61], v[154:157], v[196:199], v[58:61]
	v_mfma_f32_16x16x32_bf16 v[46:49], v[142:145], v[204:207], v[46:49]
	v_mfma_f32_16x16x32_bf16 v[42:45], v[154:157], v[204:207], v[42:45]
	v_mfma_f32_16x16x32_bf16 v[28:31], v[142:145], v[212:215], v[28:31]
	v_mfma_f32_16x16x32_bf16 v[24:27], v[154:157], v[212:215], v[24:27]
	v_mfma_f32_16x16x32_bf16 v[12:15], v[142:145], v[220:223], v[12:15]
	v_mfma_f32_16x16x32_bf16 v[8:11], v[154:157], v[220:223], v[8:11]
	v_mfma_f32_16x16x32_bf16 v[62:65], v[150:153], v[200:203], v[62:65]
	v_mfma_f32_16x16x32_bf16 v[58:61], v[158:161], v[200:203], v[58:61]
	v_mfma_f32_16x16x32_bf16 v[46:49], v[150:153], v[208:211], v[46:49]
	v_mfma_f32_16x16x32_bf16 v[42:45], v[158:161], v[208:211], v[42:45]
	v_mfma_f32_16x16x32_bf16 v[28:31], v[150:153], v[216:219], v[28:31]
	v_mfma_f32_16x16x32_bf16 v[24:27], v[158:161], v[216:219], v[24:27]
	v_mfma_f32_16x16x32_bf16 v[12:15], v[150:153], v[224:227], v[12:15]
	v_mfma_f32_16x16x32_bf16 v[8:11], v[158:161], v[224:227], v[8:11]
	v_mfma_f32_16x16x32_bf16 v[54:57], v[170:173], v[196:199], v[54:57]
	v_mfma_f32_16x16x32_bf16 v[50:53], v[178:181], v[196:199], v[50:53]
	v_mfma_f32_16x16x32_bf16 v[38:41], v[170:173], v[204:207], v[38:41]
	v_mfma_f32_16x16x32_bf16 v[34:37], v[178:181], v[204:207], v[34:37]
	v_mfma_f32_16x16x32_bf16 v[20:23], v[170:173], v[212:215], v[20:23]
	v_mfma_f32_16x16x32_bf16 v[16:19], v[178:181], v[212:215], v[16:19]
	v_mfma_f32_16x16x32_bf16 v[4:7], v[170:173], v[220:223], v[4:7]
	v_mfma_f32_16x16x32_bf16 v[0:3], v[178:181], v[220:223], v[0:3]
	v_mfma_f32_16x16x32_bf16 v[54:57], v[174:177], v[200:203], v[54:57]
	v_mfma_f32_16x16x32_bf16 v[50:53], v[182:185], v[200:203], v[50:53]
	v_mfma_f32_16x16x32_bf16 v[38:41], v[174:177], v[208:211], v[38:41]
	v_mfma_f32_16x16x32_bf16 v[34:37], v[182:185], v[208:211], v[34:37]
	v_mfma_f32_16x16x32_bf16 v[20:23], v[174:177], v[216:219], v[20:23]
	v_mfma_f32_16x16x32_bf16 v[16:19], v[182:185], v[216:219], v[16:19]
	v_mfma_f32_16x16x32_bf16 v[4:7], v[174:177], v[224:227], v[4:7]
	v_mfma_f32_16x16x32_bf16 v[0:3], v[182:185], v[224:227], v[0:3]
	s_barrier
	s_add_i32 s49, 0, 0x18000
	v_add_u32_e32 v149, s49, v146
	s_add_i32 s61, 0, 0x1c000
	ds_read_b128 v[142:145], v149
	ds_read_b128 v[150:153], v149 offset:1024
	ds_read_b128 v[154:157], v149 offset:2048
	ds_read_b128 v[158:161], v149 offset:3072
	v_add_u32_e32 v149, s61, v146
	ds_read_b128 v[170:173], v149
	ds_read_b128 v[174:177], v149 offset:1024
	ds_read_b128 v[178:181], v149 offset:2048
	ds_read_b128 v[182:185], v149 offset:3072
	s_add_u32 s46, s46, s8
	s_addc_u32 s47, s47, 0
	s_mov_b32 m0, s80
	ds_read_b128 v[196:199], v148 offset:32768
	ds_read_b128 v[200:203], v148 offset:33792
	ds_read_b128 v[204:207], v148 offset:34816
	ds_read_b128 v[208:211], v148 offset:35840
	ds_read_b128 v[212:215], v148 offset:36864
	ds_read_b128 v[216:219], v148 offset:37888
	ds_read_b128 v[220:223], v148 offset:38912
	ds_read_b128 v[224:227], v148 offset:39936
	global_load_lds_dwordx4 v130, s[46:47]
	s_mov_b32 m0, s81
	s_nop 0
	global_load_lds_dwordx4 v134, s[46:47]
	s_waitcnt vmcnt(8)
	s_waitcnt lgkmcnt(0)
	s_barrier
	v_mfma_f32_16x16x32_bf16 v[126:129], v[142:145], v[196:199], v[126:129]
	v_mfma_f32_16x16x32_bf16 v[122:125], v[154:157], v[196:199], v[122:125]
	v_mfma_f32_16x16x32_bf16 v[110:113], v[142:145], v[204:207], v[110:113]
	v_mfma_f32_16x16x32_bf16 v[106:109], v[154:157], v[204:207], v[106:109]
	v_mfma_f32_16x16x32_bf16 v[94:97], v[142:145], v[212:215], v[94:97]
	v_mfma_f32_16x16x32_bf16 v[90:93], v[154:157], v[212:215], v[90:93]
	v_mfma_f32_16x16x32_bf16 v[78:81], v[142:145], v[220:223], v[78:81]
	v_mfma_f32_16x16x32_bf16 v[74:77], v[154:157], v[220:223], v[74:77]
	v_mfma_f32_16x16x32_bf16 v[126:129], v[150:153], v[200:203], v[126:129]
	v_mfma_f32_16x16x32_bf16 v[122:125], v[158:161], v[200:203], v[122:125]
	v_mfma_f32_16x16x32_bf16 v[110:113], v[150:153], v[208:211], v[110:113]
	v_mfma_f32_16x16x32_bf16 v[106:109], v[158:161], v[208:211], v[106:109]
	v_mfma_f32_16x16x32_bf16 v[94:97], v[150:153], v[216:219], v[94:97]
	v_mfma_f32_16x16x32_bf16 v[90:93], v[158:161], v[216:219], v[90:93]
	v_mfma_f32_16x16x32_bf16 v[78:81], v[150:153], v[224:227], v[78:81]
	v_mfma_f32_16x16x32_bf16 v[74:77], v[158:161], v[224:227], v[74:77]
	v_mfma_f32_16x16x32_bf16 v[118:121], v[170:173], v[196:199], v[118:121]
	v_mfma_f32_16x16x32_bf16 v[114:117], v[178:181], v[196:199], v[114:117]
	v_mfma_f32_16x16x32_bf16 v[102:105], v[170:173], v[204:207], v[102:105]
	v_mfma_f32_16x16x32_bf16 v[98:101], v[178:181], v[204:207], v[98:101]
	v_mfma_f32_16x16x32_bf16 v[86:89], v[170:173], v[212:215], v[86:89]
	v_mfma_f32_16x16x32_bf16 v[82:85], v[178:181], v[212:215], v[82:85]
	v_mfma_f32_16x16x32_bf16 v[70:73], v[170:173], v[220:223], v[70:73]
	v_mfma_f32_16x16x32_bf16 v[66:69], v[178:181], v[220:223], v[66:69]
	v_mfma_f32_16x16x32_bf16 v[118:121], v[174:177], v[200:203], v[118:121]
	v_mfma_f32_16x16x32_bf16 v[114:117], v[182:185], v[200:203], v[114:117]
	v_mfma_f32_16x16x32_bf16 v[102:105], v[174:177], v[208:211], v[102:105]
	v_mfma_f32_16x16x32_bf16 v[98:101], v[182:185], v[208:211], v[98:101]
	v_mfma_f32_16x16x32_bf16 v[86:89], v[174:177], v[216:219], v[86:89]
	v_mfma_f32_16x16x32_bf16 v[82:85], v[182:185], v[216:219], v[82:85]
	v_mfma_f32_16x16x32_bf16 v[70:73], v[174:177], v[224:227], v[70:73]
	v_mfma_f32_16x16x32_bf16 v[66:69], v[182:185], v[224:227], v[66:69]
	s_barrier
; #define PG8_STAGE(bufoff, gbase, voff) do { _Pragma("unroll") for (int _i = 0; _i < 2; ++_i) \
;         __builtin_amdgcn_global_load_lds((const unsigned*)((const char*)(gbase) + (voff)[_i]), (PG8_LAS unsigned*)(lds + (bufoff) + ldsw + _i * 8192), 16, 0, 0); } while (0)
; #define PG8_LDA(dst, b, h) do { _Pragma("unroll") for (int m = 0; m < 4; ++m) _Pragma("unroll") for (int k = 0; k < 2; ++k) dst[m][k] = *(const PG8_LAS bf16x8*)(lds + PG8_SA(b, h) + aoff + m * 2048 + k * 1024); } while (0)
; #define PG8_MMA(ai, bj, At, Bt) do { __builtin_amdgcn_s_setprio(1); _Pragma("unroll") for (int m = 0; m < 4; ++m) _Pragma("unroll") for (int n = 0; n < 2; ++n) _Pragma("unroll") for (int k = 0; k < 2; ++k) \
;         acc[ai][bj][m][n] = __builtin_amdgcn_mfma_f32_16x16x32_bf16(Bt[n][k], At[m][k], acc[ai][bj][m][n], 0, 0, 0); __builtin_amdgcn_s_setprio(0); } while (0)
; #define PG8_WAIT_V(n) asm volatile("s_waitcnt vmcnt(" #n ")" ::: "memory")
; #define PG8_WAIT_L(n) asm volatile("s_waitcnt lgkmcnt(" #n ")" ::: "memory")
; #define PG8_BAR __builtin_amdgcn_s_barrier()
; #define PG8_SCHED __builtin_amdgcn_sched_barrier(0)
; template <class Epi, class Sched, bool ALIGN_EPI = false, bool SP2 = false>
; __device__ __forceinline__ void gemm_phase(PG8_LAS unsigned char* lds, const Gemm g, const Sched& S, const Epi& E) {
;     ...
;             PG8_LDA(At, 1, 1); PG8_STAGE(PG8_SB(1, 0), b3, voffB); PG8_STAGE(PG8_SB(1, 1), b3 + hstep, voffB); PG8_STAGE(PG8_SA(1, 0), a3, voffA);
;             PG8_WAIT_V(8); PG8_WAIT_L(0); PG8_BAR; PG8_MMA(1, 0, At, B0); PG8_MMA(1, 1, At, B1); PG8_BAR; PG8_SCHED;
;     ...
;         if constexpr (ALIGN_EPI) { if (wr == 0) PG8_BAR; }
	s_add_i32 s46, s49, s51
	v_lshl_add_u64 v[228:229], v[228:229], 0, s[34:35]
	s_mov_b32 m0, s46
	ds_read_b128 v[196:199], v148 offset:49152
	ds_read_b128 v[200:203], v148 offset:50176
	ds_read_b128 v[204:207], v148 offset:51200
	ds_read_b128 v[208:211], v148 offset:52224
	ds_read_b128 v[212:215], v148 offset:53248
	ds_read_b128 v[216:219], v148 offset:54272
	ds_read_b128 v[220:223], v148 offset:55296
	ds_read_b128 v[224:227], v148 offset:56320
	global_load_lds_dwordx4 v[228:229], off
	v_lshl_add_u64 v[228:229], v[230:231], 0, s[34:35]
	s_add_i32 m0, s46, 0x2000
	s_add_i32 s46, s61, s51
	global_load_lds_dwordx4 v[228:229], off
	v_lshl_add_u64 v[228:229], v[232:233], 0, s[34:35]
	s_mov_b32 m0, s46
	s_nop 0
	global_load_lds_dwordx4 v[228:229], off
	v_lshl_add_u64 v[228:229], v[234:235], 0, s[34:35]
	s_add_i32 m0, s46, 0x2000
	s_nop 0
	global_load_lds_dwordx4 v[228:229], off
	v_lshl_add_u64 v[228:229], v[236:237], 0, s[34:35]
	s_mov_b32 m0, s83
	s_nop 0
	global_load_lds_dwordx4 v[228:229], off
	v_lshl_add_u64 v[228:229], v[238:239], 0, s[34:35]
	s_mov_b32 m0, s84
	s_nop 0
	global_load_lds_dwordx4 v[228:229], off
	s_waitcnt vmcnt(8)
	s_waitcnt lgkmcnt(0)
	s_barrier
	v_mfma_f32_16x16x32_bf16 v[62:65], v[142:145], v[196:199], v[62:65]
	v_mfma_f32_16x16x32_bf16 v[58:61], v[154:157], v[196:199], v[58:61]
	v_mfma_f32_16x16x32_bf16 v[46:49], v[142:145], v[204:207], v[46:49]
	v_mfma_f32_16x16x32_bf16 v[42:45], v[154:157], v[204:207], v[42:45]
	v_mfma_f32_16x16x32_bf16 v[28:31], v[142:145], v[212:215], v[28:31]
	v_mfma_f32_16x16x32_bf16 v[24:27], v[154:157], v[212:215], v[24:27]
	v_mfma_f32_16x16x32_bf16 v[12:15], v[142:145], v[220:223], v[12:15]
	v_mfma_f32_16x16x32_bf16 v[8:11], v[154:157], v[220:223], v[8:11]
	v_mfma_f32_16x16x32_bf16 v[62:65], v[150:153], v[200:203], v[62:65]
	v_mfma_f32_16x16x32_bf16 v[58:61], v[158:161], v[200:203], v[58:61]
	v_mfma_f32_16x16x32_bf16 v[46:49], v[150:153], v[208:211], v[46:49]
	v_mfma_f32_16x16x32_bf16 v[42:45], v[158:161], v[208:211], v[42:45]
	v_mfma_f32_16x16x32_bf16 v[28:31], v[150:153], v[216:219], v[28:31]
	v_mfma_f32_16x16x32_bf16 v[24:27], v[158:161], v[216:219], v[24:27]
	v_mfma_f32_16x16x32_bf16 v[12:15], v[150:153], v[224:227], v[12:15]
	v_mfma_f32_16x16x32_bf16 v[8:11], v[158:161], v[224:227], v[8:11]
	v_mfma_f32_16x16x32_bf16 v[54:57], v[170:173], v[196:199], v[54:57]
	v_mfma_f32_16x16x32_bf16 v[50:53], v[178:181], v[196:199], v[50:53]
	v_mfma_f32_16x16x32_bf16 v[38:41], v[170:173], v[204:207], v[38:41]
	v_mfma_f32_16x16x32_bf16 v[34:37], v[178:181], v[204:207], v[34:37]
	v_mfma_f32_16x16x32_bf16 v[20:23], v[170:173], v[212:215], v[20:23]
	v_mfma_f32_16x16x32_bf16 v[16:19], v[178:181], v[212:215], v[16:19]
	v_mfma_f32_16x16x32_bf16 v[4:7], v[170:173], v[220:223], v[4:7]
	v_mfma_f32_16x16x32_bf16 v[0:3], v[178:181], v[220:223], v[0:3]
	v_mfma_f32_16x16x32_bf16 v[54:57], v[174:177], v[200:203], v[54:57]
	v_mfma_f32_16x16x32_bf16 v[50:53], v[182:185], v[200:203], v[50:53]
	v_mfma_f32_16x16x32_bf16 v[38:41], v[174:177], v[208:211], v[38:41]
	v_mfma_f32_16x16x32_bf16 v[34:37], v[182:185], v[208:211], v[34:37]
	v_mfma_f32_16x16x32_bf16 v[20:23], v[174:177], v[216:219], v[20:23]
	v_mfma_f32_16x16x32_bf16 v[16:19], v[182:185], v[216:219], v[16:19]
	v_mfma_f32_16x16x32_bf16 v[4:7], v[174:177], v[224:227], v[4:7]
	v_mfma_f32_16x16x32_bf16 v[0:3], v[182:185], v[224:227], v[0:3]
	s_barrier
	s_add_u32 s0, s0, 0x100
	s_addc_u32 s9, s9, 0
	s_add_u32 s44, s44, 0x100
	s_addc_u32 s45, s45, 0
	s_cmp_ge_u32 s48, s85
	s_mov_b32 s46, s48
	s_cbranch_scc0 .LBB0_546
	s_and_b64 vcc, exec, s[40:41]
	s_cbranch_vccz .LBB0_549
	s_barrier

; #define PG8_STAGE(bufoff, gbase, voff) do { _Pragma("unroll") for (int _i = 0; _i < 2; ++_i) \
;         __builtin_amdgcn_global_load_lds((const unsigned*)((const char*)(gbase) + (voff)[_i]), (PG8_LAS unsigned*)(lds + (bufoff) + ldsw + _i * 8192), 16, 0, 0); } while (0)
; #define PG8_LDA(dst, b, h) do { _Pragma("unroll") for (int m = 0; m < 4; ++m) _Pragma("unroll") for (int k = 0; k < 2; ++k) dst[m][k] = *(const PG8_LAS bf16x8*)(lds + PG8_SA(b, h) + aoff + m * 2048 + k * 1024); } while (0)
; #define PG8_LDB(dst, b, h) do { _Pragma("unroll") for (int n = 0; n < 2; ++n) _Pragma("unroll") for (int k = 0; k < 2; ++k) dst[n][k] = *(const PG8_LAS bf16x8*)(lds + PG8_SB(b, h) + boff + n * 2048 + k * 1024); } while (0)
; #define PG8_MMA(ai, bj, At, Bt) do { __builtin_amdgcn_s_setprio(1); _Pragma("unroll") for (int m = 0; m < 4; ++m) _Pragma("unroll") for (int n = 0; n < 2; ++n) _Pragma("unroll") for (int k = 0; k < 2; ++k) \
;         acc[ai][bj][m][n] = __builtin_amdgcn_mfma_f32_16x16x32_bf16(Bt[n][k], At[m][k], acc[ai][bj][m][n], 0, 0, 0); __builtin_amdgcn_s_setprio(0); } while (0)
; #define PG8_WAIT_V(n) asm volatile("s_waitcnt vmcnt(" #n ")" ::: "memory")
; #define PG8_WAIT_L(n) asm volatile("s_waitcnt lgkmcnt(" #n ")" ::: "memory")
; template <class Epi, class Sched, bool ALIGN_EPI = false, bool SP2 = false>
; __device__ __forceinline__ void gemm_phase(PG8_LAS unsigned char* lds, const Gemm g, const Sched& S, const Epi& E) {
;     ...
;             const bool last = (t == nt - 2);
;             const char* a1 = cA + (size_t)(t + 1) * kstep;
;             const char* a2 = last ? nA : cA + (size_t)(t + 2) * kstep; const char* b2 = last ? nB : cB + (size_t)(t + 2) * kstep;
;             const char* a3 = a2 + kstep; const char* b3 = b2 + kstep;
;             if (last && has_next) S.a_ready(nxt);
;             if constexpr (SP2) {
;             PG8_LDB(B0, 0, 0); PG8_LDB(B1, 0, 1); PG8_SCHED; PG8_LDA(At, 0, 0); PG8_STAGE(PG8_SA(1, 1), a1 + hstep, voffA);
;             PG8_WAIT_V(8); PG8_WAIT_L(0); PG8_BAR; PG8_MMA(0, 0, At, B0); PG8_MMA(0, 1, At, B1); PG8_BAR; PG8_SCHED;
;             PG8_LDA(At, 0, 1); PG8_STAGE(PG8_SB(0, 0), b2, voffB); PG8_STAGE(PG8_SB(0, 1), b2 + hstep, voffB); PG8_STAGE(PG8_SA(0, 0), a2, voffA);
;             PG8_WAIT_V(8); PG8_WAIT_L(0); PG8_BAR; PG8_MMA(1, 0, At, B0); PG8_MMA(1, 1, At, B1); PG8_BAR; PG8_SCHED;
.LBB0_580:
	s_add_u32 s48, s46, 0xfffc0080
	s_addc_u32 s49, s47, -1
	s_add_i32 s82, 0, 0x10000
	s_cmp_eq_u32 s81, 12
	s_cselect_b32 s51, s9, s49
	s_cselect_b32 s50, s66, s48
	v_add_u32_e32 v151, s82, v145
	s_cselect_b32 s49, s7, s80
	s_cselect_b32 s48, s67, s79
	s_add_i32 s84, 0, 0x14000
	ds_read_b128 v[170:173], v151
	ds_read_b128 v[174:177], v151 offset:1024
	ds_read_b128 v[178:181], v151 offset:2048
	ds_read_b128 v[182:185], v151 offset:3072
	v_add_u32_e32 v151, s84, v145
	ds_read_b128 v[196:199], v151
	ds_read_b128 v[200:203], v151 offset:1024
	ds_read_b128 v[204:207], v151 offset:2048
	ds_read_b128 v[208:211], v151 offset:3072
	s_add_i32 m0, s71, 0xc000
	ds_read_b128 v[212:215], v149
	ds_read_b128 v[216:219], v149 offset:1024
	ds_read_b128 v[220:223], v149 offset:2048
	ds_read_b128 v[224:227], v149 offset:3072
	ds_read_b128 v[228:231], v149 offset:4096
	ds_read_b128 v[232:235], v149 offset:5120
	ds_read_b128 v[236:239], v149 offset:6144
	ds_read_b128 v[240:243], v149 offset:7168
	global_load_lds_dwordx4 v142, s[46:47]
	s_add_i32 m0, s71, 0xe000
	s_nop 0
	global_load_lds_dwordx4 v140, s[46:47]
	s_waitcnt vmcnt(8)
	s_waitcnt lgkmcnt(0)
	s_barrier
	v_mfma_f32_16x16x32_bf16 v[126:129], v[170:173], v[212:215], v[126:129]
	v_mfma_f32_16x16x32_bf16 v[122:125], v[178:181], v[212:215], v[122:125]
	v_mfma_f32_16x16x32_bf16 v[110:113], v[170:173], v[220:223], v[110:113]
	v_mfma_f32_16x16x32_bf16 v[106:109], v[178:181], v[220:223], v[106:109]
	v_mfma_f32_16x16x32_bf16 v[94:97], v[170:173], v[228:231], v[94:97]
	v_mfma_f32_16x16x32_bf16 v[90:93], v[178:181], v[228:231], v[90:93]
	v_mfma_f32_16x16x32_bf16 v[78:81], v[170:173], v[236:239], v[78:81]
	v_mfma_f32_16x16x32_bf16 v[74:77], v[178:181], v[236:239], v[74:77]
	v_mfma_f32_16x16x32_bf16 v[126:129], v[174:177], v[216:219], v[126:129]
	v_mfma_f32_16x16x32_bf16 v[122:125], v[182:185], v[216:219], v[122:125]
	v_mfma_f32_16x16x32_bf16 v[110:113], v[174:177], v[224:227], v[110:113]
	v_mfma_f32_16x16x32_bf16 v[106:109], v[182:185], v[224:227], v[106:109]
	v_mfma_f32_16x16x32_bf16 v[94:97], v[174:177], v[232:235], v[94:97]
	v_mfma_f32_16x16x32_bf16 v[90:93], v[182:185], v[232:235], v[90:93]
	v_mfma_f32_16x16x32_bf16 v[78:81], v[174:177], v[240:243], v[78:81]
	v_mfma_f32_16x16x32_bf16 v[74:77], v[182:185], v[240:243], v[74:77]
	v_mfma_f32_16x16x32_bf16 v[118:121], v[196:199], v[212:215], v[118:121]
	v_mfma_f32_16x16x32_bf16 v[114:117], v[204:207], v[212:215], v[114:117]
	v_mfma_f32_16x16x32_bf16 v[102:105], v[196:199], v[220:223], v[102:105]
	v_mfma_f32_16x16x32_bf16 v[98:101], v[204:207], v[220:223], v[98:101]
	v_mfma_f32_16x16x32_bf16 v[86:89], v[196:199], v[228:231], v[86:89]
	v_mfma_f32_16x16x32_bf16 v[82:85], v[204:207], v[228:231], v[82:85]
	v_mfma_f32_16x16x32_bf16 v[70:73], v[196:199], v[236:239], v[70:73]
	v_mfma_f32_16x16x32_bf16 v[66:69], v[204:207], v[236:239], v[66:69]
	v_mfma_f32_16x16x32_bf16 v[118:121], v[200:203], v[216:219], v[118:121]
	v_mfma_f32_16x16x32_bf16 v[114:117], v[208:211], v[216:219], v[114:117]
	v_mfma_f32_16x16x32_bf16 v[102:105], v[200:203], v[224:227], v[102:105]
	v_mfma_f32_16x16x32_bf16 v[98:101], v[208:211], v[224:227], v[98:101]
	v_mfma_f32_16x16x32_bf16 v[86:89], v[200:203], v[232:235], v[86:89]
	v_mfma_f32_16x16x32_bf16 v[82:85], v[208:211], v[232:235], v[82:85]
	v_mfma_f32_16x16x32_bf16 v[70:73], v[200:203], v[240:243], v[70:73]
	v_mfma_f32_16x16x32_bf16 v[66:69], v[208:211], v[240:243], v[66:69]
	s_barrier
	s_add_i32 s82, s82, s69
	v_lshl_add_u64 v[160:161], s[48:49], 0, v[134:135]
	s_mov_b32 m0, s82
	ds_read_b128 v[212:215], v149 offset:16384
	ds_read_b128 v[216:219], v149 offset:17408
	ds_read_b128 v[220:223], v149 offset:18432
	ds_read_b128 v[224:227], v149 offset:19456
	ds_read_b128 v[228:231], v149 offset:20480
	ds_read_b128 v[232:235], v149 offset:21504
	ds_read_b128 v[236:239], v149 offset:22528
	ds_read_b128 v[240:243], v149 offset:23552
	global_load_lds_dwordx4 v[160:161], off
	s_add_i32 m0, s82, 0x2000
	s_add_u32 s82, s48, 0x40000
	v_lshl_add_u64 v[244:245], s[48:49], 0, v[130:131]
	s_addc_u32 s83, s49, 0
	s_add_i32 s84, s84, s69
	global_load_lds_dwordx4 v[244:245], off
	s_mov_b32 m0, s84
	v_lshl_add_u64 v[248:249], s[50:51], 0, v[132:133]
	global_load_lds_dwordx4 v134, s[82:83]
	s_add_i32 m0, s84, 0x2000
	s_nop 0
	global_load_lds_dwordx4 v130, s[82:83]
	v_lshl_add_u64 v[246:247], s[50:51], 0, v[136:137]
	s_mov_b32 m0, s71
	s_nop 0
	global_load_lds_dwordx4 v[246:247], off
	s_mov_b32 m0, s72
	s_nop 0
	global_load_lds_dwordx4 v[248:249], off
	s_waitcnt vmcnt(8)
	s_waitcnt lgkmcnt(0)
	s_barrier
; #define PG8_STAGE(bufoff, gbase, voff) do { _Pragma("unroll") for (int _i = 0; _i < 2; ++_i) \
;         __builtin_amdgcn_global_load_lds((const unsigned*)((const char*)(gbase) + (voff)[_i]), (PG8_LAS unsigned*)(lds + (bufoff) + ldsw + _i * 8192), 16, 0, 0); } while (0)
; #define PG8_LDA(dst, b, h) do { _Pragma("unroll") for (int m = 0; m < 4; ++m) _Pragma("unroll") for (int k = 0; k < 2; ++k) dst[m][k] = *(const PG8_LAS bf16x8*)(lds + PG8_SA(b, h) + aoff + m * 2048 + k * 1024); } while (0)
; #define PG8_LDB(dst, b, h) do { _Pragma("unroll") for (int n = 0; n < 2; ++n) _Pragma("unroll") for (int k = 0; k < 2; ++k) dst[n][k] = *(const PG8_LAS bf16x8*)(lds + PG8_SB(b, h) + boff + n * 2048 + k * 1024); } while (0)
; #define PG8_MMA(ai, bj, At, Bt) do { __builtin_amdgcn_s_setprio(1); _Pragma("unroll") for (int m = 0; m < 4; ++m) _Pragma("unroll") for (int n = 0; n < 2; ++n) _Pragma("unroll") for (int k = 0; k < 2; ++k) \
;         acc[ai][bj][m][n] = __builtin_amdgcn_mfma_f32_16x16x32_bf16(Bt[n][k], At[m][k], acc[ai][bj][m][n], 0, 0, 0); __builtin_amdgcn_s_setprio(0); } while (0)
; #define PG8_WAIT_V(n) asm volatile("s_waitcnt vmcnt(" #n ")" ::: "memory")
; #define PG8_WAIT_L(n) asm volatile("s_waitcnt lgkmcnt(" #n ")" ::: "memory")
; #define PG8_BAR __builtin_amdgcn_s_barrier()
; #define PG8_SCHED __builtin_amdgcn_sched_barrier(0)
; template <class Epi, class Sched, bool ALIGN_EPI = false, bool SP2 = false>
; __device__ __forceinline__ void gemm_phase(PG8_LAS unsigned char* lds, const Gemm g, const Sched& S, const Epi& E) {
;     ...
;             PG8_WAIT_V(8); PG8_WAIT_L(0); PG8_BAR; PG8_MMA(1, 0, At, B0); PG8_MMA(1, 1, At, B1); PG8_BAR; PG8_SCHED;
;             PG8_LDB(B0, 1, 0); PG8_LDB(B1, 1, 1); PG8_SCHED; PG8_LDA(At, 1, 0); PG8_STAGE(PG8_SA(0, 1), a2 + hstep, voffA);
;             PG8_WAIT_V(8); PG8_WAIT_L(0); PG8_BAR; PG8_MMA(0, 0, At, B0); PG8_MMA(0, 1, At, B1); PG8_BAR; PG8_SCHED;
	v_mfma_f32_16x16x32_bf16 v[62:65], v[170:173], v[212:215], v[62:65]
	v_mfma_f32_16x16x32_bf16 v[58:61], v[178:181], v[212:215], v[58:61]
	v_mfma_f32_16x16x32_bf16 v[46:49], v[170:173], v[220:223], v[46:49]
	v_mfma_f32_16x16x32_bf16 v[42:45], v[178:181], v[220:223], v[42:45]
	v_mfma_f32_16x16x32_bf16 v[28:31], v[170:173], v[228:231], v[28:31]
	v_mfma_f32_16x16x32_bf16 v[24:27], v[178:181], v[228:231], v[24:27]
	v_mfma_f32_16x16x32_bf16 v[12:15], v[170:173], v[236:239], v[12:15]
	v_mfma_f32_16x16x32_bf16 v[8:11], v[178:181], v[236:239], v[8:11]
	v_mfma_f32_16x16x32_bf16 v[62:65], v[174:177], v[216:219], v[62:65]
	v_mfma_f32_16x16x32_bf16 v[58:61], v[182:185], v[216:219], v[58:61]
	v_mfma_f32_16x16x32_bf16 v[46:49], v[174:177], v[224:227], v[46:49]
	v_mfma_f32_16x16x32_bf16 v[42:45], v[182:185], v[224:227], v[42:45]
	v_mfma_f32_16x16x32_bf16 v[28:31], v[174:177], v[232:235], v[28:31]
	v_mfma_f32_16x16x32_bf16 v[24:27], v[182:185], v[232:235], v[24:27]
	v_mfma_f32_16x16x32_bf16 v[12:15], v[174:177], v[240:243], v[12:15]
	v_mfma_f32_16x16x32_bf16 v[8:11], v[182:185], v[240:243], v[8:11]
	v_mfma_f32_16x16x32_bf16 v[54:57], v[196:199], v[212:215], v[54:57]
	v_mfma_f32_16x16x32_bf16 v[50:53], v[204:207], v[212:215], v[50:53]
	v_mfma_f32_16x16x32_bf16 v[38:41], v[196:199], v[220:223], v[38:41]
	v_mfma_f32_16x16x32_bf16 v[34:37], v[204:207], v[220:223], v[34:37]
	v_mfma_f32_16x16x32_bf16 v[20:23], v[196:199], v[228:231], v[20:23]
	v_mfma_f32_16x16x32_bf16 v[16:19], v[204:207], v[228:231], v[16:19]
	v_mfma_f32_16x16x32_bf16 v[4:7], v[196:199], v[236:239], v[4:7]
	v_mfma_f32_16x16x32_bf16 v[0:3], v[204:207], v[236:239], v[0:3]
	v_mfma_f32_16x16x32_bf16 v[54:57], v[200:203], v[216:219], v[54:57]
	v_mfma_f32_16x16x32_bf16 v[50:53], v[208:211], v[216:219], v[50:53]
	v_mfma_f32_16x16x32_bf16 v[38:41], v[200:203], v[224:227], v[38:41]
	v_mfma_f32_16x16x32_bf16 v[34:37], v[208:211], v[224:227], v[34:37]
	v_mfma_f32_16x16x32_bf16 v[20:23], v[200:203], v[232:235], v[20:23]
	v_mfma_f32_16x16x32_bf16 v[16:19], v[208:211], v[232:235], v[16:19]
	v_mfma_f32_16x16x32_bf16 v[4:7], v[200:203], v[240:243], v[4:7]
	v_mfma_f32_16x16x32_bf16 v[0:3], v[208:211], v[240:243], v[0:3]
	s_barrier
	s_add_i32 s82, 0, 0x18000
	v_add_u32_e32 v151, s82, v145
	s_add_i32 s83, 0, 0x1c000
	ds_read_b128 v[170:173], v151
	ds_read_b128 v[174:177], v151 offset:1024
	ds_read_b128 v[178:181], v151 offset:2048
	ds_read_b128 v[182:185], v151 offset:3072
	v_add_u32_e32 v151, s83, v145
	ds_read_b128 v[196:199], v151
	ds_read_b128 v[200:203], v151 offset:1024
	ds_read_b128 v[204:207], v151 offset:2048
	ds_read_b128 v[208:211], v151 offset:3072
	s_add_u32 s50, s50, 0x40000
	s_addc_u32 s51, s51, 0
	s_mov_b32 m0, s73
	ds_read_b128 v[212:215], v149 offset:32768
	ds_read_b128 v[216:219], v149 offset:33792
	ds_read_b128 v[220:223], v149 offset:34816
	ds_read_b128 v[224:227], v149 offset:35840
	ds_read_b128 v[228:231], v149 offset:36864
	ds_read_b128 v[232:235], v149 offset:37888
	ds_read_b128 v[236:239], v149 offset:38912
	ds_read_b128 v[240:243], v149 offset:39936
	global_load_lds_dwordx4 v136, s[50:51]
	s_mov_b32 m0, s76
	s_nop 0
	global_load_lds_dwordx4 v132, s[50:51]
	s_waitcnt vmcnt(8)
	s_waitcnt lgkmcnt(0)
	s_barrier
	v_mfma_f32_16x16x32_bf16 v[126:129], v[170:173], v[212:215], v[126:129]
	v_mfma_f32_16x16x32_bf16 v[122:125], v[178:181], v[212:215], v[122:125]
	v_mfma_f32_16x16x32_bf16 v[110:113], v[170:173], v[220:223], v[110:113]
	v_mfma_f32_16x16x32_bf16 v[106:109], v[178:181], v[220:223], v[106:109]
	v_mfma_f32_16x16x32_bf16 v[94:97], v[170:173], v[228:231], v[94:97]
	v_mfma_f32_16x16x32_bf16 v[90:93], v[178:181], v[228:231], v[90:93]
	v_mfma_f32_16x16x32_bf16 v[78:81], v[170:173], v[236:239], v[78:81]
	v_mfma_f32_16x16x32_bf16 v[74:77], v[178:181], v[236:239], v[74:77]
	v_mfma_f32_16x16x32_bf16 v[126:129], v[174:177], v[216:219], v[126:129]
	v_mfma_f32_16x16x32_bf16 v[122:125], v[182:185], v[216:219], v[122:125]
	v_mfma_f32_16x16x32_bf16 v[110:113], v[174:177], v[224:227], v[110:113]
	v_mfma_f32_16x16x32_bf16 v[106:109], v[182:185], v[224:227], v[106:109]
	v_mfma_f32_16x16x32_bf16 v[94:97], v[174:177], v[232:235], v[94:97]
	v_mfma_f32_16x16x32_bf16 v[90:93], v[182:185], v[232:235], v[90:93]
	v_mfma_f32_16x16x32_bf16 v[78:81], v[174:177], v[240:243], v[78:81]
	v_mfma_f32_16x16x32_bf16 v[74:77], v[182:185], v[240:243], v[74:77]
	v_mfma_f32_16x16x32_bf16 v[118:121], v[196:199], v[212:215], v[118:121]
	v_mfma_f32_16x16x32_bf16 v[114:117], v[204:207], v[212:215], v[114:117]
	v_mfma_f32_16x16x32_bf16 v[102:105], v[196:199], v[220:223], v[102:105]
	v_mfma_f32_16x16x32_bf16 v[98:101], v[204:207], v[220:223], v[98:101]
	v_mfma_f32_16x16x32_bf16 v[86:89], v[196:199], v[228:231], v[86:89]
	v_mfma_f32_16x16x32_bf16 v[82:85], v[204:207], v[228:231], v[82:85]
	v_mfma_f32_16x16x32_bf16 v[70:73], v[196:199], v[236:239], v[70:73]
	v_mfma_f32_16x16x32_bf16 v[66:69], v[204:207], v[236:239], v[66:69]
	v_mfma_f32_16x16x32_bf16 v[118:121], v[200:203], v[216:219], v[118:121]
	v_mfma_f32_16x16x32_bf16 v[114:117], v[208:211], v[216:219], v[114:117]
	v_mfma_f32_16x16x32_bf16 v[102:105], v[200:203], v[224:227], v[102:105]
	v_mfma_f32_16x16x32_bf16 v[98:101], v[208:211], v[224:227], v[98:101]
	v_mfma_f32_16x16x32_bf16 v[86:89], v[200:203], v[232:235], v[86:89]
	v_mfma_f32_16x16x32_bf16 v[82:85], v[208:211], v[232:235], v[82:85]
	v_mfma_f32_16x16x32_bf16 v[70:73], v[200:203], v[240:243], v[70:73]
	v_mfma_f32_16x16x32_bf16 v[66:69], v[208:211], v[240:243], v[66:69]
	s_barrier
; #define PG8_STAGE(bufoff, gbase, voff) do { _Pragma("unroll") for (int _i = 0; _i < 2; ++_i) \
;         __builtin_amdgcn_global_load_lds((const unsigned*)((const char*)(gbase) + (voff)[_i]), (PG8_LAS unsigned*)(lds + (bufoff) + ldsw + _i * 8192), 16, 0, 0); } while (0)
; #define PG8_LDA(dst, b, h) do { _Pragma("unroll") for (int m = 0; m < 4; ++m) _Pragma("unroll") for (int k = 0; k < 2; ++k) dst[m][k] = *(const PG8_LAS bf16x8*)(lds + PG8_SA(b, h) + aoff + m * 2048 + k * 1024); } while (0)
; #define PG8_MMA(ai, bj, At, Bt) do { __builtin_amdgcn_s_setprio(1); _Pragma("unroll") for (int m = 0; m < 4; ++m) _Pragma("unroll") for (int n = 0; n < 2; ++n) _Pragma("unroll") for (int k = 0; k < 2; ++k) \
;         acc[ai][bj][m][n] = __builtin_amdgcn_mfma_f32_16x16x32_bf16(Bt[n][k], At[m][k], acc[ai][bj][m][n], 0, 0, 0); __builtin_amdgcn_s_setprio(0); } while (0)
; #define PG8_WAIT_V(n) asm volatile("s_waitcnt vmcnt(" #n ")" ::: "memory")
; #define PG8_WAIT_L(n) asm volatile("s_waitcnt lgkmcnt(" #n ")" ::: "memory")
; #define PG8_BAR __builtin_amdgcn_s_barrier()
; #define PG8_SCHED __builtin_amdgcn_sched_barrier(0)
; template <class Epi, class Sched, bool ALIGN_EPI = false, bool SP2 = false>
; __device__ __forceinline__ void gemm_phase(PG8_LAS unsigned char* lds, const Gemm g, const Sched& S, const Epi& E) {
;     ...
;             PG8_LDA(At, 1, 1); PG8_STAGE(PG8_SB(1, 0), b3, voffB); PG8_STAGE(PG8_SB(1, 1), b3 + hstep, voffB); PG8_STAGE(PG8_SA(1, 0), a3, voffA);
;             PG8_WAIT_V(8); PG8_WAIT_L(0); PG8_BAR; PG8_MMA(1, 0, At, B0); PG8_MMA(1, 1, At, B1); PG8_BAR; PG8_SCHED;
;     ...
;         if constexpr (ALIGN_EPI) { if (wr == 0) PG8_BAR; }
	s_add_i32 s50, s82, s69
	v_lshl_add_u64 v[160:161], v[160:161], 0, s[34:35]
	s_mov_b32 m0, s50
	ds_read_b128 v[212:215], v149 offset:49152
	ds_read_b128 v[216:219], v149 offset:50176
	ds_read_b128 v[220:223], v149 offset:51200
	ds_read_b128 v[224:227], v149 offset:52224
	ds_read_b128 v[228:231], v149 offset:53248
	ds_read_b128 v[232:235], v149 offset:54272
	ds_read_b128 v[236:239], v149 offset:55296
	ds_read_b128 v[240:243], v149 offset:56320
	global_load_lds_dwordx4 v[160:161], off
	s_add_i32 m0, s50, 0x2000
	s_add_u32 s48, s48, 0x40080
	v_lshl_add_u64 v[160:161], v[244:245], 0, s[34:35]
	s_addc_u32 s49, s49, 0
	s_add_i32 s50, s83, s69
	global_load_lds_dwordx4 v[160:161], off
	s_mov_b32 m0, s50
	s_nop 0
	global_load_lds_dwordx4 v134, s[48:49]
	s_add_i32 m0, s50, 0x2000
	s_nop 0
	global_load_lds_dwordx4 v130, s[48:49]
	v_lshl_add_u64 v[160:161], v[246:247], 0, s[34:35]
	s_mov_b32 m0, s77
	s_nop 0
	global_load_lds_dwordx4 v[160:161], off
	v_lshl_add_u64 v[160:161], v[248:249], 0, s[34:35]
	s_mov_b32 m0, s78
	s_nop 0
	global_load_lds_dwordx4 v[160:161], off
	s_waitcnt vmcnt(8)
	s_waitcnt lgkmcnt(0)
	s_barrier
	v_mfma_f32_16x16x32_bf16 v[62:65], v[170:173], v[212:215], v[62:65]
	v_mfma_f32_16x16x32_bf16 v[58:61], v[178:181], v[212:215], v[58:61]
	v_mfma_f32_16x16x32_bf16 v[46:49], v[170:173], v[220:223], v[46:49]
	v_mfma_f32_16x16x32_bf16 v[42:45], v[178:181], v[220:223], v[42:45]
	v_mfma_f32_16x16x32_bf16 v[28:31], v[170:173], v[228:231], v[28:31]
	v_mfma_f32_16x16x32_bf16 v[24:27], v[178:181], v[228:231], v[24:27]
	v_mfma_f32_16x16x32_bf16 v[12:15], v[170:173], v[236:239], v[12:15]
	v_mfma_f32_16x16x32_bf16 v[8:11], v[178:181], v[236:239], v[8:11]
	v_mfma_f32_16x16x32_bf16 v[62:65], v[174:177], v[216:219], v[62:65]
	v_mfma_f32_16x16x32_bf16 v[58:61], v[182:185], v[216:219], v[58:61]
	v_mfma_f32_16x16x32_bf16 v[46:49], v[174:177], v[224:227], v[46:49]
	v_mfma_f32_16x16x32_bf16 v[42:45], v[182:185], v[224:227], v[42:45]
	v_mfma_f32_16x16x32_bf16 v[28:31], v[174:177], v[232:235], v[28:31]
	v_mfma_f32_16x16x32_bf16 v[24:27], v[182:185], v[232:235], v[24:27]
	v_mfma_f32_16x16x32_bf16 v[12:15], v[174:177], v[240:243], v[12:15]
	v_mfma_f32_16x16x32_bf16 v[8:11], v[182:185], v[240:243], v[8:11]
	v_mfma_f32_16x16x32_bf16 v[54:57], v[196:199], v[212:215], v[54:57]
	v_mfma_f32_16x16x32_bf16 v[50:53], v[204:207], v[212:215], v[50:53]
	v_mfma_f32_16x16x32_bf16 v[38:41], v[196:199], v[220:223], v[38:41]
	v_mfma_f32_16x16x32_bf16 v[34:37], v[204:207], v[220:223], v[34:37]
	v_mfma_f32_16x16x32_bf16 v[20:23], v[196:199], v[228:231], v[20:23]
	v_mfma_f32_16x16x32_bf16 v[16:19], v[204:207], v[228:231], v[16:19]
	v_mfma_f32_16x16x32_bf16 v[4:7], v[196:199], v[236:239], v[4:7]
	v_mfma_f32_16x16x32_bf16 v[0:3], v[204:207], v[236:239], v[0:3]
	v_mfma_f32_16x16x32_bf16 v[54:57], v[200:203], v[216:219], v[54:57]
	v_mfma_f32_16x16x32_bf16 v[50:53], v[208:211], v[216:219], v[50:53]
	v_mfma_f32_16x16x32_bf16 v[38:41], v[200:203], v[224:227], v[38:41]
	v_mfma_f32_16x16x32_bf16 v[34:37], v[208:211], v[224:227], v[34:37]
	v_mfma_f32_16x16x32_bf16 v[20:23], v[200:203], v[232:235], v[20:23]
	v_mfma_f32_16x16x32_bf16 v[16:19], v[208:211], v[232:235], v[16:19]
	v_mfma_f32_16x16x32_bf16 v[4:7], v[200:203], v[240:243], v[4:7]
	v_mfma_f32_16x16x32_bf16 v[0:3], v[208:211], v[240:243], v[0:3]
	s_barrier
	s_add_i32 s81, s81, 2
	s_add_u32 s79, s79, 0x100
	s_addc_u32 s80, s80, 0
	s_add_u32 s46, s46, 0x100
	s_addc_u32 s47, s47, 0
	s_cmp_gt_u32 s81, 13
	s_cbranch_scc0 .LBB0_580
	s_and_b64 vcc, exec, s[4:5]
	s_cbranch_vccz .LBB0_583
	s_barrier
